# v21
# baseline (speedup 1.0000x reference)
; #define WAIT_V(n) asm volatile("s_waitcnt vmcnt(" #n ")" ::: "memory")
; #define WAIT_L(n) asm volatile("s_waitcnt lgkmcnt(" #n ")" ::: "memory")
; #define BAR __builtin_amdgcn_s_barrier()
; #define SCHED __builtin_amdgcn_sched_barrier(0)
; __device__ __forceinline__ void mainloop_8phase(const u16* __restrict__ A, const u16* __restrict__ Bt, int K,
;                                                 f32x4 (&acc)[2][2][4][2], int wid_s, int ld) {
;     ...
;   int tid = get_tid(wid_s), wid = tid >> 6, lane = tid & 63, wr = wid >> 2, wc = wid & 3, fr = lane & 15, fq = lane >> 4;
;   unsigned goff0, goff1;
;   {
;     int r0, c0, r1, c1;
;     stage_rc(tid * 16, r0, c0);
;     stage_rc(tid * 16 + 8192, r1, c1);
;     goff0 = (unsigned)(r0 * ld + c0) * 2u;
;     goff1 = (unsigned)(r1 * ld + c1) * 2u;
;   }
;   __amdgpu_buffer_rsrc_t rs_A, rs_Bt;
;   {
;     unsigned long ua = (unsigned long)A, ub = (unsigned long)Bt;
;     unsigned alo = __builtin_amdgcn_readfirstlane((unsigned)ua), ahi = __builtin_amdgcn_readfirstlane((unsigned)(ua >> 32));
;     unsigned blo = __builtin_amdgcn_readfirstlane((unsigned)ub), bhi = __builtin_amdgcn_readfirstlane((unsigned)(ub >> 32));
;     rs_A = __builtin_amdgcn_make_buffer_rsrc((void*)(((unsigned long)ahi << 32) | alo), (short)0, 0x7ffffff0, 0x00020000);
;     rs_Bt = __builtin_amdgcn_make_buffer_rsrc((void*)(((unsigned long)bhi << 32) | blo), (short)0, 0x7ffffff0, 0x00020000);
;   }
;   bf16x8 At[4][2], B0[2][2], B1[2][2];
;   const int brow = 0, bcol = 0;
;   int nt = K / G_BK;
;   if (wr == 1) BAR;
;   WAIT_V(0); BAR;
;   STAGE(SB(1, 0), Bt, bcol, 1); STAGE(SA(1, 0), A, brow, 1); STAGE(SB(1, 1), Bt, bcol + G_HALF, 1);
;   WAIT_V(6); BAR;
;   for (int t = 0; t < nt - 2; t += 2) {
;     LDB(B0, 0, 0); SCHED; LDA(At, 0, 0); STAGE(SA(1, 1), A, brow + G_HALF, t + 1);
;     WAIT_L(8); BAR; WAIT_L(0); MMA(0, 0, At, B0); BAR; SCHED;
.LBB0_57:
	s_or_b64 exec, exec, s[0:1]
	v_bfe_i32 v8, v0, 27, 1
	v_lshlrev_b32_e32 v6, 4, v0
	v_lshrrev_b32_e32 v8, 22, v8
	v_add_u32_e32 v8, v6, v8
	v_and_b32_e32 v8, 0xfffffc00, v8
	v_sub_u32_e32 v8, v6, v8
	v_lshrrev_b32_e32 v9, 4, v8
	v_ashrrev_i32_e32 v7, 31, v0
	v_bitop3_b32 v8, v9, v8, 32 bitop3:0x6c
	v_lshrrev_b32_e32 v7, 26, v7
	v_ashrrev_i32_e32 v10, 31, v8
	v_add_u32_e32 v7, v0, v7
	v_lshrrev_b32_e32 v10, 26, v10
	v_ashrrev_i32_e32 v7, 6, v7
	v_add_u32_e32 v10, v8, v10
	v_lshlrev_b32_e32 v9, 3, v7
	v_lshrrev_b32_e32 v11, 6, v10
	v_and_b32_e32 v10, 0xc0, v10
	v_and_b32_e32 v9, 0xffff0, v9
	v_sub_u32_e32 v8, v8, v10
	v_add_u32_e32 v10, 0x2000, v6
	v_add_u32_e32 v9, v11, v9
	v_ashrrev_i32_e32 v11, 31, v10
	v_lshrrev_b32_e32 v11, 22, v11
	v_add_u32_e32 v11, v10, v11
	v_ashrrev_i32_e32 v11, 10, v11
	v_mul_i32_i24_e32 v12, 0x400, v11
	v_sub_u32_e32 v10, v10, v12
	v_lshrrev_b32_e32 v12, 4, v10
	v_bitop3_b32 v10, v12, v10, 32 bitop3:0x6c
	v_ashrrev_i32_e32 v13, 31, v10
	v_lshrrev_b32_e32 v13, 26, v13
	v_add_u32_e32 v13, v10, v13
	v_lshlrev_b32_e32 v7, 5, v7
	v_lshlrev_b32_e32 v12, 3, v11
	v_lshrrev_b32_e32 v14, 6, v13
	v_and_b32_e32 v13, 0xc0, v13
	v_readlane_b32 s6, v254, 43
	v_and_b32_e32 v7, 32, v7
	v_ashrrev_i16_sdwa v8, v244, sext(v8) dst_sel:DWORD dst_unused:UNUSED_PAD src0_sel:DWORD src1_sel:BYTE_0
	v_and_b32_e32 v12, 0xffff0, v12
	v_lshlrev_b32_e32 v11, 5, v11
	v_sub_u32_e32 v10, v10, v13
	s_waitcnt vmcnt(15)
	v_add_u32_e32 v138, s6, v6
	v_bfe_i32 v8, v8, 0, 16
	v_add_u32_e32 v12, v14, v12
	v_and_b32_e32 v11, 32, v11
	v_ashrrev_i16_sdwa v10, v244, sext(v10) dst_sel:DWORD dst_unused:UNUSED_PAD src0_sel:DWORD src1_sel:BYTE_0
	v_lshl_or_b32 v7, v9, 11, v7
	s_and_b32 s5, s13, 0xffff
	v_readfirstlane_b32 s0, v138
	v_add_u32_e32 v139, 0x2000, v138
	v_add_u32_e32 v140, 16, v6
	v_bfe_i32 v10, v10, 0, 16
	v_add_lshl_u32 v137, v7, v8, 1
	v_lshl_or_b32 v7, v12, 11, v11
	s_mov_b32 s20, s12
	s_mov_b32 s21, s5
	s_mov_b32 s22, s90
	s_mov_b32 s23, s91
	s_mov_b32 m0, s0
	s_movk_i32 s1, 0x80
	v_readfirstlane_b32 s0, v139
	v_add_u32_e32 v141, 0x8000, v140
	v_add_lshl_u32 v136, v7, v10, 1
	s_and_b32 s89, s11, 0xffff
	s_waitcnt vmcnt(0)
	s_barrier
	buffer_load_dwordx4 v137, s[20:23], s1 offen lds
	s_mov_b32 m0, s0
	v_readfirstlane_b32 s0, v141
	v_add_u32_e32 v142, 0xa000, v140
	v_readlane_b32 s7, v254, 44
	s_mov_b32 s16, s10
	s_mov_b32 s17, s89
	s_mov_b32 s18, s90
	s_mov_b32 s19, s91
	buffer_load_dwordx4 v136, s[20:23], s1 offen lds
	s_mov_b32 m0, s0
	v_readfirstlane_b32 s0, v142
	v_add_u32_e32 v143, s7, v6
	buffer_load_dwordx4 v137, s[16:19], s1 offen lds
	s_mov_b32 m0, s0
	v_readfirstlane_b32 s0, v143
	v_add_u32_e32 v146, 0x2000, v143
	buffer_load_dwordx4 v136, s[16:19], s1 offen lds
	s_mov_b32 m0, s0
	s_mov_b32 s1, 0x80080
	v_readfirstlane_b32 s0, v146
	buffer_load_dwordx4 v137, s[20:23], s1 offen lds
	s_mov_b32 m0, s0
	v_and_b32_e32 v4, 15, v2
	buffer_load_dwordx4 v136, s[20:23], s1 offen lds
	v_lshlrev_b32_e32 v7, 2, v2
	v_and_b32_e32 v5, 48, v2
	v_lshlrev_b32_e32 v4, 6, v4
	v_and_b32_e32 v7, 32, v7
	v_bitop3_b32 v4, v4, v7, v5 bitop3:0x36
	v_readlane_b32 s0, v254, 41
	v_lshlrev_b32_e32 v2, 6, v2
	s_waitcnt vmcnt(6)
	v_readlane_b32 s1, v254, 42
	v_add_u32_e32 v8, s0, v4
	v_add_u32_e32 v148, s0, v6
	s_movk_i32 s0, 0x3c0
	v_lshlrev_b32_e32 v11, 6, v0
	v_lshlrev_b32_e32 v3, 13, v3
	v_and_or_b32 v2, v2, s0, v5
	v_add_u32_e32 v9, s1, v4
	v_add_u32_e32 v151, s1, v6
	v_add_u32_e32 v6, s6, v4
	v_add_u32_e32 v10, s7, v4
	v_and_b32_e32 v11, 0x3000, v11
	v_add_u32_e32 v4, 16, v4
	v_xad_u32 v5, v2, v7, 16
	v_or_b32_e32 v7, 0x800, v3
	v_or_b32_e32 v12, 0x1000, v3
	v_or_b32_e32 v13, 0x1800, v3
	v_mov_b32_e32 v2, 0
	s_mov_b32 s88, s10
	s_mov_b32 s4, s12
	v_add_u32_e32 v145, 0xc000, v140
	v_add_u32_e32 v144, 0xe000, v140
	v_add_u32_e32 v149, 0x2000, v148
	v_add_u32_e32 v150, 0x2000, v140
	v_add_u32_e32 v152, 0x2000, v151
	v_add_u32_e32 v153, 0x4000, v140
	v_add_u32_e32 v154, 0x6000, v140
	s_mov_b32 s0, -2
	s_mov_b32 s1, 0x80180
	v_add_u32_e32 v155, v8, v11
	s_waitcnt lgkmcnt(0)
	v_add_u32_e32 v133, v4, v3
	v_add_u32_e32 v132, v5, v7
	v_add_u32_e32 v131, v5, v12
	v_add_u32_e32 v130, v5, v13
	v_add_u32_e32 v147, v9, v11
	v_add_u32_e32 v135, v6, v11
	v_add_u32_e32 v134, v10, v11
	s_waitcnt vmcnt(17)
	s_waitcnt vmcnt(16)
	s_waitcnt vmcnt(15)
	s_waitcnt vmcnt(14)
	s_barrier
	s_mov_b32 s7, s91
	s_add_i32 s6, s1, 0xffffff00
	s_add_i32 m0, s100, 0xc000
	ds_read_b128 v[156:159], v155
	ds_read_b128 v[160:163], v155 offset:1024
	ds_read_b128 v[164:167], v155 offset:2048
	ds_read_b128 v[168:171], v155 offset:3072
	ds_read_b128 v[172:175], v133
	ds_read_b128 v[176:179], v133 offset:1024
	ds_read_b128 v[180:183], v132
	ds_read_b128 v[184:187], v132 offset:1024
	ds_read_b128 v[188:191], v131
	ds_read_b128 v[192:195], v131 offset:1024
	ds_read_b128 v[196:199], v130
	buffer_load_dwordx4 v137, s[88:91], s6 offen lds
	s_add_i32 m0, s100, 0xe000
	ds_read_b128 v[200:203], v130 offset:1024
	buffer_load_dwordx4 v136, s[88:91], s6 offen lds
	s_waitcnt lgkmcnt(8)
	s_barrier
	s_waitcnt lgkmcnt(1)
	v_mfma_f32_16x16x32_bf16 v[126:129], v[172:175], v[156:159], 0
	s_add_i32 s15, s1, 0xfff7ff80
	s_add_i32 m0, s100, 0x10000
	v_mfma_f32_16x16x32_bf16 v[122:125], v[172:175], v[164:167], 0
	v_mfma_f32_16x16x32_bf16 v[118:121], v[180:183], v[156:159], 0
	v_mfma_f32_16x16x32_bf16 v[114:117], v[180:183], v[164:167], 0
	v_mfma_f32_16x16x32_bf16 v[110:113], v[188:191], v[156:159], 0
	v_mfma_f32_16x16x32_bf16 v[106:109], v[188:191], v[164:167], 0
	v_mfma_f32_16x16x32_bf16 v[102:105], v[196:199], v[156:159], 0
	v_mfma_f32_16x16x32_bf16 v[98:101], v[196:199], v[164:167], 0
	v_mfma_f32_16x16x32_bf16 v[126:129], v[176:179], v[160:163], v[126:129]
	v_mfma_f32_16x16x32_bf16 v[122:125], v[176:179], v[168:171], v[122:125]
	v_mfma_f32_16x16x32_bf16 v[118:121], v[184:187], v[160:163], v[118:121]
	v_mfma_f32_16x16x32_bf16 v[114:117], v[184:187], v[168:171], v[114:117]
	v_mfma_f32_16x16x32_bf16 v[110:113], v[192:195], v[160:163], v[110:113]
	v_mfma_f32_16x16x32_bf16 v[106:109], v[192:195], v[168:171], v[106:109]
	s_waitcnt lgkmcnt(0)
	v_mfma_f32_16x16x32_bf16 v[102:105], v[200:203], v[160:163], v[102:105]
	v_mfma_f32_16x16x32_bf16 v[98:101], v[200:203], v[168:171], v[98:101]
	s_barrier
; #define WAIT_V(n) asm volatile("s_waitcnt vmcnt(" #n ")" ::: "memory")
; #define WAIT_L(n) asm volatile("s_waitcnt lgkmcnt(" #n ")" ::: "memory")
; #define BAR __builtin_amdgcn_s_barrier()
; #define SCHED __builtin_amdgcn_sched_barrier(0)
; __device__ __forceinline__ void mainloop_8phase(const u16* __restrict__ A, const u16* __restrict__ Bt, int K,
;                                                 f32x4 (&acc)[2][2][4][2], int wid_s, int ld) {
;     ...
;     WAIT_L(8); BAR; WAIT_L(0); MMA(0, 0, At, B0); BAR; SCHED;
;     LDB(B1, 0, 1); STAGE(SB(0, 0), Bt, bcol, t + 2);
;     BAR; WAIT_L(0); MMA(0, 1, At, B1); BAR;
;     LDA(At, 0, 1); STAGE(SA(0, 0), A, brow, t + 2);
;     BAR; WAIT_L(0); MMA(1, 0, At, B0); BAR; SCHED;
;     STAGE(SB(0, 1), Bt, bcol + G_HALF, t + 2);
;     WAIT_V(6); BAR; MMA(1, 1, At, B1); BAR;
;     LDB(B0, 1, 0); SCHED; LDA(At, 1, 0); STAGE(SA(0, 1), A, brow + G_HALF, t + 2);
;     WAIT_L(8); BAR; WAIT_L(0); MMA(0, 0, At, B0); BAR; SCHED;
	s_mov_b32 s6, s90
	ds_read_b128 v[204:207], v147
	ds_read_b128 v[208:211], v147 offset:1024
	ds_read_b128 v[212:215], v147 offset:2048
	buffer_load_dwordx4 v137, s[4:7], s15 offen lds
	s_add_i32 m0, s100, 0x12000
	ds_read_b128 v[216:219], v147 offset:3072
	buffer_load_dwordx4 v136, s[4:7], s15 offen lds
	s_barrier
	s_waitcnt lgkmcnt(1)
	v_mfma_f32_16x16x32_bf16 v[94:97], v[172:175], v[204:207], 0
	v_mfma_f32_16x16x32_bf16 v[90:93], v[172:175], v[212:215], 0
	v_mfma_f32_16x16x32_bf16 v[86:89], v[180:183], v[204:207], 0
	v_mfma_f32_16x16x32_bf16 v[82:85], v[180:183], v[212:215], 0
	v_mfma_f32_16x16x32_bf16 v[78:81], v[188:191], v[204:207], 0
	v_mfma_f32_16x16x32_bf16 v[74:77], v[188:191], v[212:215], 0
	v_mfma_f32_16x16x32_bf16 v[70:73], v[196:199], v[204:207], 0
	v_mfma_f32_16x16x32_bf16 v[66:69], v[196:199], v[212:215], 0
	v_mfma_f32_16x16x32_bf16 v[94:97], v[176:179], v[208:211], v[94:97]
	s_waitcnt lgkmcnt(0)
	v_mfma_f32_16x16x32_bf16 v[90:93], v[176:179], v[216:219], v[90:93]
	v_mfma_f32_16x16x32_bf16 v[86:89], v[184:187], v[208:211], v[86:89]
	v_mfma_f32_16x16x32_bf16 v[82:85], v[184:187], v[216:219], v[82:85]
	v_mfma_f32_16x16x32_bf16 v[78:81], v[192:195], v[208:211], v[78:81]
	v_mfma_f32_16x16x32_bf16 v[74:77], v[192:195], v[216:219], v[74:77]
	v_mfma_f32_16x16x32_bf16 v[70:73], v[200:203], v[208:211], v[70:73]
	v_mfma_f32_16x16x32_bf16 v[66:69], v[200:203], v[216:219], v[66:69]
	s_mov_b32 m0, s100
	s_barrier
	ds_read_b128 v[172:175], v133 offset:16384
	ds_read_b128 v[176:179], v133 offset:17408
	ds_read_b128 v[180:183], v132 offset:16384
	ds_read_b128 v[184:187], v132 offset:17408
	ds_read_b128 v[188:191], v131 offset:16384
	ds_read_b128 v[192:195], v131 offset:17408
	ds_read_b128 v[196:199], v130 offset:16384
	buffer_load_dwordx4 v137, s[88:91], s15 offen lds
	s_add_i32 m0, s100, 0x2000
	ds_read_b128 v[200:203], v130 offset:17408
	buffer_load_dwordx4 v136, s[88:91], s15 offen lds
	s_barrier
	s_waitcnt lgkmcnt(1)
	v_mfma_f32_16x16x32_bf16 v[62:65], v[172:175], v[156:159], 0
	s_add_i32 s15, s1, 0xffffff80
	s_add_i32 m0, s100, 0x14000
	v_mfma_f32_16x16x32_bf16 v[58:61], v[172:175], v[164:167], 0
	v_mfma_f32_16x16x32_bf16 v[54:57], v[180:183], v[156:159], 0
	v_mfma_f32_16x16x32_bf16 v[50:53], v[180:183], v[164:167], 0
	v_mfma_f32_16x16x32_bf16 v[46:49], v[188:191], v[156:159], 0
	v_mfma_f32_16x16x32_bf16 v[42:45], v[188:191], v[164:167], 0
	v_mfma_f32_16x16x32_bf16 v[38:41], v[196:199], v[156:159], 0
	v_mfma_f32_16x16x32_bf16 v[34:37], v[196:199], v[164:167], 0
	v_mfma_f32_16x16x32_bf16 v[62:65], v[176:179], v[160:163], v[62:65]
	v_mfma_f32_16x16x32_bf16 v[58:61], v[176:179], v[168:171], v[58:61]
	v_mfma_f32_16x16x32_bf16 v[54:57], v[184:187], v[160:163], v[54:57]
	v_mfma_f32_16x16x32_bf16 v[50:53], v[184:187], v[168:171], v[50:53]
	v_mfma_f32_16x16x32_bf16 v[46:49], v[192:195], v[160:163], v[46:49]
	v_mfma_f32_16x16x32_bf16 v[42:45], v[192:195], v[168:171], v[42:45]
	s_waitcnt lgkmcnt(0)
	v_mfma_f32_16x16x32_bf16 v[38:41], v[200:203], v[160:163], v[38:41]
	v_mfma_f32_16x16x32_bf16 v[34:37], v[200:203], v[168:171], v[34:37]
	s_barrier
	buffer_load_dwordx4 v137, s[4:7], s15 offen lds
	s_add_i32 m0, s100, 0x16000
	s_nop 0
	buffer_load_dwordx4 v136, s[4:7], s15 offen lds
	s_waitcnt vmcnt(6)
	s_barrier
	v_mfma_f32_16x16x32_bf16 v[30:33], v[172:175], v[204:207], 0
	s_add_i32 m0, s100, 0x4000
	v_mfma_f32_16x16x32_bf16 v[26:29], v[172:175], v[212:215], 0
	v_mfma_f32_16x16x32_bf16 v[22:25], v[180:183], v[204:207], 0
	v_mfma_f32_16x16x32_bf16 v[18:21], v[180:183], v[212:215], 0
	v_mfma_f32_16x16x32_bf16 v[14:17], v[188:191], v[204:207], 0
	v_mfma_f32_16x16x32_bf16 v[10:13], v[188:191], v[212:215], 0
	v_mfma_f32_16x16x32_bf16 v[6:9], v[196:199], v[204:207], 0
	v_mfma_f32_16x16x32_bf16 v[2:5], v[196:199], v[212:215], 0
	v_mfma_f32_16x16x32_bf16 v[30:33], v[176:179], v[208:211], v[30:33]
	v_mfma_f32_16x16x32_bf16 v[26:29], v[176:179], v[216:219], v[26:29]
	v_mfma_f32_16x16x32_bf16 v[22:25], v[184:187], v[208:211], v[22:25]
	v_mfma_f32_16x16x32_bf16 v[18:21], v[184:187], v[216:219], v[18:21]
	v_mfma_f32_16x16x32_bf16 v[14:17], v[192:195], v[208:211], v[14:17]
	v_mfma_f32_16x16x32_bf16 v[10:13], v[192:195], v[216:219], v[10:13]
	v_mfma_f32_16x16x32_bf16 v[6:9], v[200:203], v[208:211], v[6:9]
	v_mfma_f32_16x16x32_bf16 v[2:5], v[200:203], v[216:219], v[2:5]
	s_barrier
	ds_read_b128 v[156:159], v135
	ds_read_b128 v[160:163], v135 offset:1024
	ds_read_b128 v[164:167], v135 offset:2048
	ds_read_b128 v[168:171], v135 offset:3072
	ds_read_b128 v[172:175], v133 offset:32768
	ds_read_b128 v[176:179], v133 offset:33792
	ds_read_b128 v[180:183], v132 offset:32768
	ds_read_b128 v[184:187], v132 offset:33792
	ds_read_b128 v[188:191], v131 offset:32768
	ds_read_b128 v[192:195], v131 offset:33792
	ds_read_b128 v[196:199], v130 offset:32768
	buffer_load_dwordx4 v137, s[88:91], s15 offen lds
	s_add_i32 m0, s100, 0x6000
	ds_read_b128 v[200:203], v130 offset:33792
	buffer_load_dwordx4 v136, s[88:91], s15 offen lds
	s_waitcnt lgkmcnt(8)
	s_barrier
; #define WAIT_V(n) asm volatile("s_waitcnt vmcnt(" #n ")" ::: "memory")
; #define WAIT_L(n) asm volatile("s_waitcnt lgkmcnt(" #n ")" ::: "memory")
; #define BAR __builtin_amdgcn_s_barrier()
; #define SCHED __builtin_amdgcn_sched_barrier(0)
; __device__ __forceinline__ void mainloop_8phase(const u16* __restrict__ A, const u16* __restrict__ Bt, int K,
;                                                 f32x4 (&acc)[2][2][4][2], int wid_s, int ld) {
;     ...
;     WAIT_L(8); BAR; WAIT_L(0); MMA(0, 0, At, B0); BAR; SCHED;
;     LDB(B1, 1, 1); STAGE(SB(1, 0), Bt, bcol, t + 3);
;     BAR; WAIT_L(0); MMA(0, 1, At, B1); BAR;
;     LDA(At, 1, 1); STAGE(SA(1, 0), A, brow, t + 3);
;     BAR; WAIT_L(0); MMA(1, 0, At, B0); BAR; SCHED;
;     STAGE(SB(1, 1), Bt, bcol + G_HALF, t + 3);
;     WAIT_V(6); BAR; MMA(1, 1, At, B1); BAR;
	s_waitcnt lgkmcnt(1)
	v_mfma_f32_16x16x32_bf16 v[126:129], v[172:175], v[156:159], v[126:129]
	s_add_i32 s15, s1, 0xfff80000
	s_add_i32 m0, s100, 0x18000
	v_mfma_f32_16x16x32_bf16 v[122:125], v[172:175], v[164:167], v[122:125]
	v_mfma_f32_16x16x32_bf16 v[118:121], v[180:183], v[156:159], v[118:121]
	v_mfma_f32_16x16x32_bf16 v[114:117], v[180:183], v[164:167], v[114:117]
	v_mfma_f32_16x16x32_bf16 v[110:113], v[188:191], v[156:159], v[110:113]
	v_mfma_f32_16x16x32_bf16 v[106:109], v[188:191], v[164:167], v[106:109]
	v_mfma_f32_16x16x32_bf16 v[102:105], v[196:199], v[156:159], v[102:105]
	v_mfma_f32_16x16x32_bf16 v[98:101], v[196:199], v[164:167], v[98:101]
	v_mfma_f32_16x16x32_bf16 v[126:129], v[176:179], v[160:163], v[126:129]
	v_mfma_f32_16x16x32_bf16 v[122:125], v[176:179], v[168:171], v[122:125]
	v_mfma_f32_16x16x32_bf16 v[118:121], v[184:187], v[160:163], v[118:121]
	v_mfma_f32_16x16x32_bf16 v[114:117], v[184:187], v[168:171], v[114:117]
	v_mfma_f32_16x16x32_bf16 v[110:113], v[192:195], v[160:163], v[110:113]
	v_mfma_f32_16x16x32_bf16 v[106:109], v[192:195], v[168:171], v[106:109]
	s_waitcnt lgkmcnt(0)
	v_mfma_f32_16x16x32_bf16 v[102:105], v[200:203], v[160:163], v[102:105]
	v_mfma_f32_16x16x32_bf16 v[98:101], v[200:203], v[168:171], v[98:101]
	s_barrier
	ds_read_b128 v[204:207], v134
	ds_read_b128 v[208:211], v134 offset:1024
	ds_read_b128 v[212:215], v134 offset:2048
	buffer_load_dwordx4 v137, s[4:7], s15 offen lds
	s_add_i32 m0, s100, 0x1a000
	ds_read_b128 v[216:219], v134 offset:3072
	buffer_load_dwordx4 v136, s[4:7], s15 offen lds
	s_barrier
	s_waitcnt lgkmcnt(1)
	v_mfma_f32_16x16x32_bf16 v[94:97], v[172:175], v[204:207], v[94:97]
	v_mfma_f32_16x16x32_bf16 v[90:93], v[172:175], v[212:215], v[90:93]
	v_mfma_f32_16x16x32_bf16 v[86:89], v[180:183], v[204:207], v[86:89]
	v_mfma_f32_16x16x32_bf16 v[82:85], v[180:183], v[212:215], v[82:85]
	v_mfma_f32_16x16x32_bf16 v[78:81], v[188:191], v[204:207], v[78:81]
	v_mfma_f32_16x16x32_bf16 v[74:77], v[188:191], v[212:215], v[74:77]
	v_mfma_f32_16x16x32_bf16 v[70:73], v[196:199], v[204:207], v[70:73]
	v_mfma_f32_16x16x32_bf16 v[66:69], v[196:199], v[212:215], v[66:69]
	v_mfma_f32_16x16x32_bf16 v[94:97], v[176:179], v[208:211], v[94:97]
	s_waitcnt lgkmcnt(0)
	v_mfma_f32_16x16x32_bf16 v[90:93], v[176:179], v[216:219], v[90:93]
	v_mfma_f32_16x16x32_bf16 v[86:89], v[184:187], v[208:211], v[86:89]
	v_mfma_f32_16x16x32_bf16 v[82:85], v[184:187], v[216:219], v[82:85]
	v_mfma_f32_16x16x32_bf16 v[78:81], v[192:195], v[208:211], v[78:81]
	v_mfma_f32_16x16x32_bf16 v[74:77], v[192:195], v[216:219], v[74:77]
	v_mfma_f32_16x16x32_bf16 v[70:73], v[200:203], v[208:211], v[70:73]
	v_mfma_f32_16x16x32_bf16 v[66:69], v[200:203], v[216:219], v[66:69]
	s_add_i32 m0, s100, 0x8000
	s_barrier
	ds_read_b128 v[172:175], v133 offset:49152
	ds_read_b128 v[176:179], v133 offset:50176
	ds_read_b128 v[180:183], v132 offset:49152
	ds_read_b128 v[184:187], v132 offset:50176
	ds_read_b128 v[188:191], v131 offset:49152
	ds_read_b128 v[192:195], v131 offset:50176
	ds_read_b128 v[196:199], v130 offset:49152
	buffer_load_dwordx4 v137, s[88:91], s15 offen lds
	s_add_i32 m0, s100, 0xa000
	ds_read_b128 v[200:203], v130 offset:50176
	buffer_load_dwordx4 v136, s[88:91], s15 offen lds
	s_barrier
	s_waitcnt lgkmcnt(1)
	v_mfma_f32_16x16x32_bf16 v[62:65], v[172:175], v[156:159], v[62:65]
	s_add_i32 m0, s100, 0x1c000
	v_mfma_f32_16x16x32_bf16 v[58:61], v[172:175], v[164:167], v[58:61]
	v_mfma_f32_16x16x32_bf16 v[54:57], v[180:183], v[156:159], v[54:57]
	v_mfma_f32_16x16x32_bf16 v[50:53], v[180:183], v[164:167], v[50:53]
	v_mfma_f32_16x16x32_bf16 v[46:49], v[188:191], v[156:159], v[46:49]
	v_mfma_f32_16x16x32_bf16 v[42:45], v[188:191], v[164:167], v[42:45]
	v_mfma_f32_16x16x32_bf16 v[38:41], v[196:199], v[156:159], v[38:41]
	v_mfma_f32_16x16x32_bf16 v[34:37], v[196:199], v[164:167], v[34:37]
	v_mfma_f32_16x16x32_bf16 v[62:65], v[176:179], v[160:163], v[62:65]
	v_mfma_f32_16x16x32_bf16 v[58:61], v[176:179], v[168:171], v[58:61]
	v_mfma_f32_16x16x32_bf16 v[54:57], v[184:187], v[160:163], v[54:57]
	v_mfma_f32_16x16x32_bf16 v[50:53], v[184:187], v[168:171], v[50:53]
	v_mfma_f32_16x16x32_bf16 v[46:49], v[192:195], v[160:163], v[46:49]
	v_mfma_f32_16x16x32_bf16 v[42:45], v[192:195], v[168:171], v[42:45]
	s_waitcnt lgkmcnt(0)
	v_mfma_f32_16x16x32_bf16 v[38:41], v[200:203], v[160:163], v[38:41]
	v_mfma_f32_16x16x32_bf16 v[34:37], v[200:203], v[168:171], v[34:37]
	s_barrier
	buffer_load_dwordx4 v137, s[4:7], s1 offen lds
	s_add_i32 m0, s100, 0x1e000
	s_nop 0
	buffer_load_dwordx4 v136, s[4:7], s1 offen lds
	s_waitcnt vmcnt(6)
	s_barrier
	v_mfma_f32_16x16x32_bf16 v[30:33], v[172:175], v[204:207], v[30:33]
	v_mfma_f32_16x16x32_bf16 v[26:29], v[172:175], v[212:215], v[26:29]
	v_mfma_f32_16x16x32_bf16 v[22:25], v[180:183], v[204:207], v[22:25]
	v_mfma_f32_16x16x32_bf16 v[18:21], v[180:183], v[212:215], v[18:21]
	v_mfma_f32_16x16x32_bf16 v[14:17], v[188:191], v[204:207], v[14:17]
	v_mfma_f32_16x16x32_bf16 v[10:13], v[188:191], v[212:215], v[10:13]
	v_mfma_f32_16x16x32_bf16 v[6:9], v[196:199], v[204:207], v[6:9]
	v_mfma_f32_16x16x32_bf16 v[2:5], v[196:199], v[212:215], v[2:5]
	v_mfma_f32_16x16x32_bf16 v[30:33], v[176:179], v[208:211], v[30:33]
	v_mfma_f32_16x16x32_bf16 v[26:29], v[176:179], v[216:219], v[26:29]
	v_mfma_f32_16x16x32_bf16 v[22:25], v[184:187], v[208:211], v[22:25]
	v_mfma_f32_16x16x32_bf16 v[18:21], v[184:187], v[216:219], v[18:21]
	v_mfma_f32_16x16x32_bf16 v[14:17], v[192:195], v[208:211], v[14:17]
	v_mfma_f32_16x16x32_bf16 v[10:13], v[192:195], v[216:219], v[10:13]
	v_mfma_f32_16x16x32_bf16 v[6:9], v[200:203], v[208:211], v[6:9]
	v_mfma_f32_16x16x32_bf16 v[2:5], v[200:203], v[216:219], v[2:5]
	s_add_i32 s0, s0, 2
	s_addk_i32 s1, 0x100
	s_add_i32 s6, s1, 0xffffff00
	s_add_i32 m0, s100, 0xc000
	s_cmp_lt_u32 s0, 28
	s_barrier
; #define WAIT_V(n) asm volatile("s_waitcnt vmcnt(" #n ")" ::: "memory")
; #define WAIT_L(n) asm volatile("s_waitcnt lgkmcnt(" #n ")" ::: "memory")
; #define BAR __builtin_amdgcn_s_barrier()
; #define SCHED __builtin_amdgcn_sched_barrier(0)
; __device__ __forceinline__ void mainloop_8phase(const u16* __restrict__ A, const u16* __restrict__ Bt, int K,
;                                                 f32x4 (&acc)[2][2][4][2], int wid_s, int ld) {
;     ...
;   for (int t = 0; t < nt - 2; t += 2) {
;     LDB(B0, 0, 0); SCHED; LDA(At, 0, 0); STAGE(SA(1, 1), A, brow + G_HALF, t + 1);
;     WAIT_L(8); BAR; WAIT_L(0); MMA(0, 0, At, B0); BAR; SCHED;
;     LDB(B1, 0, 1); STAGE(SB(0, 0), Bt, bcol, t + 2);
;     BAR; WAIT_L(0); MMA(0, 1, At, B1); BAR;
;     LDA(At, 0, 1); STAGE(SA(0, 0), A, brow, t + 2);
;     BAR; WAIT_L(0); MMA(1, 0, At, B0); BAR; SCHED;
;     STAGE(SB(0, 1), Bt, bcol + G_HALF, t + 2);
;     WAIT_V(6); BAR; MMA(1, 1, At, B1); BAR;
.LBB0_58:
	ds_read_b128 v[156:159], v155
	ds_read_b128 v[160:163], v155 offset:1024
	ds_read_b128 v[164:167], v155 offset:2048
	ds_read_b128 v[168:171], v155 offset:3072
	ds_read_b128 v[172:175], v133
	ds_read_b128 v[176:179], v133 offset:1024
	ds_read_b128 v[180:183], v132
	ds_read_b128 v[184:187], v132 offset:1024
	ds_read_b128 v[188:191], v131
	ds_read_b128 v[192:195], v131 offset:1024
	ds_read_b128 v[196:199], v130
	buffer_load_dwordx4 v137, s[88:91], s6 offen lds
	s_add_i32 m0, s100, 0xe000
	ds_read_b128 v[200:203], v130 offset:1024
	buffer_load_dwordx4 v136, s[88:91], s6 offen lds
	s_waitcnt lgkmcnt(8)
	s_barrier
	s_waitcnt lgkmcnt(1)
	v_mfma_f32_16x16x32_bf16 v[126:129], v[172:175], v[156:159], v[126:129]
	s_add_i32 s15, s1, 0xfff7ff80
	s_add_i32 m0, s100, 0x10000
	v_mfma_f32_16x16x32_bf16 v[122:125], v[172:175], v[164:167], v[122:125]
	v_mfma_f32_16x16x32_bf16 v[118:121], v[180:183], v[156:159], v[118:121]
	v_mfma_f32_16x16x32_bf16 v[114:117], v[180:183], v[164:167], v[114:117]
	v_mfma_f32_16x16x32_bf16 v[110:113], v[188:191], v[156:159], v[110:113]
	v_mfma_f32_16x16x32_bf16 v[106:109], v[188:191], v[164:167], v[106:109]
	v_mfma_f32_16x16x32_bf16 v[102:105], v[196:199], v[156:159], v[102:105]
	v_mfma_f32_16x16x32_bf16 v[98:101], v[196:199], v[164:167], v[98:101]
	v_mfma_f32_16x16x32_bf16 v[126:129], v[176:179], v[160:163], v[126:129]
	v_mfma_f32_16x16x32_bf16 v[122:125], v[176:179], v[168:171], v[122:125]
	v_mfma_f32_16x16x32_bf16 v[118:121], v[184:187], v[160:163], v[118:121]
	v_mfma_f32_16x16x32_bf16 v[114:117], v[184:187], v[168:171], v[114:117]
	v_mfma_f32_16x16x32_bf16 v[110:113], v[192:195], v[160:163], v[110:113]
	v_mfma_f32_16x16x32_bf16 v[106:109], v[192:195], v[168:171], v[106:109]
	s_waitcnt lgkmcnt(0)
	v_mfma_f32_16x16x32_bf16 v[102:105], v[200:203], v[160:163], v[102:105]
	v_mfma_f32_16x16x32_bf16 v[98:101], v[200:203], v[168:171], v[98:101]
	s_barrier
	s_mov_b32 s6, s90
	ds_read_b128 v[204:207], v147
	ds_read_b128 v[208:211], v147 offset:1024
	ds_read_b128 v[212:215], v147 offset:2048
	buffer_load_dwordx4 v137, s[4:7], s15 offen lds
	s_add_i32 m0, s100, 0x12000
	ds_read_b128 v[216:219], v147 offset:3072
	buffer_load_dwordx4 v136, s[4:7], s15 offen lds
	s_barrier
	s_waitcnt lgkmcnt(1)
	v_mfma_f32_16x16x32_bf16 v[94:97], v[172:175], v[204:207], v[94:97]
	v_mfma_f32_16x16x32_bf16 v[90:93], v[172:175], v[212:215], v[90:93]
	v_mfma_f32_16x16x32_bf16 v[86:89], v[180:183], v[204:207], v[86:89]
	v_mfma_f32_16x16x32_bf16 v[82:85], v[180:183], v[212:215], v[82:85]
	v_mfma_f32_16x16x32_bf16 v[78:81], v[188:191], v[204:207], v[78:81]
	v_mfma_f32_16x16x32_bf16 v[74:77], v[188:191], v[212:215], v[74:77]
	v_mfma_f32_16x16x32_bf16 v[70:73], v[196:199], v[204:207], v[70:73]
	v_mfma_f32_16x16x32_bf16 v[66:69], v[196:199], v[212:215], v[66:69]
	v_mfma_f32_16x16x32_bf16 v[94:97], v[176:179], v[208:211], v[94:97]
	s_waitcnt lgkmcnt(0)
	v_mfma_f32_16x16x32_bf16 v[90:93], v[176:179], v[216:219], v[90:93]
	v_mfma_f32_16x16x32_bf16 v[86:89], v[184:187], v[208:211], v[86:89]
	v_mfma_f32_16x16x32_bf16 v[82:85], v[184:187], v[216:219], v[82:85]
	v_mfma_f32_16x16x32_bf16 v[78:81], v[192:195], v[208:211], v[78:81]
	v_mfma_f32_16x16x32_bf16 v[74:77], v[192:195], v[216:219], v[74:77]
	v_mfma_f32_16x16x32_bf16 v[70:73], v[200:203], v[208:211], v[70:73]
	v_mfma_f32_16x16x32_bf16 v[66:69], v[200:203], v[216:219], v[66:69]
	s_mov_b32 m0, s100
	s_barrier
	ds_read_b128 v[172:175], v133 offset:16384
	ds_read_b128 v[176:179], v133 offset:17408
	ds_read_b128 v[180:183], v132 offset:16384
	ds_read_b128 v[184:187], v132 offset:17408
	ds_read_b128 v[188:191], v131 offset:16384
	ds_read_b128 v[192:195], v131 offset:17408
	ds_read_b128 v[196:199], v130 offset:16384
	buffer_load_dwordx4 v137, s[88:91], s15 offen lds
	s_add_i32 m0, s100, 0x2000
	ds_read_b128 v[200:203], v130 offset:17408
	buffer_load_dwordx4 v136, s[88:91], s15 offen lds
	s_barrier
	s_waitcnt lgkmcnt(1)
	v_mfma_f32_16x16x32_bf16 v[62:65], v[172:175], v[156:159], v[62:65]
	s_add_i32 s15, s1, 0xffffff80
	s_add_i32 m0, s100, 0x14000
	v_mfma_f32_16x16x32_bf16 v[58:61], v[172:175], v[164:167], v[58:61]
	v_mfma_f32_16x16x32_bf16 v[54:57], v[180:183], v[156:159], v[54:57]
	v_mfma_f32_16x16x32_bf16 v[50:53], v[180:183], v[164:167], v[50:53]
	v_mfma_f32_16x16x32_bf16 v[46:49], v[188:191], v[156:159], v[46:49]
	v_mfma_f32_16x16x32_bf16 v[42:45], v[188:191], v[164:167], v[42:45]
	v_mfma_f32_16x16x32_bf16 v[38:41], v[196:199], v[156:159], v[38:41]
	v_mfma_f32_16x16x32_bf16 v[34:37], v[196:199], v[164:167], v[34:37]
	v_mfma_f32_16x16x32_bf16 v[62:65], v[176:179], v[160:163], v[62:65]
	v_mfma_f32_16x16x32_bf16 v[58:61], v[176:179], v[168:171], v[58:61]
	v_mfma_f32_16x16x32_bf16 v[54:57], v[184:187], v[160:163], v[54:57]
	v_mfma_f32_16x16x32_bf16 v[50:53], v[184:187], v[168:171], v[50:53]
	v_mfma_f32_16x16x32_bf16 v[46:49], v[192:195], v[160:163], v[46:49]
	v_mfma_f32_16x16x32_bf16 v[42:45], v[192:195], v[168:171], v[42:45]
	s_waitcnt lgkmcnt(0)
	v_mfma_f32_16x16x32_bf16 v[38:41], v[200:203], v[160:163], v[38:41]
	v_mfma_f32_16x16x32_bf16 v[34:37], v[200:203], v[168:171], v[34:37]
	s_barrier
	buffer_load_dwordx4 v137, s[4:7], s15 offen lds
	s_add_i32 m0, s100, 0x16000
	s_nop 0
	buffer_load_dwordx4 v136, s[4:7], s15 offen lds
	s_waitcnt vmcnt(6)
	s_barrier
; #define WAIT_V(n) asm volatile("s_waitcnt vmcnt(" #n ")" ::: "memory")
; #define WAIT_L(n) asm volatile("s_waitcnt lgkmcnt(" #n ")" ::: "memory")
; #define BAR __builtin_amdgcn_s_barrier()
; #define SCHED __builtin_amdgcn_sched_barrier(0)
; __device__ __forceinline__ void mainloop_8phase(const u16* __restrict__ A, const u16* __restrict__ Bt, int K,
;                                                 f32x4 (&acc)[2][2][4][2], int wid_s, int ld) {
;     ...
;     WAIT_V(6); BAR; MMA(1, 1, At, B1); BAR;
;     LDB(B0, 1, 0); SCHED; LDA(At, 1, 0); STAGE(SA(0, 1), A, brow + G_HALF, t + 2);
;     WAIT_L(8); BAR; WAIT_L(0); MMA(0, 0, At, B0); BAR; SCHED;
;     LDB(B1, 1, 1); STAGE(SB(1, 0), Bt, bcol, t + 3);
;     BAR; WAIT_L(0); MMA(0, 1, At, B1); BAR;
;     LDA(At, 1, 1); STAGE(SA(1, 0), A, brow, t + 3);
;     BAR; WAIT_L(0); MMA(1, 0, At, B0); BAR; SCHED;
	v_mfma_f32_16x16x32_bf16 v[30:33], v[172:175], v[204:207], v[30:33]
	s_add_i32 m0, s100, 0x4000
	v_mfma_f32_16x16x32_bf16 v[26:29], v[172:175], v[212:215], v[26:29]
	v_mfma_f32_16x16x32_bf16 v[22:25], v[180:183], v[204:207], v[22:25]
	v_mfma_f32_16x16x32_bf16 v[18:21], v[180:183], v[212:215], v[18:21]
	v_mfma_f32_16x16x32_bf16 v[14:17], v[188:191], v[204:207], v[14:17]
	v_mfma_f32_16x16x32_bf16 v[10:13], v[188:191], v[212:215], v[10:13]
	v_mfma_f32_16x16x32_bf16 v[6:9], v[196:199], v[204:207], v[6:9]
	v_mfma_f32_16x16x32_bf16 v[2:5], v[196:199], v[212:215], v[2:5]
	v_mfma_f32_16x16x32_bf16 v[30:33], v[176:179], v[208:211], v[30:33]
	v_mfma_f32_16x16x32_bf16 v[26:29], v[176:179], v[216:219], v[26:29]
	v_mfma_f32_16x16x32_bf16 v[22:25], v[184:187], v[208:211], v[22:25]
	v_mfma_f32_16x16x32_bf16 v[18:21], v[184:187], v[216:219], v[18:21]
	v_mfma_f32_16x16x32_bf16 v[14:17], v[192:195], v[208:211], v[14:17]
	v_mfma_f32_16x16x32_bf16 v[10:13], v[192:195], v[216:219], v[10:13]
	v_mfma_f32_16x16x32_bf16 v[6:9], v[200:203], v[208:211], v[6:9]
	v_mfma_f32_16x16x32_bf16 v[2:5], v[200:203], v[216:219], v[2:5]
	s_barrier
	ds_read_b128 v[156:159], v135
	ds_read_b128 v[160:163], v135 offset:1024
	ds_read_b128 v[164:167], v135 offset:2048
	ds_read_b128 v[168:171], v135 offset:3072
	ds_read_b128 v[172:175], v133 offset:32768
	ds_read_b128 v[176:179], v133 offset:33792
	ds_read_b128 v[180:183], v132 offset:32768
	ds_read_b128 v[184:187], v132 offset:33792
	ds_read_b128 v[188:191], v131 offset:32768
	ds_read_b128 v[192:195], v131 offset:33792
	ds_read_b128 v[196:199], v130 offset:32768
	buffer_load_dwordx4 v137, s[88:91], s15 offen lds
	s_add_i32 m0, s100, 0x6000
	ds_read_b128 v[200:203], v130 offset:33792
	buffer_load_dwordx4 v136, s[88:91], s15 offen lds
	s_waitcnt lgkmcnt(8)
	s_barrier
	s_waitcnt lgkmcnt(1)
	v_mfma_f32_16x16x32_bf16 v[126:129], v[172:175], v[156:159], v[126:129]
	s_add_i32 s15, s1, 0xfff80000
	s_add_i32 m0, s100, 0x18000
	v_mfma_f32_16x16x32_bf16 v[122:125], v[172:175], v[164:167], v[122:125]
	v_mfma_f32_16x16x32_bf16 v[118:121], v[180:183], v[156:159], v[118:121]
	v_mfma_f32_16x16x32_bf16 v[114:117], v[180:183], v[164:167], v[114:117]
	v_mfma_f32_16x16x32_bf16 v[110:113], v[188:191], v[156:159], v[110:113]
	v_mfma_f32_16x16x32_bf16 v[106:109], v[188:191], v[164:167], v[106:109]
	v_mfma_f32_16x16x32_bf16 v[102:105], v[196:199], v[156:159], v[102:105]
	v_mfma_f32_16x16x32_bf16 v[98:101], v[196:199], v[164:167], v[98:101]
	v_mfma_f32_16x16x32_bf16 v[126:129], v[176:179], v[160:163], v[126:129]
	v_mfma_f32_16x16x32_bf16 v[122:125], v[176:179], v[168:171], v[122:125]
	v_mfma_f32_16x16x32_bf16 v[118:121], v[184:187], v[160:163], v[118:121]
	v_mfma_f32_16x16x32_bf16 v[114:117], v[184:187], v[168:171], v[114:117]
	v_mfma_f32_16x16x32_bf16 v[110:113], v[192:195], v[160:163], v[110:113]
	v_mfma_f32_16x16x32_bf16 v[106:109], v[192:195], v[168:171], v[106:109]
	s_waitcnt lgkmcnt(0)
	v_mfma_f32_16x16x32_bf16 v[102:105], v[200:203], v[160:163], v[102:105]
	v_mfma_f32_16x16x32_bf16 v[98:101], v[200:203], v[168:171], v[98:101]
	s_barrier
	ds_read_b128 v[204:207], v134
	ds_read_b128 v[208:211], v134 offset:1024
	ds_read_b128 v[212:215], v134 offset:2048
	buffer_load_dwordx4 v137, s[4:7], s15 offen lds
	s_add_i32 m0, s100, 0x1a000
	ds_read_b128 v[216:219], v134 offset:3072
	buffer_load_dwordx4 v136, s[4:7], s15 offen lds
	s_barrier
	s_waitcnt lgkmcnt(1)
	v_mfma_f32_16x16x32_bf16 v[94:97], v[172:175], v[204:207], v[94:97]
	v_mfma_f32_16x16x32_bf16 v[90:93], v[172:175], v[212:215], v[90:93]
	v_mfma_f32_16x16x32_bf16 v[86:89], v[180:183], v[204:207], v[86:89]
	v_mfma_f32_16x16x32_bf16 v[82:85], v[180:183], v[212:215], v[82:85]
	v_mfma_f32_16x16x32_bf16 v[78:81], v[188:191], v[204:207], v[78:81]
	v_mfma_f32_16x16x32_bf16 v[74:77], v[188:191], v[212:215], v[74:77]
	v_mfma_f32_16x16x32_bf16 v[70:73], v[196:199], v[204:207], v[70:73]
	v_mfma_f32_16x16x32_bf16 v[66:69], v[196:199], v[212:215], v[66:69]
	v_mfma_f32_16x16x32_bf16 v[94:97], v[176:179], v[208:211], v[94:97]
	s_waitcnt lgkmcnt(0)
	v_mfma_f32_16x16x32_bf16 v[90:93], v[176:179], v[216:219], v[90:93]
	v_mfma_f32_16x16x32_bf16 v[86:89], v[184:187], v[208:211], v[86:89]
	v_mfma_f32_16x16x32_bf16 v[82:85], v[184:187], v[216:219], v[82:85]
	v_mfma_f32_16x16x32_bf16 v[78:81], v[192:195], v[208:211], v[78:81]
	v_mfma_f32_16x16x32_bf16 v[74:77], v[192:195], v[216:219], v[74:77]
	v_mfma_f32_16x16x32_bf16 v[70:73], v[200:203], v[208:211], v[70:73]
	v_mfma_f32_16x16x32_bf16 v[66:69], v[200:203], v[216:219], v[66:69]
	s_add_i32 m0, s100, 0x8000
	s_barrier
	ds_read_b128 v[172:175], v133 offset:49152
	ds_read_b128 v[176:179], v133 offset:50176
	ds_read_b128 v[180:183], v132 offset:49152
	ds_read_b128 v[184:187], v132 offset:50176
	ds_read_b128 v[188:191], v131 offset:49152
	ds_read_b128 v[192:195], v131 offset:50176
	ds_read_b128 v[196:199], v130 offset:49152
	buffer_load_dwordx4 v137, s[88:91], s15 offen lds
	s_add_i32 m0, s100, 0xa000
	ds_read_b128 v[200:203], v130 offset:50176
	buffer_load_dwordx4 v136, s[88:91], s15 offen lds
	s_barrier
; #define WAIT_V(n) asm volatile("s_waitcnt vmcnt(" #n ")" ::: "memory")
; #define WAIT_L(n) asm volatile("s_waitcnt lgkmcnt(" #n ")" ::: "memory")
; #define BAR __builtin_amdgcn_s_barrier()
; #define SCHED __builtin_amdgcn_sched_barrier(0)
; __device__ __forceinline__ void mainloop_8phase(const u16* __restrict__ A, const u16* __restrict__ Bt, int K,
;                                                 f32x4 (&acc)[2][2][4][2], int wid_s, int ld) {
;     ...
;     BAR; WAIT_L(0); MMA(1, 0, At, B0); BAR; SCHED;
;     STAGE(SB(1, 1), Bt, bcol + G_HALF, t + 3);
;     WAIT_V(6); BAR; MMA(1, 1, At, B1); BAR;
;   }
;   { LDB(B0, 0, 0); LDA(At, 0, 0); STAGE(SA(1, 1), A, brow + G_HALF, nt - 1);
;     BAR; WAIT_L(0); MMA(0, 0, At, B0); BAR;
	s_waitcnt lgkmcnt(1)
	v_mfma_f32_16x16x32_bf16 v[62:65], v[172:175], v[156:159], v[62:65]
	s_add_i32 m0, s100, 0x1c000
	v_mfma_f32_16x16x32_bf16 v[58:61], v[172:175], v[164:167], v[58:61]
	v_mfma_f32_16x16x32_bf16 v[54:57], v[180:183], v[156:159], v[54:57]
	v_mfma_f32_16x16x32_bf16 v[50:53], v[180:183], v[164:167], v[50:53]
	v_mfma_f32_16x16x32_bf16 v[46:49], v[188:191], v[156:159], v[46:49]
	v_mfma_f32_16x16x32_bf16 v[42:45], v[188:191], v[164:167], v[42:45]
	v_mfma_f32_16x16x32_bf16 v[38:41], v[196:199], v[156:159], v[38:41]
	v_mfma_f32_16x16x32_bf16 v[34:37], v[196:199], v[164:167], v[34:37]
	v_mfma_f32_16x16x32_bf16 v[62:65], v[176:179], v[160:163], v[62:65]
	v_mfma_f32_16x16x32_bf16 v[58:61], v[176:179], v[168:171], v[58:61]
	v_mfma_f32_16x16x32_bf16 v[54:57], v[184:187], v[160:163], v[54:57]
	v_mfma_f32_16x16x32_bf16 v[50:53], v[184:187], v[168:171], v[50:53]
	v_mfma_f32_16x16x32_bf16 v[46:49], v[192:195], v[160:163], v[46:49]
	v_mfma_f32_16x16x32_bf16 v[42:45], v[192:195], v[168:171], v[42:45]
	s_waitcnt lgkmcnt(0)
	v_mfma_f32_16x16x32_bf16 v[38:41], v[200:203], v[160:163], v[38:41]
	v_mfma_f32_16x16x32_bf16 v[34:37], v[200:203], v[168:171], v[34:37]
	s_barrier
	buffer_load_dwordx4 v137, s[4:7], s1 offen lds
	s_add_i32 m0, s100, 0x1e000
	s_nop 0
	buffer_load_dwordx4 v136, s[4:7], s1 offen lds
	s_waitcnt vmcnt(6)
	s_barrier
	v_mfma_f32_16x16x32_bf16 v[30:33], v[172:175], v[204:207], v[30:33]
	v_mfma_f32_16x16x32_bf16 v[26:29], v[172:175], v[212:215], v[26:29]
	v_mfma_f32_16x16x32_bf16 v[22:25], v[180:183], v[204:207], v[22:25]
	v_mfma_f32_16x16x32_bf16 v[18:21], v[180:183], v[212:215], v[18:21]
	v_mfma_f32_16x16x32_bf16 v[14:17], v[188:191], v[204:207], v[14:17]
	v_mfma_f32_16x16x32_bf16 v[10:13], v[188:191], v[212:215], v[10:13]
	v_mfma_f32_16x16x32_bf16 v[6:9], v[196:199], v[204:207], v[6:9]
	v_mfma_f32_16x16x32_bf16 v[2:5], v[196:199], v[212:215], v[2:5]
	v_mfma_f32_16x16x32_bf16 v[30:33], v[176:179], v[208:211], v[30:33]
	v_mfma_f32_16x16x32_bf16 v[26:29], v[176:179], v[216:219], v[26:29]
	v_mfma_f32_16x16x32_bf16 v[22:25], v[184:187], v[208:211], v[22:25]
	v_mfma_f32_16x16x32_bf16 v[18:21], v[184:187], v[216:219], v[18:21]
	v_mfma_f32_16x16x32_bf16 v[14:17], v[192:195], v[208:211], v[14:17]
	v_mfma_f32_16x16x32_bf16 v[10:13], v[192:195], v[216:219], v[10:13]
	v_mfma_f32_16x16x32_bf16 v[6:9], v[200:203], v[208:211], v[6:9]
	v_mfma_f32_16x16x32_bf16 v[2:5], v[200:203], v[216:219], v[2:5]
	s_add_i32 s0, s0, 2
	s_addk_i32 s1, 0x100
	s_add_i32 s6, s1, 0xffffff00
	s_add_i32 m0, s100, 0xc000
	s_cmp_lt_u32 s0, 28
	s_barrier
	s_cbranch_scc1 .LBB0_58
	v_readfirstlane_b32 s0, v145
	s_mov_b32 m0, s0
	s_mov_b32 s1, 0x80f80
	v_readfirstlane_b32 s0, v144
	ds_read_b128 v[138:141], v155
	ds_read_b128 v[148:151], v155 offset:1024
	ds_read_b128 v[156:159], v155 offset:2048
	ds_read_b128 v[152:155], v155 offset:3072
	ds_read_b128 v[160:163], v133
	ds_read_b128 v[164:167], v133 offset:1024
	ds_read_b128 v[168:171], v132
	ds_read_b128 v[172:175], v132 offset:1024
	ds_read_b128 v[176:179], v131
	ds_read_b128 v[180:183], v131 offset:1024
	ds_read_b128 v[184:187], v130
	ds_read_b128 v[188:191], v130 offset:1024
	buffer_load_dwordx4 v137, s[88:91], s1 offen lds
	s_mov_b32 m0, s0
	s_nop 0
	buffer_load_dwordx4 v136, s[88:91], s1 offen lds
	s_barrier
	s_waitcnt lgkmcnt(0)
	v_mfma_f32_16x16x32_bf16 v[126:129], v[160:163], v[138:141], v[126:129]
	v_mfma_f32_16x16x32_bf16 v[122:125], v[160:163], v[156:159], v[122:125]
	v_mfma_f32_16x16x32_bf16 v[118:121], v[168:171], v[138:141], v[118:121]
	v_mfma_f32_16x16x32_bf16 v[114:117], v[168:171], v[156:159], v[114:117]
	v_mfma_f32_16x16x32_bf16 v[102:105], v[184:187], v[138:141], v[102:105]
	v_mfma_f32_16x16x32_bf16 v[98:101], v[184:187], v[156:159], v[98:101]
	v_mfma_f32_16x16x32_bf16 v[126:129], v[164:167], v[148:151], v[126:129]
	v_mfma_f32_16x16x32_bf16 v[122:125], v[164:167], v[152:155], v[122:125]
	v_mfma_f32_16x16x32_bf16 v[118:121], v[172:175], v[148:151], v[118:121]
	v_mfma_f32_16x16x32_bf16 v[114:117], v[172:175], v[152:155], v[114:117]
	v_mfma_f32_16x16x32_bf16 v[110:113], v[176:179], v[138:141], v[110:113]
	v_mfma_f32_16x16x32_bf16 v[106:109], v[176:179], v[156:159], v[106:109]
	v_mfma_f32_16x16x32_bf16 v[102:105], v[188:191], v[148:151], v[102:105]
	v_mfma_f32_16x16x32_bf16 v[98:101], v[188:191], v[152:155], v[98:101]
	v_mfma_f32_16x16x32_bf16 v[142:145], v[180:183], v[148:151], v[110:113]
	v_mfma_f32_16x16x32_bf16 v[192:195], v[180:183], v[152:155], v[106:109]
	s_barrier
	s_nop 0
	ds_read_b128 v[106:109], v147
	ds_read_b128 v[110:113], v147 offset:1024
	ds_read_b128 v[196:199], v147 offset:2048
	ds_read_b128 v[200:203], v147 offset:3072
	s_barrier
	s_waitcnt lgkmcnt(0)
	v_mfma_f32_16x16x32_bf16 v[86:89], v[168:171], v[106:109], v[86:89]
	v_mfma_f32_16x16x32_bf16 v[82:85], v[168:171], v[196:199], v[82:85]
	v_mfma_f32_16x16x32_bf16 v[70:73], v[184:187], v[106:109], v[70:73]
	v_mfma_f32_16x16x32_bf16 v[66:69], v[184:187], v[196:199], v[66:69]
	v_mfma_f32_16x16x32_bf16 v[94:97], v[160:163], v[106:109], v[94:97]
	v_mfma_f32_16x16x32_bf16 v[90:93], v[160:163], v[196:199], v[90:93]
	v_mfma_f32_16x16x32_bf16 v[86:89], v[172:175], v[110:113], v[86:89]
	v_mfma_f32_16x16x32_bf16 v[82:85], v[172:175], v[200:203], v[82:85]
	v_mfma_f32_16x16x32_bf16 v[78:81], v[176:179], v[106:109], v[78:81]
	v_mfma_f32_16x16x32_bf16 v[74:77], v[176:179], v[196:199], v[74:77]
	v_mfma_f32_16x16x32_bf16 v[70:73], v[188:191], v[110:113], v[70:73]
	v_mfma_f32_16x16x32_bf16 v[66:69], v[188:191], v[200:203], v[66:69]
	v_mfma_f32_16x16x32_bf16 v[204:207], v[164:167], v[110:113], v[94:97]
	v_mfma_f32_16x16x32_bf16 v[160:163], v[164:167], v[200:203], v[90:93]
	v_mfma_f32_16x16x32_bf16 v[164:167], v[180:183], v[110:113], v[78:81]
	v_mfma_f32_16x16x32_bf16 v[168:171], v[180:183], v[200:203], v[74:77]
	s_barrier
; #define WAIT_V(n) asm volatile("s_waitcnt vmcnt(" #n ")" ::: "memory")
; #define WAIT_L(n) asm volatile("s_waitcnt lgkmcnt(" #n ")" ::: "memory")
; #define BAR __builtin_amdgcn_s_barrier()
; __device__ __forceinline__ void mainloop_8phase(const u16* __restrict__ A, const u16* __restrict__ Bt, int K,
;                                                 f32x4 (&acc)[2][2][4][2], int wid_s, int ld) {
;     ...
;     LDB(B1, 0, 1); BAR; WAIT_L(0); MMA(0, 1, At, B1); BAR;
;     LDA(At, 0, 1); WAIT_V(4); BAR; WAIT_L(0); MMA(1, 0, At, B0); MMA(1, 1, At, B1); BAR; }
;   { LDB(B0, 1, 0); LDA(At, 1, 0); WAIT_V(2); BAR; WAIT_L(0); MMA(0, 0, At, B0); BAR;
	s_nop 0
	ds_read_b128 v[74:77], v133 offset:16384
	ds_read_b128 v[78:81], v133 offset:17408
	ds_read_b128 v[90:93], v132 offset:16384
	ds_read_b128 v[94:97], v132 offset:17408
	ds_read_b128 v[172:175], v131 offset:16384
	ds_read_b128 v[176:179], v131 offset:17408
	ds_read_b128 v[180:183], v130 offset:16384
	ds_read_b128 v[184:187], v130 offset:17408
	s_waitcnt vmcnt(4)
	s_barrier
	s_waitcnt lgkmcnt(0)
	v_mfma_f32_16x16x32_bf16 v[62:65], v[74:77], v[138:141], v[62:65]
	v_mfma_f32_16x16x32_bf16 v[58:61], v[74:77], v[156:159], v[58:61]
	v_mfma_f32_16x16x32_bf16 v[54:57], v[90:93], v[138:141], v[54:57]
	v_mfma_f32_16x16x32_bf16 v[50:53], v[90:93], v[156:159], v[50:53]
	v_mfma_f32_16x16x32_bf16 v[38:41], v[180:183], v[138:141], v[38:41]
	v_mfma_f32_16x16x32_bf16 v[34:37], v[180:183], v[156:159], v[34:37]
	v_mfma_f32_16x16x32_bf16 v[62:65], v[78:81], v[148:151], v[62:65]
	v_mfma_f32_16x16x32_bf16 v[58:61], v[78:81], v[152:155], v[58:61]
	v_mfma_f32_16x16x32_bf16 v[54:57], v[94:97], v[148:151], v[54:57]
	v_mfma_f32_16x16x32_bf16 v[50:53], v[94:97], v[152:155], v[50:53]
	v_mfma_f32_16x16x32_bf16 v[46:49], v[172:175], v[138:141], v[46:49]
	v_mfma_f32_16x16x32_bf16 v[42:45], v[172:175], v[156:159], v[42:45]
	v_mfma_f32_16x16x32_bf16 v[38:41], v[184:187], v[148:151], v[38:41]
	v_mfma_f32_16x16x32_bf16 v[34:37], v[184:187], v[152:155], v[34:37]
	v_mfma_f32_16x16x32_bf16 v[188:191], v[176:179], v[148:151], v[46:49]
	v_mfma_f32_16x16x32_bf16 v[208:211], v[176:179], v[152:155], v[42:45]
	v_mfma_f32_16x16x32_bf16 v[22:25], v[90:93], v[106:109], v[22:25]
	v_mfma_f32_16x16x32_bf16 v[18:21], v[90:93], v[196:199], v[18:21]
	v_mfma_f32_16x16x32_bf16 v[6:9], v[180:183], v[106:109], v[6:9]
	v_mfma_f32_16x16x32_bf16 v[2:5], v[180:183], v[196:199], v[2:5]
	v_mfma_f32_16x16x32_bf16 v[30:33], v[74:77], v[106:109], v[30:33]
	v_mfma_f32_16x16x32_bf16 v[26:29], v[74:77], v[196:199], v[26:29]
	v_mfma_f32_16x16x32_bf16 v[22:25], v[94:97], v[110:113], v[22:25]
	v_mfma_f32_16x16x32_bf16 v[18:21], v[94:97], v[200:203], v[18:21]
	v_mfma_f32_16x16x32_bf16 v[14:17], v[172:175], v[106:109], v[14:17]
	v_mfma_f32_16x16x32_bf16 v[10:13], v[172:175], v[196:199], v[10:13]
	v_mfma_f32_16x16x32_bf16 v[6:9], v[184:187], v[110:113], v[6:9]
	v_mfma_f32_16x16x32_bf16 v[2:5], v[184:187], v[200:203], v[2:5]
	v_mfma_f32_16x16x32_bf16 v[136:139], v[78:81], v[110:113], v[30:33]
	v_mfma_f32_16x16x32_bf16 v[146:149], v[78:81], v[200:203], v[26:29]
	v_mfma_f32_16x16x32_bf16 v[150:153], v[176:179], v[110:113], v[14:17]
	v_mfma_f32_16x16x32_bf16 v[154:157], v[176:179], v[200:203], v[10:13]
	s_barrier
	s_nop 0
	ds_read_b128 v[10:13], v135
	ds_read_b128 v[14:17], v135 offset:1024
	ds_read_b128 v[172:175], v135 offset:2048
	ds_read_b128 v[176:179], v135 offset:3072
	ds_read_b128 v[26:29], v133 offset:32768
	ds_read_b128 v[30:33], v133 offset:33792
	ds_read_b128 v[42:45], v132 offset:32768
	ds_read_b128 v[46:49], v132 offset:33792
	ds_read_b128 v[180:183], v131 offset:32768
	ds_read_b128 v[184:187], v131 offset:33792
	ds_read_b128 v[196:199], v130 offset:32768
	ds_read_b128 v[200:203], v130 offset:33792
	s_waitcnt vmcnt(2)
	s_barrier
	s_waitcnt lgkmcnt(0)
	v_mfma_f32_16x16x32_bf16 v[74:77], v[26:29], v[10:13], v[126:129]
	v_mfma_f32_16x16x32_bf16 v[126:129], v[30:33], v[14:17], v[74:77]
	v_mfma_f32_16x16x32_bf16 v[74:77], v[26:29], v[172:175], v[122:125]
	v_mfma_f32_16x16x32_bf16 v[122:125], v[30:33], v[176:179], v[74:77]
	v_mfma_f32_16x16x32_bf16 v[74:77], v[42:45], v[10:13], v[118:121]
	v_mfma_f32_16x16x32_bf16 v[110:113], v[46:49], v[14:17], v[74:77]
	v_mfma_f32_16x16x32_bf16 v[74:77], v[42:45], v[172:175], v[114:117]
	v_mfma_f32_16x16x32_bf16 v[106:109], v[46:49], v[176:179], v[74:77]
	v_mfma_f32_16x16x32_bf16 v[74:77], v[180:183], v[10:13], v[142:145]
	v_mfma_f32_16x16x32_bf16 v[94:97], v[184:187], v[14:17], v[74:77]
	v_mfma_f32_16x16x32_bf16 v[74:77], v[180:183], v[172:175], v[192:195]
	v_mfma_f32_16x16x32_bf16 v[90:93], v[184:187], v[176:179], v[74:77]
	v_mfma_f32_16x16x32_bf16 v[74:77], v[196:199], v[10:13], v[102:105]
	v_mfma_f32_16x16x32_bf16 v[78:81], v[200:203], v[14:17], v[74:77]
	v_mfma_f32_16x16x32_bf16 v[74:77], v[196:199], v[172:175], v[98:101]
	v_mfma_f32_16x16x32_bf16 v[74:77], v[200:203], v[176:179], v[74:77]
	s_barrier
; #define WAIT_V(n) asm volatile("s_waitcnt vmcnt(" #n ")" ::: "memory")
; #define WAIT_L(n) asm volatile("s_waitcnt lgkmcnt(" #n ")" ::: "memory")
; #define BAR __builtin_amdgcn_s_barrier()
; __device__ __forceinline__ void mainloop_8phase(const u16* __restrict__ A, const u16* __restrict__ Bt, int K,
;                                                 f32x4 (&acc)[2][2][4][2], int wid_s, int ld) {
;     ...
;   { LDB(B0, 1, 0); LDA(At, 1, 0); WAIT_V(2); BAR; WAIT_L(0); MMA(0, 0, At, B0); BAR;
;     LDB(B1, 1, 1); WAIT_V(0); BAR; WAIT_L(0); MMA(0, 1, At, B1); BAR;
;     LDA(At, 1, 1); BAR; WAIT_L(0); MMA(1, 0, At, B0); MMA(1, 1, At, B1); BAR; }
;   if (wr == 0) BAR;
	ds_read_b128 v[140:143], v134
	ds_read_b128 v[192:195], v134 offset:1024
	ds_read_b128 v[212:215], v134 offset:2048
	ds_read_b128 v[216:219], v134 offset:3072
	s_waitcnt vmcnt(0)
	s_barrier
	s_waitcnt lgkmcnt(0)
	v_mfma_f32_16x16x32_bf16 v[98:101], v[26:29], v[140:143], v[204:207]
	v_mfma_f32_16x16x32_bf16 v[26:29], v[26:29], v[212:215], v[160:163]
	v_mfma_f32_16x16x32_bf16 v[114:117], v[30:33], v[216:219], v[26:29]
	v_mfma_f32_16x16x32_bf16 v[26:29], v[42:45], v[140:143], v[86:89]
	v_mfma_f32_16x16x32_bf16 v[102:105], v[46:49], v[192:195], v[26:29]
	v_mfma_f32_16x16x32_bf16 v[26:29], v[42:45], v[212:215], v[82:85]
	v_mfma_f32_16x16x32_bf16 v[118:121], v[30:33], v[192:195], v[98:101]
	v_mfma_f32_16x16x32_bf16 v[98:101], v[46:49], v[216:219], v[26:29]
	v_mfma_f32_16x16x32_bf16 v[26:29], v[180:183], v[140:143], v[164:167]
	v_mfma_f32_16x16x32_bf16 v[86:89], v[184:187], v[192:195], v[26:29]
	v_mfma_f32_16x16x32_bf16 v[26:29], v[180:183], v[212:215], v[168:171]
	v_mfma_f32_16x16x32_bf16 v[82:85], v[184:187], v[216:219], v[26:29]
	v_mfma_f32_16x16x32_bf16 v[26:29], v[196:199], v[140:143], v[70:73]
	v_mfma_f32_16x16x32_bf16 v[70:73], v[200:203], v[192:195], v[26:29]
	v_mfma_f32_16x16x32_bf16 v[26:29], v[196:199], v[212:215], v[66:69]
	v_mfma_f32_16x16x32_bf16 v[66:69], v[200:203], v[216:219], v[26:29]
	s_barrier
	ds_read_b128 v[158:161], v133 offset:49152
	ds_read_b128 v[162:165], v133 offset:50176
	ds_read_b128 v[166:169], v132 offset:49152
	ds_read_b128 v[132:135], v132 offset:50176
	ds_read_b128 v[180:183], v131 offset:49152
	ds_read_b128 v[184:187], v131 offset:50176
	ds_read_b128 v[196:199], v130 offset:49152
	ds_read_b128 v[200:203], v130 offset:50176
	s_barrier
	s_waitcnt lgkmcnt(0)
	v_mfma_f32_16x16x32_bf16 v[26:29], v[158:161], v[10:13], v[62:65]
	v_mfma_f32_16x16x32_bf16 v[62:65], v[162:165], v[14:17], v[26:29]
	v_mfma_f32_16x16x32_bf16 v[26:29], v[158:161], v[172:175], v[58:61]
	v_mfma_f32_16x16x32_bf16 v[58:61], v[162:165], v[176:179], v[26:29]
	v_mfma_f32_16x16x32_bf16 v[26:29], v[166:169], v[10:13], v[54:57]
	v_mfma_f32_16x16x32_bf16 v[46:49], v[132:135], v[14:17], v[26:29]
	v_mfma_f32_16x16x32_bf16 v[26:29], v[166:169], v[172:175], v[50:53]
	v_mfma_f32_16x16x32_bf16 v[42:45], v[132:135], v[176:179], v[26:29]
	v_mfma_f32_16x16x32_bf16 v[26:29], v[180:183], v[10:13], v[188:191]
	v_mfma_f32_16x16x32_bf16 v[10:13], v[196:199], v[10:13], v[38:41]
	v_mfma_f32_16x16x32_bf16 v[30:33], v[184:187], v[14:17], v[26:29]
	v_mfma_f32_16x16x32_bf16 v[26:29], v[180:183], v[172:175], v[208:211]
	v_mfma_f32_16x16x32_bf16 v[14:17], v[200:203], v[14:17], v[10:13]
	v_mfma_f32_16x16x32_bf16 v[10:13], v[196:199], v[172:175], v[34:37]
	v_mfma_f32_16x16x32_bf16 v[26:29], v[184:187], v[176:179], v[26:29]
	v_mfma_f32_16x16x32_bf16 v[10:13], v[200:203], v[176:179], v[10:13]
	v_mfma_f32_16x16x32_bf16 v[34:37], v[158:161], v[140:143], v[136:139]
	v_mfma_f32_16x16x32_bf16 v[54:57], v[162:165], v[192:195], v[34:37]
	v_mfma_f32_16x16x32_bf16 v[34:37], v[158:161], v[212:215], v[146:149]
	v_mfma_f32_16x16x32_bf16 v[18:21], v[166:169], v[212:215], v[18:21]
	v_mfma_f32_16x16x32_bf16 v[50:53], v[162:165], v[216:219], v[34:37]
	v_mfma_f32_16x16x32_bf16 v[22:25], v[166:169], v[140:143], v[22:25]
	v_mfma_f32_16x16x32_bf16 v[34:37], v[132:135], v[216:219], v[18:21]
	v_mfma_f32_16x16x32_bf16 v[18:21], v[180:183], v[140:143], v[150:153]
	v_mfma_f32_16x16x32_bf16 v[38:41], v[132:135], v[192:195], v[22:25]
	v_mfma_f32_16x16x32_bf16 v[22:25], v[184:187], v[192:195], v[18:21]
	v_mfma_f32_16x16x32_bf16 v[18:21], v[180:183], v[212:215], v[154:157]
	v_mfma_f32_16x16x32_bf16 v[6:9], v[196:199], v[140:143], v[6:9]
	v_mfma_f32_16x16x32_bf16 v[2:5], v[196:199], v[212:215], v[2:5]
	v_mfma_f32_16x16x32_bf16 v[18:21], v[184:187], v[216:219], v[18:21]
	v_mfma_f32_16x16x32_bf16 v[6:9], v[200:203], v[192:195], v[6:9]
	v_mfma_f32_16x16x32_bf16 v[2:5], v[200:203], v[216:219], v[2:5]
	s_movk_i32 s0, 0x100
	v_cmp_gt_u32_e32 vcc, s0, v0
	s_barrier
	s_and_saveexec_b64 s[0:1], vcc
	s_cbranch_execz .LBB0_61
	s_barrier

; #define WAIT_V(n) asm volatile("s_waitcnt vmcnt(" #n ")" ::: "memory")
; #define WAIT_L(n) asm volatile("s_waitcnt lgkmcnt(" #n ")" ::: "memory")
; #define BAR __builtin_amdgcn_s_barrier()
; #define SCHED __builtin_amdgcn_sched_barrier(0)
; __device__ __forceinline__ void mainloop_8phase(const u16* __restrict__ A, const u16* __restrict__ Bt, int K,
;                                                 f32x4 (&acc)[2][2][4][2], int wid_s, int ld) {
;     ...
;   int tid = get_tid(wid_s), wid = tid >> 6, lane = tid & 63, wr = wid >> 2, wc = wid & 3, fr = lane & 15, fq = lane >> 4;
;   unsigned goff0, goff1;
;   {
;     int r0, c0, r1, c1;
;     stage_rc(tid * 16, r0, c0);
;     stage_rc(tid * 16 + 8192, r1, c1);
;     goff0 = (unsigned)(r0 * ld + c0) * 2u;
;     goff1 = (unsigned)(r1 * ld + c1) * 2u;
;   }
;   __amdgpu_buffer_rsrc_t rs_A, rs_Bt;
;   {
;     unsigned long ua = (unsigned long)A, ub = (unsigned long)Bt;
;     unsigned alo = __builtin_amdgcn_readfirstlane((unsigned)ua), ahi = __builtin_amdgcn_readfirstlane((unsigned)(ua >> 32));
;     unsigned blo = __builtin_amdgcn_readfirstlane((unsigned)ub), bhi = __builtin_amdgcn_readfirstlane((unsigned)(ub >> 32));
;     rs_A = __builtin_amdgcn_make_buffer_rsrc((void*)(((unsigned long)ahi << 32) | alo), (short)0, 0x7ffffff0, 0x00020000);
;     rs_Bt = __builtin_amdgcn_make_buffer_rsrc((void*)(((unsigned long)bhi << 32) | blo), (short)0, 0x7ffffff0, 0x00020000);
;   }
;   bf16x8 At[4][2], B0[2][2], B1[2][2];
;   const int brow = 0, bcol = 0;
;   int nt = K / G_BK;
;   if (wr == 1) BAR;
;   WAIT_V(0); BAR;
;   STAGE(SB(1, 0), Bt, bcol, 1); STAGE(SA(1, 0), A, brow, 1); STAGE(SB(1, 1), Bt, bcol + G_HALF, 1);
;   WAIT_V(6); BAR;
;   for (int t = 0; t < nt - 2; t += 2) {
;     LDB(B0, 0, 0); SCHED; LDA(At, 0, 0); STAGE(SA(1, 1), A, brow + G_HALF, t + 1);
;     WAIT_L(8); BAR; WAIT_L(0); MMA(0, 0, At, B0); BAR; SCHED;
.LBB0_161:
	s_or_b64 exec, exec, s[2:3]
	v_bfe_i32 v8, v0, 27, 1
	v_lshlrev_b32_e32 v6, 4, v0
	v_lshrrev_b32_e32 v8, 22, v8
	v_add_u32_e32 v8, v6, v8
	v_and_b32_e32 v8, 0xfffffc00, v8
	v_sub_u32_e32 v8, v6, v8
	v_lshrrev_b32_e32 v9, 4, v8
	v_ashrrev_i32_e32 v7, 31, v0
	v_bitop3_b32 v8, v9, v8, 32 bitop3:0x6c
	v_lshrrev_b32_e32 v7, 26, v7
	v_ashrrev_i32_e32 v10, 31, v8
	v_add_u32_e32 v7, v0, v7
	v_lshrrev_b32_e32 v10, 26, v10
	v_ashrrev_i32_e32 v7, 6, v7
	v_add_u32_e32 v10, v8, v10
	v_lshlrev_b32_e32 v9, 3, v7
	v_lshrrev_b32_e32 v11, 6, v10
	v_and_b32_e32 v10, 0xc0, v10
	v_and_b32_e32 v9, 0xffff0, v9
	v_sub_u32_e32 v8, v8, v10
	v_add_u32_e32 v10, 0x2000, v6
	v_add_u32_e32 v9, v11, v9
	v_ashrrev_i32_e32 v11, 31, v10
	v_lshrrev_b32_e32 v11, 22, v11
	v_add_u32_e32 v11, v10, v11
	v_ashrrev_i32_e32 v11, 10, v11
	v_mul_i32_i24_e32 v12, 0x400, v11
	v_sub_u32_e32 v10, v10, v12
	v_lshrrev_b32_e32 v12, 4, v10
	v_bitop3_b32 v10, v12, v10, 32 bitop3:0x6c
	v_ashrrev_i32_e32 v13, 31, v10
	v_lshrrev_b32_e32 v13, 26, v13
	v_add_u32_e32 v13, v10, v13
	v_lshlrev_b32_e32 v7, 5, v7
	v_lshlrev_b32_e32 v12, 3, v11
	v_lshrrev_b32_e32 v14, 6, v13
	v_and_b32_e32 v13, 0xc0, v13
	v_readlane_b32 s6, v254, 43
	v_and_b32_e32 v7, 32, v7
	v_ashrrev_i16_sdwa v8, v244, sext(v8) dst_sel:DWORD dst_unused:UNUSED_PAD src0_sel:DWORD src1_sel:BYTE_0
	v_and_b32_e32 v12, 0xffff0, v12
	v_lshlrev_b32_e32 v11, 5, v11
	v_sub_u32_e32 v10, v10, v13
	s_waitcnt vmcnt(7)
	v_add_u32_e32 v138, s6, v6
	v_bfe_i32 v8, v8, 0, 16
	v_add_u32_e32 v12, v14, v12
	v_and_b32_e32 v11, 32, v11
	v_ashrrev_i16_sdwa v10, v244, sext(v10) dst_sel:DWORD dst_unused:UNUSED_PAD src0_sel:DWORD src1_sel:BYTE_0
	v_lshl_or_b32 v7, v9, 11, v7
	s_and_b32 s5, s13, 0xffff
	v_readfirstlane_b32 s2, v138
	v_add_u32_e32 v139, 0x2000, v138
	v_add_u32_e32 v140, 16, v6
	v_bfe_i32 v10, v10, 0, 16
	v_add_lshl_u32 v137, v7, v8, 1
	v_lshl_or_b32 v7, v12, 11, v11
	s_mov_b32 s24, s12
	s_mov_b32 s25, s5
	s_mov_b32 s26, s90
	s_mov_b32 s27, s91
	s_mov_b32 m0, s2
	s_movk_i32 s3, 0x80
	v_readfirstlane_b32 s2, v139
	v_add_u32_e32 v141, 0x8000, v140
	v_add_lshl_u32 v136, v7, v10, 1
	s_and_b32 s89, s1, 0xffff
	s_waitcnt vmcnt(0)
	s_barrier
	buffer_load_dwordx4 v137, s[24:27], s3 offen lds
	s_mov_b32 m0, s2
	v_readfirstlane_b32 s2, v141
	v_add_u32_e32 v142, 0xa000, v140
	v_readlane_b32 s7, v254, 44
	s_mov_b32 s16, s0
	s_mov_b32 s17, s89
	s_mov_b32 s18, s90
	s_mov_b32 s19, s91
	buffer_load_dwordx4 v136, s[24:27], s3 offen lds
	s_mov_b32 m0, s2
	v_readfirstlane_b32 s2, v142
	v_add_u32_e32 v143, s7, v6
	buffer_load_dwordx4 v137, s[16:19], s3 offen lds
	s_mov_b32 m0, s2
	v_readfirstlane_b32 s2, v143
	v_add_u32_e32 v144, 0x2000, v143
	buffer_load_dwordx4 v136, s[16:19], s3 offen lds
	s_mov_b32 m0, s2
	s_mov_b32 s3, 0x80080
	v_readfirstlane_b32 s2, v144
	buffer_load_dwordx4 v137, s[24:27], s3 offen lds
	s_mov_b32 m0, s2
	v_and_b32_e32 v4, 15, v2
	buffer_load_dwordx4 v136, s[24:27], s3 offen lds
	v_lshlrev_b32_e32 v7, 2, v2
	v_and_b32_e32 v5, 48, v2
	v_lshlrev_b32_e32 v4, 6, v4
	v_and_b32_e32 v7, 32, v7
	v_bitop3_b32 v4, v4, v7, v5 bitop3:0x36
	v_readlane_b32 s2, v254, 41
	v_lshlrev_b32_e32 v2, 6, v2
	s_waitcnt vmcnt(6)
	v_readlane_b32 s3, v254, 42
	v_add_u32_e32 v8, s2, v4
	v_add_u32_e32 v146, s2, v6
	s_movk_i32 s2, 0x3c0
	v_lshlrev_b32_e32 v11, 6, v0
	v_lshlrev_b32_e32 v3, 13, v3
	v_and_or_b32 v2, v2, s2, v5
	v_add_u32_e32 v9, s3, v4
	v_add_u32_e32 v147, s3, v6
	v_add_u32_e32 v6, s6, v4
	v_add_u32_e32 v10, s7, v4
	v_and_b32_e32 v11, 0x3000, v11
	v_add_u32_e32 v4, 16, v4
	v_xad_u32 v5, v2, v7, 16
	v_or_b32_e32 v7, 0x800, v3
	v_or_b32_e32 v12, 0x1000, v3
	v_or_b32_e32 v13, 0x1800, v3
	v_mov_b32_e32 v2, 0
	s_mov_b32 s88, s0
	s_mov_b32 s4, s12
	s_mov_b32 s2, -2
	s_mov_b32 s3, 0x80180
	v_add_u32_e32 v148, v8, v11
	s_waitcnt lgkmcnt(0)
	v_add_u32_e32 v133, v4, v3
	v_add_u32_e32 v132, v5, v7
	v_add_u32_e32 v131, v5, v12
	v_add_u32_e32 v130, v5, v13
	v_add_u32_e32 v145, v9, v11
	v_add_u32_e32 v135, v6, v11
	v_add_u32_e32 v134, v10, v11
	s_waitcnt vmcnt(9)
	s_waitcnt vmcnt(8)
	s_waitcnt vmcnt(7)
	s_waitcnt vmcnt(6)
	v_add_u32_e32 v150, 0xc000, v140
	v_add_u32_e32 v149, 0xe000, v140
	v_add_u32_e32 v151, 0x2000, v146
	v_add_u32_e32 v152, 0x2000, v140
	v_add_u32_e32 v153, 0x2000, v147
	v_add_u32_e32 v154, 0x4000, v140
	v_add_u32_e32 v155, 0x6000, v140
	s_barrier
	s_mov_b32 s7, s91
	s_add_i32 s6, s3, 0xffffff00
	s_add_i32 m0, s100, 0xc000
	ds_read_b128 v[156:159], v148
	ds_read_b128 v[160:163], v148 offset:1024
	ds_read_b128 v[164:167], v148 offset:2048
	ds_read_b128 v[168:171], v148 offset:3072
	ds_read_b128 v[172:175], v133
	ds_read_b128 v[176:179], v133 offset:1024
	ds_read_b128 v[180:183], v132
	ds_read_b128 v[184:187], v132 offset:1024
	ds_read_b128 v[188:191], v131
	ds_read_b128 v[192:195], v131 offset:1024
	ds_read_b128 v[196:199], v130
	buffer_load_dwordx4 v137, s[88:91], s6 offen lds
	s_add_i32 m0, s100, 0xe000
	ds_read_b128 v[200:203], v130 offset:1024
	buffer_load_dwordx4 v136, s[88:91], s6 offen lds
	s_waitcnt lgkmcnt(8)
	s_barrier
	s_waitcnt lgkmcnt(1)
	v_mfma_f32_16x16x32_bf16 v[126:129], v[172:175], v[156:159], 0
	s_add_i32 s15, s3, 0xfff7ff80
	s_add_i32 m0, s100, 0x10000
	v_mfma_f32_16x16x32_bf16 v[122:125], v[172:175], v[164:167], 0
	v_mfma_f32_16x16x32_bf16 v[118:121], v[180:183], v[156:159], 0
	v_mfma_f32_16x16x32_bf16 v[114:117], v[180:183], v[164:167], 0
	v_mfma_f32_16x16x32_bf16 v[110:113], v[188:191], v[156:159], 0
	v_mfma_f32_16x16x32_bf16 v[106:109], v[188:191], v[164:167], 0
	v_mfma_f32_16x16x32_bf16 v[102:105], v[196:199], v[156:159], 0
	v_mfma_f32_16x16x32_bf16 v[98:101], v[196:199], v[164:167], 0
	v_mfma_f32_16x16x32_bf16 v[126:129], v[176:179], v[160:163], v[126:129]
	v_mfma_f32_16x16x32_bf16 v[122:125], v[176:179], v[168:171], v[122:125]
	v_mfma_f32_16x16x32_bf16 v[118:121], v[184:187], v[160:163], v[118:121]
	v_mfma_f32_16x16x32_bf16 v[114:117], v[184:187], v[168:171], v[114:117]
	v_mfma_f32_16x16x32_bf16 v[110:113], v[192:195], v[160:163], v[110:113]
	v_mfma_f32_16x16x32_bf16 v[106:109], v[192:195], v[168:171], v[106:109]
	s_waitcnt lgkmcnt(0)
	v_mfma_f32_16x16x32_bf16 v[102:105], v[200:203], v[160:163], v[102:105]
	v_mfma_f32_16x16x32_bf16 v[98:101], v[200:203], v[168:171], v[98:101]
	s_barrier
; #define WAIT_V(n) asm volatile("s_waitcnt vmcnt(" #n ")" ::: "memory")
; #define WAIT_L(n) asm volatile("s_waitcnt lgkmcnt(" #n ")" ::: "memory")
; #define BAR __builtin_amdgcn_s_barrier()
; #define SCHED __builtin_amdgcn_sched_barrier(0)
; __device__ __forceinline__ void mainloop_8phase(const u16* __restrict__ A, const u16* __restrict__ Bt, int K,
;                                                 f32x4 (&acc)[2][2][4][2], int wid_s, int ld) {
;     ...
;     LDB(B1, 0, 1); STAGE(SB(0, 0), Bt, bcol, t + 2);
;     BAR; WAIT_L(0); MMA(0, 1, At, B1); BAR;
;     LDA(At, 0, 1); STAGE(SA(0, 0), A, brow, t + 2);
;     BAR; WAIT_L(0); MMA(1, 0, At, B0); BAR; SCHED;
;     STAGE(SB(0, 1), Bt, bcol + G_HALF, t + 2);
;     WAIT_V(6); BAR; MMA(1, 1, At, B1); BAR;
;     LDB(B0, 1, 0); SCHED; LDA(At, 1, 0); STAGE(SA(0, 1), A, brow + G_HALF, t + 2);
	s_mov_b32 s6, s90
	ds_read_b128 v[204:207], v145
	ds_read_b128 v[208:211], v145 offset:1024
	ds_read_b128 v[212:215], v145 offset:2048
	buffer_load_dwordx4 v137, s[4:7], s15 offen lds
	s_add_i32 m0, s100, 0x12000
	ds_read_b128 v[216:219], v145 offset:3072
	buffer_load_dwordx4 v136, s[4:7], s15 offen lds
	s_barrier
	s_waitcnt lgkmcnt(1)
	v_mfma_f32_16x16x32_bf16 v[94:97], v[172:175], v[204:207], 0
	v_mfma_f32_16x16x32_bf16 v[90:93], v[172:175], v[212:215], 0
	v_mfma_f32_16x16x32_bf16 v[86:89], v[180:183], v[204:207], 0
	v_mfma_f32_16x16x32_bf16 v[82:85], v[180:183], v[212:215], 0
	v_mfma_f32_16x16x32_bf16 v[78:81], v[188:191], v[204:207], 0
	v_mfma_f32_16x16x32_bf16 v[74:77], v[188:191], v[212:215], 0
	v_mfma_f32_16x16x32_bf16 v[70:73], v[196:199], v[204:207], 0
	v_mfma_f32_16x16x32_bf16 v[66:69], v[196:199], v[212:215], 0
	v_mfma_f32_16x16x32_bf16 v[94:97], v[176:179], v[208:211], v[94:97]
	s_waitcnt lgkmcnt(0)
	v_mfma_f32_16x16x32_bf16 v[90:93], v[176:179], v[216:219], v[90:93]
	v_mfma_f32_16x16x32_bf16 v[86:89], v[184:187], v[208:211], v[86:89]
	v_mfma_f32_16x16x32_bf16 v[82:85], v[184:187], v[216:219], v[82:85]
	v_mfma_f32_16x16x32_bf16 v[78:81], v[192:195], v[208:211], v[78:81]
	v_mfma_f32_16x16x32_bf16 v[74:77], v[192:195], v[216:219], v[74:77]
	v_mfma_f32_16x16x32_bf16 v[70:73], v[200:203], v[208:211], v[70:73]
	v_mfma_f32_16x16x32_bf16 v[66:69], v[200:203], v[216:219], v[66:69]
	s_mov_b32 m0, s100
	s_barrier
	ds_read_b128 v[172:175], v133 offset:16384
	ds_read_b128 v[176:179], v133 offset:17408
	ds_read_b128 v[180:183], v132 offset:16384
	ds_read_b128 v[184:187], v132 offset:17408
	ds_read_b128 v[188:191], v131 offset:16384
	ds_read_b128 v[192:195], v131 offset:17408
	ds_read_b128 v[196:199], v130 offset:16384
	buffer_load_dwordx4 v137, s[88:91], s15 offen lds
	s_add_i32 m0, s100, 0x2000
	ds_read_b128 v[200:203], v130 offset:17408
	buffer_load_dwordx4 v136, s[88:91], s15 offen lds
	s_barrier
	s_waitcnt lgkmcnt(1)
	v_mfma_f32_16x16x32_bf16 v[62:65], v[172:175], v[156:159], 0
	s_add_i32 s15, s3, 0xffffff80
	s_add_i32 m0, s100, 0x14000
	v_mfma_f32_16x16x32_bf16 v[58:61], v[172:175], v[164:167], 0
	v_mfma_f32_16x16x32_bf16 v[54:57], v[180:183], v[156:159], 0
	v_mfma_f32_16x16x32_bf16 v[50:53], v[180:183], v[164:167], 0
	v_mfma_f32_16x16x32_bf16 v[46:49], v[188:191], v[156:159], 0
	v_mfma_f32_16x16x32_bf16 v[42:45], v[188:191], v[164:167], 0
	v_mfma_f32_16x16x32_bf16 v[38:41], v[196:199], v[156:159], 0
	v_mfma_f32_16x16x32_bf16 v[34:37], v[196:199], v[164:167], 0
	v_mfma_f32_16x16x32_bf16 v[62:65], v[176:179], v[160:163], v[62:65]
	v_mfma_f32_16x16x32_bf16 v[58:61], v[176:179], v[168:171], v[58:61]
	v_mfma_f32_16x16x32_bf16 v[54:57], v[184:187], v[160:163], v[54:57]
	v_mfma_f32_16x16x32_bf16 v[50:53], v[184:187], v[168:171], v[50:53]
	v_mfma_f32_16x16x32_bf16 v[46:49], v[192:195], v[160:163], v[46:49]
	v_mfma_f32_16x16x32_bf16 v[42:45], v[192:195], v[168:171], v[42:45]
	s_waitcnt lgkmcnt(0)
	v_mfma_f32_16x16x32_bf16 v[38:41], v[200:203], v[160:163], v[38:41]
	v_mfma_f32_16x16x32_bf16 v[34:37], v[200:203], v[168:171], v[34:37]
	s_barrier
	buffer_load_dwordx4 v137, s[4:7], s15 offen lds
	s_add_i32 m0, s100, 0x16000
	s_nop 0
	buffer_load_dwordx4 v136, s[4:7], s15 offen lds
	s_waitcnt vmcnt(6)
	s_barrier
	v_mfma_f32_16x16x32_bf16 v[30:33], v[172:175], v[204:207], 0
	s_add_i32 m0, s100, 0x4000
	v_mfma_f32_16x16x32_bf16 v[26:29], v[172:175], v[212:215], 0
	v_mfma_f32_16x16x32_bf16 v[22:25], v[180:183], v[204:207], 0
	v_mfma_f32_16x16x32_bf16 v[18:21], v[180:183], v[212:215], 0
	v_mfma_f32_16x16x32_bf16 v[14:17], v[188:191], v[204:207], 0
	v_mfma_f32_16x16x32_bf16 v[10:13], v[188:191], v[212:215], 0
	v_mfma_f32_16x16x32_bf16 v[6:9], v[196:199], v[204:207], 0
	v_mfma_f32_16x16x32_bf16 v[2:5], v[196:199], v[212:215], 0
	v_mfma_f32_16x16x32_bf16 v[30:33], v[176:179], v[208:211], v[30:33]
	v_mfma_f32_16x16x32_bf16 v[26:29], v[176:179], v[216:219], v[26:29]
	v_mfma_f32_16x16x32_bf16 v[22:25], v[184:187], v[208:211], v[22:25]
	v_mfma_f32_16x16x32_bf16 v[18:21], v[184:187], v[216:219], v[18:21]
	v_mfma_f32_16x16x32_bf16 v[14:17], v[192:195], v[208:211], v[14:17]
	v_mfma_f32_16x16x32_bf16 v[10:13], v[192:195], v[216:219], v[10:13]
	v_mfma_f32_16x16x32_bf16 v[6:9], v[200:203], v[208:211], v[6:9]
	v_mfma_f32_16x16x32_bf16 v[2:5], v[200:203], v[216:219], v[2:5]
	s_barrier
	ds_read_b128 v[156:159], v135
	ds_read_b128 v[160:163], v135 offset:1024
	ds_read_b128 v[164:167], v135 offset:2048
	ds_read_b128 v[168:171], v135 offset:3072
	ds_read_b128 v[172:175], v133 offset:32768
	ds_read_b128 v[176:179], v133 offset:33792
	ds_read_b128 v[180:183], v132 offset:32768
	ds_read_b128 v[184:187], v132 offset:33792
	ds_read_b128 v[188:191], v131 offset:32768
	ds_read_b128 v[192:195], v131 offset:33792
	ds_read_b128 v[196:199], v130 offset:32768
	buffer_load_dwordx4 v137, s[88:91], s15 offen lds
	s_add_i32 m0, s100, 0x6000
	ds_read_b128 v[200:203], v130 offset:33792
	buffer_load_dwordx4 v136, s[88:91], s15 offen lds
	s_waitcnt lgkmcnt(8)
	s_barrier
; #define WAIT_V(n) asm volatile("s_waitcnt vmcnt(" #n ")" ::: "memory")
; #define WAIT_L(n) asm volatile("s_waitcnt lgkmcnt(" #n ")" ::: "memory")
; #define BAR __builtin_amdgcn_s_barrier()
; #define SCHED __builtin_amdgcn_sched_barrier(0)
; __device__ __forceinline__ void mainloop_8phase(const u16* __restrict__ A, const u16* __restrict__ Bt, int K,
;                                                 f32x4 (&acc)[2][2][4][2], int wid_s, int ld) {
;     ...
;     WAIT_L(8); BAR; WAIT_L(0); MMA(0, 0, At, B0); BAR; SCHED;
;     LDB(B1, 1, 1); STAGE(SB(1, 0), Bt, bcol, t + 3);
;     BAR; WAIT_L(0); MMA(0, 1, At, B1); BAR;
;     LDA(At, 1, 1); STAGE(SA(1, 0), A, brow, t + 3);
;     BAR; WAIT_L(0); MMA(1, 0, At, B0); BAR; SCHED;
;     STAGE(SB(1, 1), Bt, bcol + G_HALF, t + 3);
;     WAIT_V(6); BAR; MMA(1, 1, At, B1); BAR;
	s_waitcnt lgkmcnt(1)
	v_mfma_f32_16x16x32_bf16 v[126:129], v[172:175], v[156:159], v[126:129]
	s_add_i32 s15, s3, 0xfff80000
	s_add_i32 m0, s100, 0x18000
	v_mfma_f32_16x16x32_bf16 v[122:125], v[172:175], v[164:167], v[122:125]
	v_mfma_f32_16x16x32_bf16 v[118:121], v[180:183], v[156:159], v[118:121]
	v_mfma_f32_16x16x32_bf16 v[114:117], v[180:183], v[164:167], v[114:117]
	v_mfma_f32_16x16x32_bf16 v[110:113], v[188:191], v[156:159], v[110:113]
	v_mfma_f32_16x16x32_bf16 v[106:109], v[188:191], v[164:167], v[106:109]
	v_mfma_f32_16x16x32_bf16 v[102:105], v[196:199], v[156:159], v[102:105]
	v_mfma_f32_16x16x32_bf16 v[98:101], v[196:199], v[164:167], v[98:101]
	v_mfma_f32_16x16x32_bf16 v[126:129], v[176:179], v[160:163], v[126:129]
	v_mfma_f32_16x16x32_bf16 v[122:125], v[176:179], v[168:171], v[122:125]
	v_mfma_f32_16x16x32_bf16 v[118:121], v[184:187], v[160:163], v[118:121]
	v_mfma_f32_16x16x32_bf16 v[114:117], v[184:187], v[168:171], v[114:117]
	v_mfma_f32_16x16x32_bf16 v[110:113], v[192:195], v[160:163], v[110:113]
	v_mfma_f32_16x16x32_bf16 v[106:109], v[192:195], v[168:171], v[106:109]
	s_waitcnt lgkmcnt(0)
	v_mfma_f32_16x16x32_bf16 v[102:105], v[200:203], v[160:163], v[102:105]
	v_mfma_f32_16x16x32_bf16 v[98:101], v[200:203], v[168:171], v[98:101]
	s_barrier
	ds_read_b128 v[204:207], v134
	ds_read_b128 v[208:211], v134 offset:1024
	ds_read_b128 v[212:215], v134 offset:2048
	buffer_load_dwordx4 v137, s[4:7], s15 offen lds
	s_add_i32 m0, s100, 0x1a000
	ds_read_b128 v[216:219], v134 offset:3072
	buffer_load_dwordx4 v136, s[4:7], s15 offen lds
	s_barrier
	s_waitcnt lgkmcnt(1)
	v_mfma_f32_16x16x32_bf16 v[94:97], v[172:175], v[204:207], v[94:97]
	v_mfma_f32_16x16x32_bf16 v[90:93], v[172:175], v[212:215], v[90:93]
	v_mfma_f32_16x16x32_bf16 v[86:89], v[180:183], v[204:207], v[86:89]
	v_mfma_f32_16x16x32_bf16 v[82:85], v[180:183], v[212:215], v[82:85]
	v_mfma_f32_16x16x32_bf16 v[78:81], v[188:191], v[204:207], v[78:81]
	v_mfma_f32_16x16x32_bf16 v[74:77], v[188:191], v[212:215], v[74:77]
	v_mfma_f32_16x16x32_bf16 v[70:73], v[196:199], v[204:207], v[70:73]
	v_mfma_f32_16x16x32_bf16 v[66:69], v[196:199], v[212:215], v[66:69]
	v_mfma_f32_16x16x32_bf16 v[94:97], v[176:179], v[208:211], v[94:97]
	s_waitcnt lgkmcnt(0)
	v_mfma_f32_16x16x32_bf16 v[90:93], v[176:179], v[216:219], v[90:93]
	v_mfma_f32_16x16x32_bf16 v[86:89], v[184:187], v[208:211], v[86:89]
	v_mfma_f32_16x16x32_bf16 v[82:85], v[184:187], v[216:219], v[82:85]
	v_mfma_f32_16x16x32_bf16 v[78:81], v[192:195], v[208:211], v[78:81]
	v_mfma_f32_16x16x32_bf16 v[74:77], v[192:195], v[216:219], v[74:77]
	v_mfma_f32_16x16x32_bf16 v[70:73], v[200:203], v[208:211], v[70:73]
	v_mfma_f32_16x16x32_bf16 v[66:69], v[200:203], v[216:219], v[66:69]
	s_add_i32 m0, s100, 0x8000
	s_barrier
	ds_read_b128 v[172:175], v133 offset:49152
	ds_read_b128 v[176:179], v133 offset:50176
	ds_read_b128 v[180:183], v132 offset:49152
	ds_read_b128 v[184:187], v132 offset:50176
	ds_read_b128 v[188:191], v131 offset:49152
	ds_read_b128 v[192:195], v131 offset:50176
	ds_read_b128 v[196:199], v130 offset:49152
	buffer_load_dwordx4 v137, s[88:91], s15 offen lds
	s_add_i32 m0, s100, 0xa000
	ds_read_b128 v[200:203], v130 offset:50176
	buffer_load_dwordx4 v136, s[88:91], s15 offen lds
	s_barrier
	s_waitcnt lgkmcnt(1)
	v_mfma_f32_16x16x32_bf16 v[62:65], v[172:175], v[156:159], v[62:65]
	s_add_i32 m0, s100, 0x1c000
	v_mfma_f32_16x16x32_bf16 v[58:61], v[172:175], v[164:167], v[58:61]
	v_mfma_f32_16x16x32_bf16 v[54:57], v[180:183], v[156:159], v[54:57]
	v_mfma_f32_16x16x32_bf16 v[50:53], v[180:183], v[164:167], v[50:53]
	v_mfma_f32_16x16x32_bf16 v[46:49], v[188:191], v[156:159], v[46:49]
	v_mfma_f32_16x16x32_bf16 v[42:45], v[188:191], v[164:167], v[42:45]
	v_mfma_f32_16x16x32_bf16 v[38:41], v[196:199], v[156:159], v[38:41]
	v_mfma_f32_16x16x32_bf16 v[34:37], v[196:199], v[164:167], v[34:37]
	v_mfma_f32_16x16x32_bf16 v[62:65], v[176:179], v[160:163], v[62:65]
	v_mfma_f32_16x16x32_bf16 v[58:61], v[176:179], v[168:171], v[58:61]
	v_mfma_f32_16x16x32_bf16 v[54:57], v[184:187], v[160:163], v[54:57]
	v_mfma_f32_16x16x32_bf16 v[50:53], v[184:187], v[168:171], v[50:53]
	v_mfma_f32_16x16x32_bf16 v[46:49], v[192:195], v[160:163], v[46:49]
	v_mfma_f32_16x16x32_bf16 v[42:45], v[192:195], v[168:171], v[42:45]
	s_waitcnt lgkmcnt(0)
	v_mfma_f32_16x16x32_bf16 v[38:41], v[200:203], v[160:163], v[38:41]
	v_mfma_f32_16x16x32_bf16 v[34:37], v[200:203], v[168:171], v[34:37]
	s_barrier
	buffer_load_dwordx4 v137, s[4:7], s3 offen lds
	s_add_i32 m0, s100, 0x1e000
	s_nop 0
	buffer_load_dwordx4 v136, s[4:7], s3 offen lds
	s_waitcnt vmcnt(6)
	s_barrier
	v_mfma_f32_16x16x32_bf16 v[30:33], v[172:175], v[204:207], v[30:33]
	v_mfma_f32_16x16x32_bf16 v[26:29], v[172:175], v[212:215], v[26:29]
	v_mfma_f32_16x16x32_bf16 v[22:25], v[180:183], v[204:207], v[22:25]
	v_mfma_f32_16x16x32_bf16 v[18:21], v[180:183], v[212:215], v[18:21]
	v_mfma_f32_16x16x32_bf16 v[14:17], v[188:191], v[204:207], v[14:17]
	v_mfma_f32_16x16x32_bf16 v[10:13], v[188:191], v[212:215], v[10:13]
	v_mfma_f32_16x16x32_bf16 v[6:9], v[196:199], v[204:207], v[6:9]
	v_mfma_f32_16x16x32_bf16 v[2:5], v[196:199], v[212:215], v[2:5]
	v_mfma_f32_16x16x32_bf16 v[30:33], v[176:179], v[208:211], v[30:33]
	v_mfma_f32_16x16x32_bf16 v[26:29], v[176:179], v[216:219], v[26:29]
	v_mfma_f32_16x16x32_bf16 v[22:25], v[184:187], v[208:211], v[22:25]
	v_mfma_f32_16x16x32_bf16 v[18:21], v[184:187], v[216:219], v[18:21]
	v_mfma_f32_16x16x32_bf16 v[14:17], v[192:195], v[208:211], v[14:17]
	v_mfma_f32_16x16x32_bf16 v[10:13], v[192:195], v[216:219], v[10:13]
	v_mfma_f32_16x16x32_bf16 v[6:9], v[200:203], v[208:211], v[6:9]
	v_mfma_f32_16x16x32_bf16 v[2:5], v[200:203], v[216:219], v[2:5]
	s_add_i32 s2, s2, 2
	s_addk_i32 s3, 0x100
	s_add_i32 s6, s3, 0xffffff00
	s_add_i32 m0, s100, 0xc000
	s_cmp_lt_u32 s2, 28
	s_barrier
; #define WAIT_V(n) asm volatile("s_waitcnt vmcnt(" #n ")" ::: "memory")
; #define WAIT_L(n) asm volatile("s_waitcnt lgkmcnt(" #n ")" ::: "memory")
; #define BAR __builtin_amdgcn_s_barrier()
; #define SCHED __builtin_amdgcn_sched_barrier(0)
; __device__ __forceinline__ void mainloop_8phase(const u16* __restrict__ A, const u16* __restrict__ Bt, int K,
;                                                 f32x4 (&acc)[2][2][4][2], int wid_s, int ld) {
;     ...
;   for (int t = 0; t < nt - 2; t += 2) {
;     LDB(B0, 0, 0); SCHED; LDA(At, 0, 0); STAGE(SA(1, 1), A, brow + G_HALF, t + 1);
;     WAIT_L(8); BAR; WAIT_L(0); MMA(0, 0, At, B0); BAR; SCHED;
;     LDB(B1, 0, 1); STAGE(SB(0, 0), Bt, bcol, t + 2);
;     BAR; WAIT_L(0); MMA(0, 1, At, B1); BAR;
;     LDA(At, 0, 1); STAGE(SA(0, 0), A, brow, t + 2);
;     BAR; WAIT_L(0); MMA(1, 0, At, B0); BAR; SCHED;
;     STAGE(SB(0, 1), Bt, bcol + G_HALF, t + 2);
;     WAIT_V(6); BAR; MMA(1, 1, At, B1); BAR;
.LBB0_162:
	ds_read_b128 v[156:159], v148
	ds_read_b128 v[160:163], v148 offset:1024
	ds_read_b128 v[164:167], v148 offset:2048
	ds_read_b128 v[168:171], v148 offset:3072
	ds_read_b128 v[172:175], v133
	ds_read_b128 v[176:179], v133 offset:1024
	ds_read_b128 v[180:183], v132
	ds_read_b128 v[184:187], v132 offset:1024
	ds_read_b128 v[188:191], v131
	ds_read_b128 v[192:195], v131 offset:1024
	ds_read_b128 v[196:199], v130
	buffer_load_dwordx4 v137, s[88:91], s6 offen lds
	s_add_i32 m0, s100, 0xe000
	ds_read_b128 v[200:203], v130 offset:1024
	buffer_load_dwordx4 v136, s[88:91], s6 offen lds
	s_waitcnt lgkmcnt(8)
	s_barrier
	s_waitcnt lgkmcnt(1)
	v_mfma_f32_16x16x32_bf16 v[126:129], v[172:175], v[156:159], v[126:129]
	s_add_i32 s15, s3, 0xfff7ff80
	s_add_i32 m0, s100, 0x10000
	v_mfma_f32_16x16x32_bf16 v[122:125], v[172:175], v[164:167], v[122:125]
	v_mfma_f32_16x16x32_bf16 v[118:121], v[180:183], v[156:159], v[118:121]
	v_mfma_f32_16x16x32_bf16 v[114:117], v[180:183], v[164:167], v[114:117]
	v_mfma_f32_16x16x32_bf16 v[110:113], v[188:191], v[156:159], v[110:113]
	v_mfma_f32_16x16x32_bf16 v[106:109], v[188:191], v[164:167], v[106:109]
	v_mfma_f32_16x16x32_bf16 v[102:105], v[196:199], v[156:159], v[102:105]
	v_mfma_f32_16x16x32_bf16 v[98:101], v[196:199], v[164:167], v[98:101]
	v_mfma_f32_16x16x32_bf16 v[126:129], v[176:179], v[160:163], v[126:129]
	v_mfma_f32_16x16x32_bf16 v[122:125], v[176:179], v[168:171], v[122:125]
	v_mfma_f32_16x16x32_bf16 v[118:121], v[184:187], v[160:163], v[118:121]
	v_mfma_f32_16x16x32_bf16 v[114:117], v[184:187], v[168:171], v[114:117]
	v_mfma_f32_16x16x32_bf16 v[110:113], v[192:195], v[160:163], v[110:113]
	v_mfma_f32_16x16x32_bf16 v[106:109], v[192:195], v[168:171], v[106:109]
	s_waitcnt lgkmcnt(0)
	v_mfma_f32_16x16x32_bf16 v[102:105], v[200:203], v[160:163], v[102:105]
	v_mfma_f32_16x16x32_bf16 v[98:101], v[200:203], v[168:171], v[98:101]
	s_barrier
	s_mov_b32 s6, s90
	ds_read_b128 v[204:207], v145
	ds_read_b128 v[208:211], v145 offset:1024
	ds_read_b128 v[212:215], v145 offset:2048
	buffer_load_dwordx4 v137, s[4:7], s15 offen lds
	s_add_i32 m0, s100, 0x12000
	ds_read_b128 v[216:219], v145 offset:3072
	buffer_load_dwordx4 v136, s[4:7], s15 offen lds
	s_barrier
	s_waitcnt lgkmcnt(1)
	v_mfma_f32_16x16x32_bf16 v[94:97], v[172:175], v[204:207], v[94:97]
	v_mfma_f32_16x16x32_bf16 v[90:93], v[172:175], v[212:215], v[90:93]
	v_mfma_f32_16x16x32_bf16 v[86:89], v[180:183], v[204:207], v[86:89]
	v_mfma_f32_16x16x32_bf16 v[82:85], v[180:183], v[212:215], v[82:85]
	v_mfma_f32_16x16x32_bf16 v[78:81], v[188:191], v[204:207], v[78:81]
	v_mfma_f32_16x16x32_bf16 v[74:77], v[188:191], v[212:215], v[74:77]
	v_mfma_f32_16x16x32_bf16 v[70:73], v[196:199], v[204:207], v[70:73]
	v_mfma_f32_16x16x32_bf16 v[66:69], v[196:199], v[212:215], v[66:69]
	v_mfma_f32_16x16x32_bf16 v[94:97], v[176:179], v[208:211], v[94:97]
	s_waitcnt lgkmcnt(0)
	v_mfma_f32_16x16x32_bf16 v[90:93], v[176:179], v[216:219], v[90:93]
	v_mfma_f32_16x16x32_bf16 v[86:89], v[184:187], v[208:211], v[86:89]
	v_mfma_f32_16x16x32_bf16 v[82:85], v[184:187], v[216:219], v[82:85]
	v_mfma_f32_16x16x32_bf16 v[78:81], v[192:195], v[208:211], v[78:81]
	v_mfma_f32_16x16x32_bf16 v[74:77], v[192:195], v[216:219], v[74:77]
	v_mfma_f32_16x16x32_bf16 v[70:73], v[200:203], v[208:211], v[70:73]
	v_mfma_f32_16x16x32_bf16 v[66:69], v[200:203], v[216:219], v[66:69]
	s_mov_b32 m0, s100
	s_barrier
	ds_read_b128 v[172:175], v133 offset:16384
	ds_read_b128 v[176:179], v133 offset:17408
	ds_read_b128 v[180:183], v132 offset:16384
	ds_read_b128 v[184:187], v132 offset:17408
	ds_read_b128 v[188:191], v131 offset:16384
	ds_read_b128 v[192:195], v131 offset:17408
	ds_read_b128 v[196:199], v130 offset:16384
	buffer_load_dwordx4 v137, s[88:91], s15 offen lds
	s_add_i32 m0, s100, 0x2000
	ds_read_b128 v[200:203], v130 offset:17408
	buffer_load_dwordx4 v136, s[88:91], s15 offen lds
	s_barrier
	s_waitcnt lgkmcnt(1)
	v_mfma_f32_16x16x32_bf16 v[62:65], v[172:175], v[156:159], v[62:65]
	s_add_i32 s15, s3, 0xffffff80
	s_add_i32 m0, s100, 0x14000
	v_mfma_f32_16x16x32_bf16 v[58:61], v[172:175], v[164:167], v[58:61]
	v_mfma_f32_16x16x32_bf16 v[54:57], v[180:183], v[156:159], v[54:57]
	v_mfma_f32_16x16x32_bf16 v[50:53], v[180:183], v[164:167], v[50:53]
	v_mfma_f32_16x16x32_bf16 v[46:49], v[188:191], v[156:159], v[46:49]
	v_mfma_f32_16x16x32_bf16 v[42:45], v[188:191], v[164:167], v[42:45]
	v_mfma_f32_16x16x32_bf16 v[38:41], v[196:199], v[156:159], v[38:41]
	v_mfma_f32_16x16x32_bf16 v[34:37], v[196:199], v[164:167], v[34:37]
	v_mfma_f32_16x16x32_bf16 v[62:65], v[176:179], v[160:163], v[62:65]
	v_mfma_f32_16x16x32_bf16 v[58:61], v[176:179], v[168:171], v[58:61]
	v_mfma_f32_16x16x32_bf16 v[54:57], v[184:187], v[160:163], v[54:57]
	v_mfma_f32_16x16x32_bf16 v[50:53], v[184:187], v[168:171], v[50:53]
	v_mfma_f32_16x16x32_bf16 v[46:49], v[192:195], v[160:163], v[46:49]
	v_mfma_f32_16x16x32_bf16 v[42:45], v[192:195], v[168:171], v[42:45]
	s_waitcnt lgkmcnt(0)
	v_mfma_f32_16x16x32_bf16 v[38:41], v[200:203], v[160:163], v[38:41]
	v_mfma_f32_16x16x32_bf16 v[34:37], v[200:203], v[168:171], v[34:37]
	s_barrier
	buffer_load_dwordx4 v137, s[4:7], s15 offen lds
	s_add_i32 m0, s100, 0x16000
	s_nop 0
	buffer_load_dwordx4 v136, s[4:7], s15 offen lds
	s_waitcnt vmcnt(6)
	s_barrier
; #define WAIT_V(n) asm volatile("s_waitcnt vmcnt(" #n ")" ::: "memory")
; #define WAIT_L(n) asm volatile("s_waitcnt lgkmcnt(" #n ")" ::: "memory")
; #define BAR __builtin_amdgcn_s_barrier()
; #define SCHED __builtin_amdgcn_sched_barrier(0)
; __device__ __forceinline__ void mainloop_8phase(const u16* __restrict__ A, const u16* __restrict__ Bt, int K,
;                                                 f32x4 (&acc)[2][2][4][2], int wid_s, int ld) {
;     ...
;     WAIT_V(6); BAR; MMA(1, 1, At, B1); BAR;
;     LDB(B0, 1, 0); SCHED; LDA(At, 1, 0); STAGE(SA(0, 1), A, brow + G_HALF, t + 2);
;     WAIT_L(8); BAR; WAIT_L(0); MMA(0, 0, At, B0); BAR; SCHED;
;     LDB(B1, 1, 1); STAGE(SB(1, 0), Bt, bcol, t + 3);
;     BAR; WAIT_L(0); MMA(0, 1, At, B1); BAR;
;     LDA(At, 1, 1); STAGE(SA(1, 0), A, brow, t + 3);
	v_mfma_f32_16x16x32_bf16 v[30:33], v[172:175], v[204:207], v[30:33]
	s_add_i32 m0, s100, 0x4000
	v_mfma_f32_16x16x32_bf16 v[26:29], v[172:175], v[212:215], v[26:29]
	v_mfma_f32_16x16x32_bf16 v[22:25], v[180:183], v[204:207], v[22:25]
	v_mfma_f32_16x16x32_bf16 v[18:21], v[180:183], v[212:215], v[18:21]
	v_mfma_f32_16x16x32_bf16 v[14:17], v[188:191], v[204:207], v[14:17]
	v_mfma_f32_16x16x32_bf16 v[10:13], v[188:191], v[212:215], v[10:13]
	v_mfma_f32_16x16x32_bf16 v[6:9], v[196:199], v[204:207], v[6:9]
	v_mfma_f32_16x16x32_bf16 v[2:5], v[196:199], v[212:215], v[2:5]
	v_mfma_f32_16x16x32_bf16 v[30:33], v[176:179], v[208:211], v[30:33]
	v_mfma_f32_16x16x32_bf16 v[26:29], v[176:179], v[216:219], v[26:29]
	v_mfma_f32_16x16x32_bf16 v[22:25], v[184:187], v[208:211], v[22:25]
	v_mfma_f32_16x16x32_bf16 v[18:21], v[184:187], v[216:219], v[18:21]
	v_mfma_f32_16x16x32_bf16 v[14:17], v[192:195], v[208:211], v[14:17]
	v_mfma_f32_16x16x32_bf16 v[10:13], v[192:195], v[216:219], v[10:13]
	v_mfma_f32_16x16x32_bf16 v[6:9], v[200:203], v[208:211], v[6:9]
	v_mfma_f32_16x16x32_bf16 v[2:5], v[200:203], v[216:219], v[2:5]
	s_barrier
	ds_read_b128 v[156:159], v135
	ds_read_b128 v[160:163], v135 offset:1024
	ds_read_b128 v[164:167], v135 offset:2048
	ds_read_b128 v[168:171], v135 offset:3072
	ds_read_b128 v[172:175], v133 offset:32768
	ds_read_b128 v[176:179], v133 offset:33792
	ds_read_b128 v[180:183], v132 offset:32768
	ds_read_b128 v[184:187], v132 offset:33792
	ds_read_b128 v[188:191], v131 offset:32768
	ds_read_b128 v[192:195], v131 offset:33792
	ds_read_b128 v[196:199], v130 offset:32768
	buffer_load_dwordx4 v137, s[88:91], s15 offen lds
	s_add_i32 m0, s100, 0x6000
	ds_read_b128 v[200:203], v130 offset:33792
	buffer_load_dwordx4 v136, s[88:91], s15 offen lds
	s_waitcnt lgkmcnt(8)
	s_barrier
	s_waitcnt lgkmcnt(1)
	v_mfma_f32_16x16x32_bf16 v[126:129], v[172:175], v[156:159], v[126:129]
	s_add_i32 s15, s3, 0xfff80000
	s_add_i32 m0, s100, 0x18000
	v_mfma_f32_16x16x32_bf16 v[122:125], v[172:175], v[164:167], v[122:125]
	v_mfma_f32_16x16x32_bf16 v[118:121], v[180:183], v[156:159], v[118:121]
	v_mfma_f32_16x16x32_bf16 v[114:117], v[180:183], v[164:167], v[114:117]
	v_mfma_f32_16x16x32_bf16 v[110:113], v[188:191], v[156:159], v[110:113]
	v_mfma_f32_16x16x32_bf16 v[106:109], v[188:191], v[164:167], v[106:109]
	v_mfma_f32_16x16x32_bf16 v[102:105], v[196:199], v[156:159], v[102:105]
	v_mfma_f32_16x16x32_bf16 v[98:101], v[196:199], v[164:167], v[98:101]
	v_mfma_f32_16x16x32_bf16 v[126:129], v[176:179], v[160:163], v[126:129]
	v_mfma_f32_16x16x32_bf16 v[122:125], v[176:179], v[168:171], v[122:125]
	v_mfma_f32_16x16x32_bf16 v[118:121], v[184:187], v[160:163], v[118:121]
	v_mfma_f32_16x16x32_bf16 v[114:117], v[184:187], v[168:171], v[114:117]
	v_mfma_f32_16x16x32_bf16 v[110:113], v[192:195], v[160:163], v[110:113]
	v_mfma_f32_16x16x32_bf16 v[106:109], v[192:195], v[168:171], v[106:109]
	s_waitcnt lgkmcnt(0)
	v_mfma_f32_16x16x32_bf16 v[102:105], v[200:203], v[160:163], v[102:105]
	v_mfma_f32_16x16x32_bf16 v[98:101], v[200:203], v[168:171], v[98:101]
	s_barrier
	ds_read_b128 v[204:207], v134
	ds_read_b128 v[208:211], v134 offset:1024
	ds_read_b128 v[212:215], v134 offset:2048
	buffer_load_dwordx4 v137, s[4:7], s15 offen lds
	s_add_i32 m0, s100, 0x1a000
	ds_read_b128 v[216:219], v134 offset:3072
	buffer_load_dwordx4 v136, s[4:7], s15 offen lds
	s_barrier
	s_waitcnt lgkmcnt(1)
	v_mfma_f32_16x16x32_bf16 v[94:97], v[172:175], v[204:207], v[94:97]
	v_mfma_f32_16x16x32_bf16 v[90:93], v[172:175], v[212:215], v[90:93]
	v_mfma_f32_16x16x32_bf16 v[86:89], v[180:183], v[204:207], v[86:89]
	v_mfma_f32_16x16x32_bf16 v[82:85], v[180:183], v[212:215], v[82:85]
	v_mfma_f32_16x16x32_bf16 v[78:81], v[188:191], v[204:207], v[78:81]
	v_mfma_f32_16x16x32_bf16 v[74:77], v[188:191], v[212:215], v[74:77]
	v_mfma_f32_16x16x32_bf16 v[70:73], v[196:199], v[204:207], v[70:73]
	v_mfma_f32_16x16x32_bf16 v[66:69], v[196:199], v[212:215], v[66:69]
	v_mfma_f32_16x16x32_bf16 v[94:97], v[176:179], v[208:211], v[94:97]
	s_waitcnt lgkmcnt(0)
	v_mfma_f32_16x16x32_bf16 v[90:93], v[176:179], v[216:219], v[90:93]
	v_mfma_f32_16x16x32_bf16 v[86:89], v[184:187], v[208:211], v[86:89]
	v_mfma_f32_16x16x32_bf16 v[82:85], v[184:187], v[216:219], v[82:85]
	v_mfma_f32_16x16x32_bf16 v[78:81], v[192:195], v[208:211], v[78:81]
	v_mfma_f32_16x16x32_bf16 v[74:77], v[192:195], v[216:219], v[74:77]
	v_mfma_f32_16x16x32_bf16 v[70:73], v[200:203], v[208:211], v[70:73]
	v_mfma_f32_16x16x32_bf16 v[66:69], v[200:203], v[216:219], v[66:69]
	s_add_i32 m0, s100, 0x8000
	s_barrier
	ds_read_b128 v[172:175], v133 offset:49152
	ds_read_b128 v[176:179], v133 offset:50176
	ds_read_b128 v[180:183], v132 offset:49152
	ds_read_b128 v[184:187], v132 offset:50176
	ds_read_b128 v[188:191], v131 offset:49152
	ds_read_b128 v[192:195], v131 offset:50176
	ds_read_b128 v[196:199], v130 offset:49152
	buffer_load_dwordx4 v137, s[88:91], s15 offen lds
	s_add_i32 m0, s100, 0xa000
	ds_read_b128 v[200:203], v130 offset:50176
	buffer_load_dwordx4 v136, s[88:91], s15 offen lds
	s_barrier
; #define WAIT_V(n) asm volatile("s_waitcnt vmcnt(" #n ")" ::: "memory")
; #define WAIT_L(n) asm volatile("s_waitcnt lgkmcnt(" #n ")" ::: "memory")
; #define BAR __builtin_amdgcn_s_barrier()
; #define SCHED __builtin_amdgcn_sched_barrier(0)
; __device__ __forceinline__ void mainloop_8phase(const u16* __restrict__ A, const u16* __restrict__ Bt, int K,
;                                                 f32x4 (&acc)[2][2][4][2], int wid_s, int ld) {
;     ...
;     BAR; WAIT_L(0); MMA(1, 0, At, B0); BAR; SCHED;
;     STAGE(SB(1, 1), Bt, bcol + G_HALF, t + 3);
;     WAIT_V(6); BAR; MMA(1, 1, At, B1); BAR;
;   }
;   { LDB(B0, 0, 0); LDA(At, 0, 0); STAGE(SA(1, 1), A, brow + G_HALF, nt - 1);
;     BAR; WAIT_L(0); MMA(0, 0, At, B0); BAR;
	s_waitcnt lgkmcnt(1)
	v_mfma_f32_16x16x32_bf16 v[62:65], v[172:175], v[156:159], v[62:65]
	s_add_i32 m0, s100, 0x1c000
	v_mfma_f32_16x16x32_bf16 v[58:61], v[172:175], v[164:167], v[58:61]
	v_mfma_f32_16x16x32_bf16 v[54:57], v[180:183], v[156:159], v[54:57]
	v_mfma_f32_16x16x32_bf16 v[50:53], v[180:183], v[164:167], v[50:53]
	v_mfma_f32_16x16x32_bf16 v[46:49], v[188:191], v[156:159], v[46:49]
	v_mfma_f32_16x16x32_bf16 v[42:45], v[188:191], v[164:167], v[42:45]
	v_mfma_f32_16x16x32_bf16 v[38:41], v[196:199], v[156:159], v[38:41]
	v_mfma_f32_16x16x32_bf16 v[34:37], v[196:199], v[164:167], v[34:37]
	v_mfma_f32_16x16x32_bf16 v[62:65], v[176:179], v[160:163], v[62:65]
	v_mfma_f32_16x16x32_bf16 v[58:61], v[176:179], v[168:171], v[58:61]
	v_mfma_f32_16x16x32_bf16 v[54:57], v[184:187], v[160:163], v[54:57]
	v_mfma_f32_16x16x32_bf16 v[50:53], v[184:187], v[168:171], v[50:53]
	v_mfma_f32_16x16x32_bf16 v[46:49], v[192:195], v[160:163], v[46:49]
	v_mfma_f32_16x16x32_bf16 v[42:45], v[192:195], v[168:171], v[42:45]
	s_waitcnt lgkmcnt(0)
	v_mfma_f32_16x16x32_bf16 v[38:41], v[200:203], v[160:163], v[38:41]
	v_mfma_f32_16x16x32_bf16 v[34:37], v[200:203], v[168:171], v[34:37]
	s_barrier
	buffer_load_dwordx4 v137, s[4:7], s3 offen lds
	s_add_i32 m0, s100, 0x1e000
	s_nop 0
	buffer_load_dwordx4 v136, s[4:7], s3 offen lds
	s_waitcnt vmcnt(6)
	s_barrier
	v_mfma_f32_16x16x32_bf16 v[30:33], v[172:175], v[204:207], v[30:33]
	v_mfma_f32_16x16x32_bf16 v[26:29], v[172:175], v[212:215], v[26:29]
	v_mfma_f32_16x16x32_bf16 v[22:25], v[180:183], v[204:207], v[22:25]
	v_mfma_f32_16x16x32_bf16 v[18:21], v[180:183], v[212:215], v[18:21]
	v_mfma_f32_16x16x32_bf16 v[14:17], v[188:191], v[204:207], v[14:17]
	v_mfma_f32_16x16x32_bf16 v[10:13], v[188:191], v[212:215], v[10:13]
	v_mfma_f32_16x16x32_bf16 v[6:9], v[196:199], v[204:207], v[6:9]
	v_mfma_f32_16x16x32_bf16 v[2:5], v[196:199], v[212:215], v[2:5]
	v_mfma_f32_16x16x32_bf16 v[30:33], v[176:179], v[208:211], v[30:33]
	v_mfma_f32_16x16x32_bf16 v[26:29], v[176:179], v[216:219], v[26:29]
	v_mfma_f32_16x16x32_bf16 v[22:25], v[184:187], v[208:211], v[22:25]
	v_mfma_f32_16x16x32_bf16 v[18:21], v[184:187], v[216:219], v[18:21]
	v_mfma_f32_16x16x32_bf16 v[14:17], v[192:195], v[208:211], v[14:17]
	v_mfma_f32_16x16x32_bf16 v[10:13], v[192:195], v[216:219], v[10:13]
	v_mfma_f32_16x16x32_bf16 v[6:9], v[200:203], v[208:211], v[6:9]
	v_mfma_f32_16x16x32_bf16 v[2:5], v[200:203], v[216:219], v[2:5]
	s_add_i32 s2, s2, 2
	s_addk_i32 s3, 0x100
	s_add_i32 s6, s3, 0xffffff00
	s_add_i32 m0, s100, 0xc000
	s_cmp_lt_u32 s2, 28
	s_barrier
	s_cbranch_scc1 .LBB0_162
	v_readfirstlane_b32 s2, v150
	s_mov_b32 m0, s2
	s_mov_b32 s3, 0x80f80
	v_readfirstlane_b32 s2, v149
	ds_read_b128 v[138:141], v148
	ds_read_b128 v[152:155], v148 offset:1024
	ds_read_b128 v[156:159], v148 offset:2048
	ds_read_b128 v[160:163], v148 offset:3072
	ds_read_b128 v[164:167], v133
	ds_read_b128 v[168:171], v133 offset:1024
	ds_read_b128 v[172:175], v132
	ds_read_b128 v[176:179], v132 offset:1024
	ds_read_b128 v[180:183], v131
	ds_read_b128 v[184:187], v131 offset:1024
	ds_read_b128 v[188:191], v130
	ds_read_b128 v[192:195], v130 offset:1024
	buffer_load_dwordx4 v137, s[88:91], s3 offen lds
	s_mov_b32 m0, s2
	s_nop 0
	buffer_load_dwordx4 v136, s[88:91], s3 offen lds
	s_barrier
	s_waitcnt lgkmcnt(0)
	v_mfma_f32_16x16x32_bf16 v[126:129], v[164:167], v[138:141], v[126:129]
	v_mfma_f32_16x16x32_bf16 v[118:121], v[172:175], v[138:141], v[118:121]
	v_mfma_f32_16x16x32_bf16 v[110:113], v[180:183], v[138:141], v[110:113]
	v_mfma_f32_16x16x32_bf16 v[102:105], v[188:191], v[138:141], v[102:105]
	v_mfma_f32_16x16x32_bf16 v[126:129], v[168:171], v[152:155], v[126:129]
	v_mfma_f32_16x16x32_bf16 v[122:125], v[164:167], v[156:159], v[122:125]
	v_mfma_f32_16x16x32_bf16 v[118:121], v[176:179], v[152:155], v[118:121]
	v_mfma_f32_16x16x32_bf16 v[114:117], v[172:175], v[156:159], v[114:117]
	v_mfma_f32_16x16x32_bf16 v[110:113], v[184:187], v[152:155], v[110:113]
	v_mfma_f32_16x16x32_bf16 v[106:109], v[180:183], v[156:159], v[106:109]
	v_mfma_f32_16x16x32_bf16 v[102:105], v[192:195], v[152:155], v[102:105]
	v_mfma_f32_16x16x32_bf16 v[98:101], v[188:191], v[156:159], v[98:101]
	v_mfma_f32_16x16x32_bf16 v[146:149], v[168:171], v[160:163], v[122:125]
	v_mfma_f32_16x16x32_bf16 v[196:199], v[176:179], v[160:163], v[114:117]
	v_mfma_f32_16x16x32_bf16 v[200:203], v[184:187], v[160:163], v[106:109]
	v_mfma_f32_16x16x32_bf16 v[204:207], v[192:195], v[160:163], v[98:101]
	s_barrier
	s_nop 1
	ds_read_b128 v[98:101], v145
	ds_read_b128 v[106:109], v145 offset:1024
	ds_read_b128 v[114:117], v145 offset:2048
	ds_read_b128 v[122:125], v145 offset:3072
	s_barrier
	s_waitcnt lgkmcnt(0)
	v_mfma_f32_16x16x32_bf16 v[94:97], v[164:167], v[98:101], v[94:97]
	v_mfma_f32_16x16x32_bf16 v[90:93], v[164:167], v[114:117], v[90:93]
	v_mfma_f32_16x16x32_bf16 v[86:89], v[172:175], v[98:101], v[86:89]
	v_mfma_f32_16x16x32_bf16 v[82:85], v[172:175], v[114:117], v[82:85]
	v_mfma_f32_16x16x32_bf16 v[78:81], v[180:183], v[98:101], v[78:81]
	v_mfma_f32_16x16x32_bf16 v[74:77], v[180:183], v[114:117], v[74:77]
	v_mfma_f32_16x16x32_bf16 v[70:73], v[188:191], v[98:101], v[70:73]
	v_mfma_f32_16x16x32_bf16 v[66:69], v[188:191], v[114:117], v[66:69]
	v_mfma_f32_16x16x32_bf16 v[94:97], v[168:171], v[106:109], v[94:97]
	v_mfma_f32_16x16x32_bf16 v[90:93], v[168:171], v[122:125], v[90:93]
	v_mfma_f32_16x16x32_bf16 v[86:89], v[176:179], v[106:109], v[86:89]
	v_mfma_f32_16x16x32_bf16 v[82:85], v[176:179], v[122:125], v[82:85]
	v_mfma_f32_16x16x32_bf16 v[78:81], v[184:187], v[106:109], v[78:81]
	v_mfma_f32_16x16x32_bf16 v[74:77], v[184:187], v[122:125], v[74:77]
	v_mfma_f32_16x16x32_bf16 v[70:73], v[192:195], v[106:109], v[70:73]
	v_mfma_f32_16x16x32_bf16 v[66:69], v[192:195], v[122:125], v[66:69]
	s_barrier
; #define WAIT_V(n) asm volatile("s_waitcnt vmcnt(" #n ")" ::: "memory")
; #define WAIT_L(n) asm volatile("s_waitcnt lgkmcnt(" #n ")" ::: "memory")
; #define BAR __builtin_amdgcn_s_barrier()
; __device__ __forceinline__ void mainloop_8phase(const u16* __restrict__ A, const u16* __restrict__ Bt, int K,
;                                                 f32x4 (&acc)[2][2][4][2], int wid_s, int ld) {
;     ...
;     LDB(B1, 0, 1); BAR; WAIT_L(0); MMA(0, 1, At, B1); BAR;
;     LDA(At, 0, 1); WAIT_V(4); BAR; WAIT_L(0); MMA(1, 0, At, B0); MMA(1, 1, At, B1); BAR; }
;   { LDB(B0, 1, 0); LDA(At, 1, 0); WAIT_V(2); BAR; WAIT_L(0); MMA(0, 0, At, B0); BAR;
	ds_read_b128 v[142:145], v133 offset:16384
	ds_read_b128 v[164:167], v133 offset:17408
	ds_read_b128 v[168:171], v132 offset:16384
	ds_read_b128 v[172:175], v132 offset:17408
	ds_read_b128 v[176:179], v131 offset:16384
	ds_read_b128 v[180:183], v131 offset:17408
	ds_read_b128 v[184:187], v130 offset:16384
	ds_read_b128 v[188:191], v130 offset:17408
	s_waitcnt vmcnt(4)
	s_barrier
	s_waitcnt lgkmcnt(0)
	v_mfma_f32_16x16x32_bf16 v[62:65], v[142:145], v[138:141], v[62:65]
	v_mfma_f32_16x16x32_bf16 v[58:61], v[142:145], v[156:159], v[58:61]
	v_mfma_f32_16x16x32_bf16 v[54:57], v[168:171], v[138:141], v[54:57]
	v_mfma_f32_16x16x32_bf16 v[50:53], v[168:171], v[156:159], v[50:53]
	v_mfma_f32_16x16x32_bf16 v[46:49], v[176:179], v[138:141], v[46:49]
	v_mfma_f32_16x16x32_bf16 v[42:45], v[176:179], v[156:159], v[42:45]
	v_mfma_f32_16x16x32_bf16 v[38:41], v[184:187], v[138:141], v[38:41]
	v_mfma_f32_16x16x32_bf16 v[34:37], v[184:187], v[156:159], v[34:37]
	v_mfma_f32_16x16x32_bf16 v[192:195], v[164:167], v[152:155], v[62:65]
	v_mfma_f32_16x16x32_bf16 v[208:211], v[164:167], v[160:163], v[58:61]
	v_mfma_f32_16x16x32_bf16 v[212:215], v[172:175], v[152:155], v[54:57]
	v_mfma_f32_16x16x32_bf16 v[216:219], v[172:175], v[160:163], v[50:53]
	v_mfma_f32_16x16x32_bf16 v[220:223], v[180:183], v[152:155], v[46:49]
	v_mfma_f32_16x16x32_bf16 v[224:227], v[180:183], v[160:163], v[42:45]
	v_mfma_f32_16x16x32_bf16 v[136:139], v[188:191], v[152:155], v[38:41]
	v_mfma_f32_16x16x32_bf16 v[150:153], v[188:191], v[160:163], v[34:37]
	v_mfma_f32_16x16x32_bf16 v[30:33], v[142:145], v[98:101], v[30:33]
	v_mfma_f32_16x16x32_bf16 v[22:25], v[168:171], v[98:101], v[22:25]
	v_mfma_f32_16x16x32_bf16 v[14:17], v[176:179], v[98:101], v[14:17]
	v_mfma_f32_16x16x32_bf16 v[6:9], v[184:187], v[98:101], v[6:9]
	v_mfma_f32_16x16x32_bf16 v[30:33], v[164:167], v[106:109], v[30:33]
	v_mfma_f32_16x16x32_bf16 v[26:29], v[142:145], v[114:117], v[26:29]
	v_mfma_f32_16x16x32_bf16 v[22:25], v[172:175], v[106:109], v[22:25]
	v_mfma_f32_16x16x32_bf16 v[18:21], v[168:171], v[114:117], v[18:21]
	v_mfma_f32_16x16x32_bf16 v[14:17], v[180:183], v[106:109], v[14:17]
	v_mfma_f32_16x16x32_bf16 v[10:13], v[176:179], v[114:117], v[10:13]
	v_mfma_f32_16x16x32_bf16 v[6:9], v[188:191], v[106:109], v[6:9]
	v_mfma_f32_16x16x32_bf16 v[2:5], v[184:187], v[114:117], v[2:5]
	v_mfma_f32_16x16x32_bf16 v[140:143], v[164:167], v[122:125], v[26:29]
	v_mfma_f32_16x16x32_bf16 v[154:157], v[172:175], v[122:125], v[18:21]
	v_mfma_f32_16x16x32_bf16 v[158:161], v[180:183], v[122:125], v[10:13]
	v_mfma_f32_16x16x32_bf16 v[162:165], v[188:191], v[122:125], v[2:5]
	s_barrier
	s_nop 1
	ds_read_b128 v[2:5], v135
	ds_read_b128 v[166:169], v135 offset:1024
	ds_read_b128 v[170:173], v135 offset:2048
	ds_read_b128 v[174:177], v135 offset:3072
	ds_read_b128 v[10:13], v133 offset:32768
	ds_read_b128 v[18:21], v133 offset:33792
	ds_read_b128 v[26:29], v132 offset:32768
	ds_read_b128 v[38:41], v132 offset:33792
	ds_read_b128 v[46:49], v131 offset:32768
	ds_read_b128 v[178:181], v131 offset:33792
	ds_read_b128 v[182:185], v130 offset:32768
	ds_read_b128 v[186:189], v130 offset:33792
	s_waitcnt vmcnt(2)
	s_barrier
	s_waitcnt lgkmcnt(0)
	v_mfma_f32_16x16x32_bf16 v[34:37], v[10:13], v[2:5], v[126:129]
	v_mfma_f32_16x16x32_bf16 v[122:125], v[18:21], v[166:169], v[34:37]
	v_mfma_f32_16x16x32_bf16 v[34:37], v[10:13], v[170:173], v[146:149]
	v_mfma_f32_16x16x32_bf16 v[58:61], v[18:21], v[174:177], v[34:37]
	v_mfma_f32_16x16x32_bf16 v[34:37], v[26:29], v[2:5], v[118:121]
	v_mfma_f32_16x16x32_bf16 v[114:117], v[38:41], v[166:169], v[34:37]
	v_mfma_f32_16x16x32_bf16 v[34:37], v[26:29], v[170:173], v[196:199]
	v_mfma_f32_16x16x32_bf16 v[50:53], v[38:41], v[174:177], v[34:37]
	v_mfma_f32_16x16x32_bf16 v[34:37], v[46:49], v[2:5], v[110:113]
	v_mfma_f32_16x16x32_bf16 v[106:109], v[178:181], v[166:169], v[34:37]
	v_mfma_f32_16x16x32_bf16 v[34:37], v[46:49], v[170:173], v[200:203]
	v_mfma_f32_16x16x32_bf16 v[42:45], v[178:181], v[174:177], v[34:37]
	v_mfma_f32_16x16x32_bf16 v[34:37], v[182:185], v[2:5], v[102:105]
	v_mfma_f32_16x16x32_bf16 v[98:101], v[186:189], v[166:169], v[34:37]
	v_mfma_f32_16x16x32_bf16 v[34:37], v[182:185], v[170:173], v[204:207]
	v_mfma_f32_16x16x32_bf16 v[34:37], v[186:189], v[174:177], v[34:37]
	s_barrier
; #define WAIT_V(n) asm volatile("s_waitcnt vmcnt(" #n ")" ::: "memory")
; #define WAIT_L(n) asm volatile("s_waitcnt lgkmcnt(" #n ")" ::: "memory")
; #define BAR __builtin_amdgcn_s_barrier()
; __device__ __forceinline__ void mainloop_8phase(const u16* __restrict__ A, const u16* __restrict__ Bt, int K,
;                                                 f32x4 (&acc)[2][2][4][2], int wid_s, int ld) {
;     ...
;   { LDB(B0, 1, 0); LDA(At, 1, 0); WAIT_V(2); BAR; WAIT_L(0); MMA(0, 0, At, B0); BAR;
;     LDB(B1, 1, 1); WAIT_V(0); BAR; WAIT_L(0); MMA(0, 1, At, B1); BAR;
;     LDA(At, 1, 1); BAR; WAIT_L(0); MMA(1, 0, At, B0); MMA(1, 1, At, B1); BAR; }
;   if (wr == 0) BAR;
	ds_read_b128 v[144:147], v134
	ds_read_b128 v[196:199], v134 offset:1024
	ds_read_b128 v[200:203], v134 offset:2048
	ds_read_b128 v[204:207], v134 offset:3072
	s_waitcnt vmcnt(0)
	s_barrier
	s_waitcnt lgkmcnt(0)
	v_mfma_f32_16x16x32_bf16 v[54:57], v[10:13], v[144:147], v[94:97]
	v_mfma_f32_16x16x32_bf16 v[10:13], v[10:13], v[200:203], v[90:93]
	v_mfma_f32_16x16x32_bf16 v[62:65], v[18:21], v[204:207], v[10:13]
	v_mfma_f32_16x16x32_bf16 v[10:13], v[26:29], v[144:147], v[86:89]
	v_mfma_f32_16x16x32_bf16 v[118:121], v[38:41], v[196:199], v[10:13]
	v_mfma_f32_16x16x32_bf16 v[10:13], v[26:29], v[200:203], v[82:85]
	v_mfma_f32_16x16x32_bf16 v[126:129], v[18:21], v[196:199], v[54:57]
	v_mfma_f32_16x16x32_bf16 v[54:57], v[38:41], v[204:207], v[10:13]
	v_mfma_f32_16x16x32_bf16 v[10:13], v[46:49], v[144:147], v[78:81]
	v_mfma_f32_16x16x32_bf16 v[110:113], v[178:181], v[196:199], v[10:13]
	v_mfma_f32_16x16x32_bf16 v[10:13], v[46:49], v[200:203], v[74:77]
	v_mfma_f32_16x16x32_bf16 v[46:49], v[178:181], v[204:207], v[10:13]
	v_mfma_f32_16x16x32_bf16 v[10:13], v[182:185], v[144:147], v[70:73]
	v_mfma_f32_16x16x32_bf16 v[102:105], v[186:189], v[196:199], v[10:13]
	v_mfma_f32_16x16x32_bf16 v[10:13], v[182:185], v[200:203], v[66:69]
	v_mfma_f32_16x16x32_bf16 v[38:41], v[186:189], v[204:207], v[10:13]
	s_barrier
	ds_read_b128 v[70:73], v133 offset:49152
	ds_read_b128 v[78:81], v133 offset:50176
	ds_read_b128 v[178:181], v132 offset:49152
	ds_read_b128 v[132:135], v132 offset:50176
	ds_read_b128 v[182:185], v131 offset:49152
	ds_read_b128 v[186:189], v131 offset:50176
	ds_read_b128 v[228:231], v130 offset:49152
	ds_read_b128 v[232:235], v130 offset:50176
	s_barrier
	s_waitcnt lgkmcnt(0)
	v_mfma_f32_16x16x32_bf16 v[10:13], v[70:73], v[2:5], v[192:195]
	v_mfma_f32_16x16x32_bf16 v[90:93], v[78:81], v[166:169], v[10:13]
	v_mfma_f32_16x16x32_bf16 v[10:13], v[70:73], v[170:173], v[208:211]
	v_mfma_f32_16x16x32_bf16 v[26:29], v[78:81], v[174:177], v[10:13]
	v_mfma_f32_16x16x32_bf16 v[10:13], v[178:181], v[2:5], v[212:215]
	v_mfma_f32_16x16x32_bf16 v[82:85], v[132:135], v[166:169], v[10:13]
	v_mfma_f32_16x16x32_bf16 v[10:13], v[178:181], v[170:173], v[216:219]
	v_mfma_f32_16x16x32_bf16 v[18:21], v[132:135], v[174:177], v[10:13]
	v_mfma_f32_16x16x32_bf16 v[10:13], v[182:185], v[2:5], v[220:223]
	v_mfma_f32_16x16x32_bf16 v[2:5], v[228:231], v[2:5], v[136:139]
	v_mfma_f32_16x16x32_bf16 v[74:77], v[186:189], v[166:169], v[10:13]
	v_mfma_f32_16x16x32_bf16 v[10:13], v[182:185], v[170:173], v[224:227]
	v_mfma_f32_16x16x32_bf16 v[66:69], v[232:235], v[166:169], v[2:5]
	v_mfma_f32_16x16x32_bf16 v[2:5], v[228:231], v[170:173], v[150:153]
	v_mfma_f32_16x16x32_bf16 v[10:13], v[186:189], v[174:177], v[10:13]
	v_mfma_f32_16x16x32_bf16 v[2:5], v[232:235], v[174:177], v[2:5]
	v_mfma_f32_16x16x32_bf16 v[30:33], v[70:73], v[144:147], v[30:33]
	v_mfma_f32_16x16x32_bf16 v[94:97], v[78:81], v[196:199], v[30:33]
	v_mfma_f32_16x16x32_bf16 v[30:33], v[70:73], v[200:203], v[140:143]
	v_mfma_f32_16x16x32_bf16 v[22:25], v[178:181], v[144:147], v[22:25]
	v_mfma_f32_16x16x32_bf16 v[14:17], v[182:185], v[144:147], v[14:17]
	v_mfma_f32_16x16x32_bf16 v[6:9], v[228:231], v[144:147], v[6:9]
	v_mfma_f32_16x16x32_bf16 v[30:33], v[78:81], v[204:207], v[30:33]
	v_mfma_f32_16x16x32_bf16 v[86:89], v[132:135], v[196:199], v[22:25]
	v_mfma_f32_16x16x32_bf16 v[22:25], v[178:181], v[200:203], v[154:157]
	v_mfma_f32_16x16x32_bf16 v[78:81], v[186:189], v[196:199], v[14:17]
	v_mfma_f32_16x16x32_bf16 v[14:17], v[182:185], v[200:203], v[158:161]
	v_mfma_f32_16x16x32_bf16 v[70:73], v[232:235], v[196:199], v[6:9]
	v_mfma_f32_16x16x32_bf16 v[6:9], v[228:231], v[200:203], v[162:165]
	v_mfma_f32_16x16x32_bf16 v[22:25], v[132:135], v[204:207], v[22:25]
	v_mfma_f32_16x16x32_bf16 v[14:17], v[186:189], v[204:207], v[14:17]
	v_mfma_f32_16x16x32_bf16 v[6:9], v[232:235], v[204:207], v[6:9]
	s_movk_i32 s2, 0x100
	v_cmp_gt_u32_e32 vcc, s2, v0
	s_barrier
	s_and_saveexec_b64 s[2:3], vcc
	s_cbranch_execz .LBB0_165
	s_barrier

; #define WAIT_V(n) asm volatile("s_waitcnt vmcnt(" #n ")" ::: "memory")
; #define BAR __builtin_amdgcn_s_barrier()
; #define SCHED __builtin_amdgcn_sched_barrier(0)
; __device__ __forceinline__ void mainloop_8phase(const u16* __restrict__ A, const u16* __restrict__ Bt, int K,
;                                                 f32x4 (&acc)[2][2][4][2], int wid_s, int ld) {
;     ...
;   int tid = get_tid(wid_s), wid = tid >> 6, lane = tid & 63, wr = wid >> 2, wc = wid & 3, fr = lane & 15, fq = lane >> 4;
;   unsigned goff0, goff1;
;   {
;     int r0, c0, r1, c1;
;     stage_rc(tid * 16, r0, c0);
;     stage_rc(tid * 16 + 8192, r1, c1);
;     goff0 = (unsigned)(r0 * ld + c0) * 2u;
;     goff1 = (unsigned)(r1 * ld + c1) * 2u;
;   }
;   __amdgpu_buffer_rsrc_t rs_A, rs_Bt;
;   {
;     unsigned long ua = (unsigned long)A, ub = (unsigned long)Bt;
;     unsigned alo = __builtin_amdgcn_readfirstlane((unsigned)ua), ahi = __builtin_amdgcn_readfirstlane((unsigned)(ua >> 32));
;     unsigned blo = __builtin_amdgcn_readfirstlane((unsigned)ub), bhi = __builtin_amdgcn_readfirstlane((unsigned)(ub >> 32));
;     rs_A = __builtin_amdgcn_make_buffer_rsrc((void*)(((unsigned long)ahi << 32) | alo), (short)0, 0x7ffffff0, 0x00020000);
;     rs_Bt = __builtin_amdgcn_make_buffer_rsrc((void*)(((unsigned long)bhi << 32) | blo), (short)0, 0x7ffffff0, 0x00020000);
;   }
;   bf16x8 At[4][2], B0[2][2], B1[2][2];
;   const int brow = 0, bcol = 0;
;   int nt = K / G_BK;
;   if (wr == 1) BAR;
;   WAIT_V(0); BAR;
;   STAGE(SB(1, 0), Bt, bcol, 1); STAGE(SA(1, 0), A, brow, 1); STAGE(SB(1, 1), Bt, bcol + G_HALF, 1);
;   WAIT_V(6); BAR;
;   for (int t = 0; t < nt - 2; t += 2) {
;     LDB(B0, 0, 0); SCHED; LDA(At, 0, 0); STAGE(SA(1, 1), A, brow + G_HALF, t + 1);
.LBB0_246:
	s_or_b64 exec, exec, s[0:1]
	v_bfe_i32 v8, v0, 27, 1
	v_lshlrev_b32_e32 v6, 4, v0
	v_lshrrev_b32_e32 v8, 22, v8
	v_add_u32_e32 v8, v6, v8
	v_and_b32_e32 v8, 0xfffffc00, v8
	v_sub_u32_e32 v8, v6, v8
	v_lshrrev_b32_e32 v9, 4, v8
	v_ashrrev_i32_e32 v7, 31, v0
	v_bitop3_b32 v8, v9, v8, 32 bitop3:0x6c
	v_lshrrev_b32_e32 v7, 26, v7
	v_ashrrev_i32_e32 v10, 31, v8
	v_add_u32_e32 v7, v0, v7
	v_lshrrev_b32_e32 v10, 26, v10
	v_ashrrev_i32_e32 v7, 6, v7
	v_add_u32_e32 v10, v8, v10
	v_lshlrev_b32_e32 v9, 3, v7
	v_lshrrev_b32_e32 v11, 6, v10
	v_and_b32_e32 v10, 0xc0, v10
	v_and_b32_e32 v9, 0xffff0, v9
	v_sub_u32_e32 v8, v8, v10
	v_add_u32_e32 v10, 0x2000, v6
	v_add_u32_e32 v9, v11, v9
	v_ashrrev_i32_e32 v11, 31, v10
	v_lshrrev_b32_e32 v11, 22, v11
	v_add_u32_e32 v11, v10, v11
	v_ashrrev_i32_e32 v11, 10, v11
	v_mul_i32_i24_e32 v12, 0x400, v11
	v_sub_u32_e32 v10, v10, v12
	v_lshrrev_b32_e32 v12, 4, v10
	v_bitop3_b32 v10, v12, v10, 32 bitop3:0x6c
	v_ashrrev_i32_e32 v13, 31, v10
	v_lshrrev_b32_e32 v13, 26, v13
	v_add_u32_e32 v13, v10, v13
	v_lshlrev_b32_e32 v7, 5, v7
	v_lshlrev_b32_e32 v12, 3, v11
	v_lshrrev_b32_e32 v14, 6, v13
	v_and_b32_e32 v13, 0xc0, v13
	v_readlane_b32 s3, v254, 43
	v_and_b32_e32 v7, 32, v7
	v_ashrrev_i16_sdwa v8, v244, sext(v8) dst_sel:DWORD dst_unused:UNUSED_PAD src0_sel:DWORD src1_sel:BYTE_0
	v_and_b32_e32 v12, 0xffff0, v12
	v_lshlrev_b32_e32 v11, 5, v11
	v_sub_u32_e32 v10, v10, v13
	s_waitcnt vmcnt(7)
	v_add_u32_e32 v138, s3, v6
	v_bfe_i32 v8, v8, 0, 16
	v_add_u32_e32 v12, v14, v12
	v_and_b32_e32 v11, 32, v11
	v_ashrrev_i16_sdwa v10, v244, sext(v10) dst_sel:DWORD dst_unused:UNUSED_PAD src0_sel:DWORD src1_sel:BYTE_0
	v_lshl_or_b32 v7, v9, 11, v7
	s_and_b32 s5, s13, 0xffff
	v_readfirstlane_b32 s0, v138
	v_add_u32_e32 v139, 0x2000, v138
	v_add_u32_e32 v140, 16, v6
	v_bfe_i32 v10, v10, 0, 16
	v_add_lshl_u32 v137, v7, v8, 1
	v_lshl_or_b32 v7, v12, 11, v11
	s_mov_b32 s24, s12
	s_mov_b32 s25, s5
	s_mov_b32 s26, s90
	s_mov_b32 s27, s91
	s_mov_b32 m0, s0
	s_movk_i32 s1, 0x80
	v_readfirstlane_b32 s0, v139
	v_add_u32_e32 v141, 0x8000, v140
	v_add_lshl_u32 v136, v7, v10, 1
	s_and_b32 s89, s11, 0xffff
	s_waitcnt vmcnt(0)
	s_barrier
	buffer_load_dwordx4 v137, s[24:27], s1 offen lds
	s_mov_b32 m0, s0
	v_readfirstlane_b32 s0, v141
	v_add_u32_e32 v142, 0xa000, v140
	v_readlane_b32 s6, v254, 44
	s_mov_b32 s20, s10
	s_mov_b32 s21, s89
	s_mov_b32 s22, s90
	s_mov_b32 s23, s91
	buffer_load_dwordx4 v136, s[24:27], s1 offen lds
	s_mov_b32 m0, s0
	v_readfirstlane_b32 s0, v142
	v_add_u32_e32 v143, s6, v6
	buffer_load_dwordx4 v137, s[20:23], s1 offen lds
	s_mov_b32 m0, s0
	v_readfirstlane_b32 s0, v143
	v_add_u32_e32 v146, 0x2000, v143
	buffer_load_dwordx4 v136, s[20:23], s1 offen lds
	s_mov_b32 m0, s0
	s_mov_b32 s1, 0x80080
	v_readfirstlane_b32 s0, v146
	buffer_load_dwordx4 v137, s[24:27], s1 offen lds
	s_mov_b32 m0, s0
	v_and_b32_e32 v4, 15, v2
	buffer_load_dwordx4 v136, s[24:27], s1 offen lds
	v_lshlrev_b32_e32 v7, 2, v2
	v_and_b32_e32 v5, 48, v2
	v_lshlrev_b32_e32 v4, 6, v4
	v_and_b32_e32 v7, 32, v7
	v_bitop3_b32 v4, v4, v7, v5 bitop3:0x36
	v_readlane_b32 s0, v254, 41
	v_lshlrev_b32_e32 v2, 6, v2
	s_waitcnt vmcnt(6)
	v_readlane_b32 s1, v254, 42
	v_add_u32_e32 v8, s0, v4
	v_add_u32_e32 v148, s0, v6
	s_movk_i32 s0, 0x3c0
	v_lshlrev_b32_e32 v11, 6, v0
	v_lshlrev_b32_e32 v3, 13, v3
	v_and_or_b32 v2, v2, s0, v5
	v_add_u32_e32 v9, s1, v4
	v_add_u32_e32 v151, s1, v6
	v_add_u32_e32 v6, s3, v4
	v_add_u32_e32 v10, s6, v4
	v_and_b32_e32 v11, 0x3000, v11
	v_add_u32_e32 v4, 16, v4
	v_xad_u32 v5, v2, v7, 16
	v_or_b32_e32 v7, 0x800, v3
	v_or_b32_e32 v12, 0x1000, v3
	v_or_b32_e32 v13, 0x1800, v3
	v_mov_b32_e32 v2, 0
	s_mov_b32 s88, s10
	s_mov_b32 s4, s12
	v_add_u32_e32 v145, 0xc000, v140
	v_add_u32_e32 v144, 0xe000, v140
	v_add_u32_e32 v149, 0x2000, v148
	v_add_u32_e32 v150, 0x2000, v140
	v_add_u32_e32 v152, 0x2000, v151
	v_add_u32_e32 v153, 0x4000, v140
	v_add_u32_e32 v154, 0x6000, v140
	s_mov_b32 s0, -2
	s_mov_b32 s1, 0x80180
	v_add_u32_e32 v155, v8, v11
	s_waitcnt lgkmcnt(0)
	v_add_u32_e32 v133, v4, v3
	v_add_u32_e32 v132, v5, v7
	v_add_u32_e32 v131, v5, v12
	v_add_u32_e32 v130, v5, v13
	v_add_u32_e32 v147, v9, v11
	v_add_u32_e32 v135, v6, v11
	v_add_u32_e32 v134, v10, v11
	s_waitcnt vmcnt(9)
	s_waitcnt vmcnt(8)
	s_waitcnt vmcnt(7)
	s_waitcnt vmcnt(6)
	s_barrier
	s_mov_b32 s6, s90
	s_mov_b32 s7, s91
	s_add_i32 s3, s1, 0xffffff00
	s_add_i32 m0, s100, 0xc000
	ds_read_b128 v[156:159], v155
	ds_read_b128 v[160:163], v155 offset:1024
	ds_read_b128 v[164:167], v155 offset:2048
	ds_read_b128 v[168:171], v155 offset:3072
	ds_read_b128 v[172:175], v133
	ds_read_b128 v[176:179], v133 offset:1024
	ds_read_b128 v[180:183], v132
	ds_read_b128 v[184:187], v132 offset:1024
	ds_read_b128 v[188:191], v131
	ds_read_b128 v[192:195], v131 offset:1024
	ds_read_b128 v[196:199], v130
	buffer_load_dwordx4 v137, s[88:91], s3 offen lds
	s_add_i32 m0, s100, 0xe000
	ds_read_b128 v[200:203], v130 offset:1024
	buffer_load_dwordx4 v136, s[88:91], s3 offen lds
	s_waitcnt lgkmcnt(8)
	s_barrier
; #define WAIT_V(n) asm volatile("s_waitcnt vmcnt(" #n ")" ::: "memory")
; #define WAIT_L(n) asm volatile("s_waitcnt lgkmcnt(" #n ")" ::: "memory")
; #define BAR __builtin_amdgcn_s_barrier()
; #define SCHED __builtin_amdgcn_sched_barrier(0)
; __device__ __forceinline__ void mainloop_8phase(const u16* __restrict__ A, const u16* __restrict__ Bt, int K,
;                                                 f32x4 (&acc)[2][2][4][2], int wid_s, int ld) {
;     ...
;     WAIT_L(8); BAR; WAIT_L(0); MMA(0, 0, At, B0); BAR; SCHED;
;     LDB(B1, 0, 1); STAGE(SB(0, 0), Bt, bcol, t + 2);
;     BAR; WAIT_L(0); MMA(0, 1, At, B1); BAR;
;     LDA(At, 0, 1); STAGE(SA(0, 0), A, brow, t + 2);
;     BAR; WAIT_L(0); MMA(1, 0, At, B0); BAR; SCHED;
;     STAGE(SB(0, 1), Bt, bcol + G_HALF, t + 2);
;     WAIT_V(6); BAR; MMA(1, 1, At, B1); BAR;
	s_waitcnt lgkmcnt(1)
	v_mfma_f32_16x16x32_bf16 v[126:129], v[172:175], v[156:159], 0
	s_add_i32 s3, s1, 0xfff7ff80
	s_add_i32 m0, s100, 0x10000
	v_mfma_f32_16x16x32_bf16 v[122:125], v[172:175], v[164:167], 0
	v_mfma_f32_16x16x32_bf16 v[118:121], v[180:183], v[156:159], 0
	v_mfma_f32_16x16x32_bf16 v[114:117], v[180:183], v[164:167], 0
	v_mfma_f32_16x16x32_bf16 v[110:113], v[188:191], v[156:159], 0
	v_mfma_f32_16x16x32_bf16 v[106:109], v[188:191], v[164:167], 0
	v_mfma_f32_16x16x32_bf16 v[102:105], v[196:199], v[156:159], 0
	v_mfma_f32_16x16x32_bf16 v[98:101], v[196:199], v[164:167], 0
	v_mfma_f32_16x16x32_bf16 v[126:129], v[176:179], v[160:163], v[126:129]
	v_mfma_f32_16x16x32_bf16 v[122:125], v[176:179], v[168:171], v[122:125]
	v_mfma_f32_16x16x32_bf16 v[118:121], v[184:187], v[160:163], v[118:121]
	v_mfma_f32_16x16x32_bf16 v[114:117], v[184:187], v[168:171], v[114:117]
	v_mfma_f32_16x16x32_bf16 v[110:113], v[192:195], v[160:163], v[110:113]
	v_mfma_f32_16x16x32_bf16 v[106:109], v[192:195], v[168:171], v[106:109]
	s_waitcnt lgkmcnt(0)
	v_mfma_f32_16x16x32_bf16 v[102:105], v[200:203], v[160:163], v[102:105]
	v_mfma_f32_16x16x32_bf16 v[98:101], v[200:203], v[168:171], v[98:101]
	s_barrier
	ds_read_b128 v[204:207], v147
	ds_read_b128 v[208:211], v147 offset:1024
	ds_read_b128 v[212:215], v147 offset:2048
	buffer_load_dwordx4 v137, s[4:7], s3 offen lds
	s_add_i32 m0, s100, 0x12000
	ds_read_b128 v[216:219], v147 offset:3072
	buffer_load_dwordx4 v136, s[4:7], s3 offen lds
	s_barrier
	s_waitcnt lgkmcnt(1)
	v_mfma_f32_16x16x32_bf16 v[94:97], v[172:175], v[204:207], 0
	v_mfma_f32_16x16x32_bf16 v[90:93], v[172:175], v[212:215], 0
	v_mfma_f32_16x16x32_bf16 v[86:89], v[180:183], v[204:207], 0
	v_mfma_f32_16x16x32_bf16 v[82:85], v[180:183], v[212:215], 0
	v_mfma_f32_16x16x32_bf16 v[78:81], v[188:191], v[204:207], 0
	v_mfma_f32_16x16x32_bf16 v[74:77], v[188:191], v[212:215], 0
	v_mfma_f32_16x16x32_bf16 v[70:73], v[196:199], v[204:207], 0
	v_mfma_f32_16x16x32_bf16 v[66:69], v[196:199], v[212:215], 0
	v_mfma_f32_16x16x32_bf16 v[94:97], v[176:179], v[208:211], v[94:97]
	s_waitcnt lgkmcnt(0)
	v_mfma_f32_16x16x32_bf16 v[90:93], v[176:179], v[216:219], v[90:93]
	v_mfma_f32_16x16x32_bf16 v[86:89], v[184:187], v[208:211], v[86:89]
	v_mfma_f32_16x16x32_bf16 v[82:85], v[184:187], v[216:219], v[82:85]
	v_mfma_f32_16x16x32_bf16 v[78:81], v[192:195], v[208:211], v[78:81]
	v_mfma_f32_16x16x32_bf16 v[74:77], v[192:195], v[216:219], v[74:77]
	v_mfma_f32_16x16x32_bf16 v[70:73], v[200:203], v[208:211], v[70:73]
	v_mfma_f32_16x16x32_bf16 v[66:69], v[200:203], v[216:219], v[66:69]
	s_mov_b32 m0, s100
	s_barrier
	ds_read_b128 v[172:175], v133 offset:16384
	ds_read_b128 v[176:179], v133 offset:17408
	ds_read_b128 v[180:183], v132 offset:16384
	ds_read_b128 v[184:187], v132 offset:17408
	ds_read_b128 v[188:191], v131 offset:16384
	ds_read_b128 v[192:195], v131 offset:17408
	ds_read_b128 v[196:199], v130 offset:16384
	buffer_load_dwordx4 v137, s[88:91], s3 offen lds
	s_add_i32 m0, s100, 0x2000
	ds_read_b128 v[200:203], v130 offset:17408
	buffer_load_dwordx4 v136, s[88:91], s3 offen lds
	s_barrier
	s_waitcnt lgkmcnt(1)
	v_mfma_f32_16x16x32_bf16 v[62:65], v[172:175], v[156:159], 0
	s_add_i32 s3, s1, 0xffffff80
	s_add_i32 m0, s100, 0x14000
	v_mfma_f32_16x16x32_bf16 v[58:61], v[172:175], v[164:167], 0
	v_mfma_f32_16x16x32_bf16 v[54:57], v[180:183], v[156:159], 0
	v_mfma_f32_16x16x32_bf16 v[50:53], v[180:183], v[164:167], 0
	v_mfma_f32_16x16x32_bf16 v[46:49], v[188:191], v[156:159], 0
	v_mfma_f32_16x16x32_bf16 v[42:45], v[188:191], v[164:167], 0
	v_mfma_f32_16x16x32_bf16 v[38:41], v[196:199], v[156:159], 0
	v_mfma_f32_16x16x32_bf16 v[34:37], v[196:199], v[164:167], 0
	v_mfma_f32_16x16x32_bf16 v[62:65], v[176:179], v[160:163], v[62:65]
	v_mfma_f32_16x16x32_bf16 v[58:61], v[176:179], v[168:171], v[58:61]
	v_mfma_f32_16x16x32_bf16 v[54:57], v[184:187], v[160:163], v[54:57]
	v_mfma_f32_16x16x32_bf16 v[50:53], v[184:187], v[168:171], v[50:53]
	v_mfma_f32_16x16x32_bf16 v[46:49], v[192:195], v[160:163], v[46:49]
	v_mfma_f32_16x16x32_bf16 v[42:45], v[192:195], v[168:171], v[42:45]
	s_waitcnt lgkmcnt(0)
	v_mfma_f32_16x16x32_bf16 v[38:41], v[200:203], v[160:163], v[38:41]
	v_mfma_f32_16x16x32_bf16 v[34:37], v[200:203], v[168:171], v[34:37]
	s_barrier
	buffer_load_dwordx4 v137, s[4:7], s3 offen lds
	s_add_i32 m0, s100, 0x16000
	s_nop 0
	buffer_load_dwordx4 v136, s[4:7], s3 offen lds
	s_waitcnt vmcnt(6)
	s_barrier
	v_mfma_f32_16x16x32_bf16 v[30:33], v[172:175], v[204:207], 0
	s_add_i32 m0, s100, 0x4000
	v_mfma_f32_16x16x32_bf16 v[26:29], v[172:175], v[212:215], 0
	v_mfma_f32_16x16x32_bf16 v[22:25], v[180:183], v[204:207], 0
	v_mfma_f32_16x16x32_bf16 v[18:21], v[180:183], v[212:215], 0
	v_mfma_f32_16x16x32_bf16 v[14:17], v[188:191], v[204:207], 0
	v_mfma_f32_16x16x32_bf16 v[10:13], v[188:191], v[212:215], 0
	v_mfma_f32_16x16x32_bf16 v[6:9], v[196:199], v[204:207], 0
	v_mfma_f32_16x16x32_bf16 v[2:5], v[196:199], v[212:215], 0
	v_mfma_f32_16x16x32_bf16 v[30:33], v[176:179], v[208:211], v[30:33]
	v_mfma_f32_16x16x32_bf16 v[26:29], v[176:179], v[216:219], v[26:29]
	v_mfma_f32_16x16x32_bf16 v[22:25], v[184:187], v[208:211], v[22:25]
	v_mfma_f32_16x16x32_bf16 v[18:21], v[184:187], v[216:219], v[18:21]
	v_mfma_f32_16x16x32_bf16 v[14:17], v[192:195], v[208:211], v[14:17]
	v_mfma_f32_16x16x32_bf16 v[10:13], v[192:195], v[216:219], v[10:13]
	v_mfma_f32_16x16x32_bf16 v[6:9], v[200:203], v[208:211], v[6:9]
	v_mfma_f32_16x16x32_bf16 v[2:5], v[200:203], v[216:219], v[2:5]
	s_barrier
; #define WAIT_V(n) asm volatile("s_waitcnt vmcnt(" #n ")" ::: "memory")
; #define WAIT_L(n) asm volatile("s_waitcnt lgkmcnt(" #n ")" ::: "memory")
; #define BAR __builtin_amdgcn_s_barrier()
; #define SCHED __builtin_amdgcn_sched_barrier(0)
; __device__ __forceinline__ void mainloop_8phase(const u16* __restrict__ A, const u16* __restrict__ Bt, int K,
;                                                 f32x4 (&acc)[2][2][4][2], int wid_s, int ld) {
;     ...
;     LDB(B0, 1, 0); SCHED; LDA(At, 1, 0); STAGE(SA(0, 1), A, brow + G_HALF, t + 2);
;     WAIT_L(8); BAR; WAIT_L(0); MMA(0, 0, At, B0); BAR; SCHED;
;     LDB(B1, 1, 1); STAGE(SB(1, 0), Bt, bcol, t + 3);
;     BAR; WAIT_L(0); MMA(0, 1, At, B1); BAR;
;     LDA(At, 1, 1); STAGE(SA(1, 0), A, brow, t + 3);
;     BAR; WAIT_L(0); MMA(1, 0, At, B0); BAR; SCHED;
;     STAGE(SB(1, 1), Bt, bcol + G_HALF, t + 3);
;     WAIT_V(6); BAR; MMA(1, 1, At, B1); BAR;
	ds_read_b128 v[156:159], v135
	ds_read_b128 v[160:163], v135 offset:1024
	ds_read_b128 v[164:167], v135 offset:2048
	ds_read_b128 v[168:171], v135 offset:3072
	ds_read_b128 v[172:175], v133 offset:32768
	ds_read_b128 v[176:179], v133 offset:33792
	ds_read_b128 v[180:183], v132 offset:32768
	ds_read_b128 v[184:187], v132 offset:33792
	ds_read_b128 v[188:191], v131 offset:32768
	ds_read_b128 v[192:195], v131 offset:33792
	ds_read_b128 v[196:199], v130 offset:32768
	buffer_load_dwordx4 v137, s[88:91], s3 offen lds
	s_add_i32 m0, s100, 0x6000
	ds_read_b128 v[200:203], v130 offset:33792
	buffer_load_dwordx4 v136, s[88:91], s3 offen lds
	s_waitcnt lgkmcnt(8)
	s_barrier
	s_waitcnt lgkmcnt(1)
	v_mfma_f32_16x16x32_bf16 v[126:129], v[172:175], v[156:159], v[126:129]
	s_add_i32 s3, s1, 0xfff80000
	s_add_i32 m0, s100, 0x18000
	v_mfma_f32_16x16x32_bf16 v[122:125], v[172:175], v[164:167], v[122:125]
	v_mfma_f32_16x16x32_bf16 v[118:121], v[180:183], v[156:159], v[118:121]
	v_mfma_f32_16x16x32_bf16 v[114:117], v[180:183], v[164:167], v[114:117]
	v_mfma_f32_16x16x32_bf16 v[110:113], v[188:191], v[156:159], v[110:113]
	v_mfma_f32_16x16x32_bf16 v[106:109], v[188:191], v[164:167], v[106:109]
	v_mfma_f32_16x16x32_bf16 v[102:105], v[196:199], v[156:159], v[102:105]
	v_mfma_f32_16x16x32_bf16 v[98:101], v[196:199], v[164:167], v[98:101]
	v_mfma_f32_16x16x32_bf16 v[126:129], v[176:179], v[160:163], v[126:129]
	v_mfma_f32_16x16x32_bf16 v[122:125], v[176:179], v[168:171], v[122:125]
	v_mfma_f32_16x16x32_bf16 v[118:121], v[184:187], v[160:163], v[118:121]
	v_mfma_f32_16x16x32_bf16 v[114:117], v[184:187], v[168:171], v[114:117]
	v_mfma_f32_16x16x32_bf16 v[110:113], v[192:195], v[160:163], v[110:113]
	v_mfma_f32_16x16x32_bf16 v[106:109], v[192:195], v[168:171], v[106:109]
	s_waitcnt lgkmcnt(0)
	v_mfma_f32_16x16x32_bf16 v[102:105], v[200:203], v[160:163], v[102:105]
	v_mfma_f32_16x16x32_bf16 v[98:101], v[200:203], v[168:171], v[98:101]
	s_barrier
	ds_read_b128 v[204:207], v134
	ds_read_b128 v[208:211], v134 offset:1024
	ds_read_b128 v[212:215], v134 offset:2048
	buffer_load_dwordx4 v137, s[4:7], s3 offen lds
	s_add_i32 m0, s100, 0x1a000
	ds_read_b128 v[216:219], v134 offset:3072
	buffer_load_dwordx4 v136, s[4:7], s3 offen lds
	s_barrier
	s_waitcnt lgkmcnt(1)
	v_mfma_f32_16x16x32_bf16 v[94:97], v[172:175], v[204:207], v[94:97]
	v_mfma_f32_16x16x32_bf16 v[90:93], v[172:175], v[212:215], v[90:93]
	v_mfma_f32_16x16x32_bf16 v[86:89], v[180:183], v[204:207], v[86:89]
	v_mfma_f32_16x16x32_bf16 v[82:85], v[180:183], v[212:215], v[82:85]
	v_mfma_f32_16x16x32_bf16 v[78:81], v[188:191], v[204:207], v[78:81]
	v_mfma_f32_16x16x32_bf16 v[74:77], v[188:191], v[212:215], v[74:77]
	v_mfma_f32_16x16x32_bf16 v[70:73], v[196:199], v[204:207], v[70:73]
	v_mfma_f32_16x16x32_bf16 v[66:69], v[196:199], v[212:215], v[66:69]
	v_mfma_f32_16x16x32_bf16 v[94:97], v[176:179], v[208:211], v[94:97]
	s_waitcnt lgkmcnt(0)
	v_mfma_f32_16x16x32_bf16 v[90:93], v[176:179], v[216:219], v[90:93]
	v_mfma_f32_16x16x32_bf16 v[86:89], v[184:187], v[208:211], v[86:89]
	v_mfma_f32_16x16x32_bf16 v[82:85], v[184:187], v[216:219], v[82:85]
	v_mfma_f32_16x16x32_bf16 v[78:81], v[192:195], v[208:211], v[78:81]
	v_mfma_f32_16x16x32_bf16 v[74:77], v[192:195], v[216:219], v[74:77]
	v_mfma_f32_16x16x32_bf16 v[70:73], v[200:203], v[208:211], v[70:73]
	v_mfma_f32_16x16x32_bf16 v[66:69], v[200:203], v[216:219], v[66:69]
	s_add_i32 m0, s100, 0x8000
	s_barrier
	ds_read_b128 v[172:175], v133 offset:49152
	ds_read_b128 v[176:179], v133 offset:50176
	ds_read_b128 v[180:183], v132 offset:49152
	ds_read_b128 v[184:187], v132 offset:50176
	ds_read_b128 v[188:191], v131 offset:49152
	ds_read_b128 v[192:195], v131 offset:50176
	ds_read_b128 v[196:199], v130 offset:49152
	buffer_load_dwordx4 v137, s[88:91], s3 offen lds
	s_add_i32 m0, s100, 0xa000
	ds_read_b128 v[200:203], v130 offset:50176
	buffer_load_dwordx4 v136, s[88:91], s3 offen lds
	s_barrier
	s_waitcnt lgkmcnt(1)
	v_mfma_f32_16x16x32_bf16 v[62:65], v[172:175], v[156:159], v[62:65]
	s_add_i32 m0, s100, 0x1c000
	v_mfma_f32_16x16x32_bf16 v[58:61], v[172:175], v[164:167], v[58:61]
	v_mfma_f32_16x16x32_bf16 v[54:57], v[180:183], v[156:159], v[54:57]
	v_mfma_f32_16x16x32_bf16 v[50:53], v[180:183], v[164:167], v[50:53]
	v_mfma_f32_16x16x32_bf16 v[46:49], v[188:191], v[156:159], v[46:49]
	v_mfma_f32_16x16x32_bf16 v[42:45], v[188:191], v[164:167], v[42:45]
	v_mfma_f32_16x16x32_bf16 v[38:41], v[196:199], v[156:159], v[38:41]
	v_mfma_f32_16x16x32_bf16 v[34:37], v[196:199], v[164:167], v[34:37]
	v_mfma_f32_16x16x32_bf16 v[62:65], v[176:179], v[160:163], v[62:65]
	v_mfma_f32_16x16x32_bf16 v[58:61], v[176:179], v[168:171], v[58:61]
	v_mfma_f32_16x16x32_bf16 v[54:57], v[184:187], v[160:163], v[54:57]
	v_mfma_f32_16x16x32_bf16 v[50:53], v[184:187], v[168:171], v[50:53]
	v_mfma_f32_16x16x32_bf16 v[46:49], v[192:195], v[160:163], v[46:49]
	v_mfma_f32_16x16x32_bf16 v[42:45], v[192:195], v[168:171], v[42:45]
	s_waitcnt lgkmcnt(0)
	v_mfma_f32_16x16x32_bf16 v[38:41], v[200:203], v[160:163], v[38:41]
	v_mfma_f32_16x16x32_bf16 v[34:37], v[200:203], v[168:171], v[34:37]
	s_barrier
	buffer_load_dwordx4 v137, s[4:7], s1 offen lds
	s_add_i32 m0, s100, 0x1e000
	s_nop 0
	buffer_load_dwordx4 v136, s[4:7], s1 offen lds
	s_waitcnt vmcnt(6)
	s_barrier
	v_mfma_f32_16x16x32_bf16 v[30:33], v[172:175], v[204:207], v[30:33]
	v_mfma_f32_16x16x32_bf16 v[26:29], v[172:175], v[212:215], v[26:29]
	v_mfma_f32_16x16x32_bf16 v[22:25], v[180:183], v[204:207], v[22:25]
	v_mfma_f32_16x16x32_bf16 v[18:21], v[180:183], v[212:215], v[18:21]
	v_mfma_f32_16x16x32_bf16 v[14:17], v[188:191], v[204:207], v[14:17]
	v_mfma_f32_16x16x32_bf16 v[10:13], v[188:191], v[212:215], v[10:13]
	v_mfma_f32_16x16x32_bf16 v[6:9], v[196:199], v[204:207], v[6:9]
	v_mfma_f32_16x16x32_bf16 v[2:5], v[196:199], v[212:215], v[2:5]
	v_mfma_f32_16x16x32_bf16 v[30:33], v[176:179], v[208:211], v[30:33]
	v_mfma_f32_16x16x32_bf16 v[26:29], v[176:179], v[216:219], v[26:29]
	v_mfma_f32_16x16x32_bf16 v[22:25], v[184:187], v[208:211], v[22:25]
	v_mfma_f32_16x16x32_bf16 v[18:21], v[184:187], v[216:219], v[18:21]
	v_mfma_f32_16x16x32_bf16 v[14:17], v[192:195], v[208:211], v[14:17]
	v_mfma_f32_16x16x32_bf16 v[10:13], v[192:195], v[216:219], v[10:13]
	v_mfma_f32_16x16x32_bf16 v[6:9], v[200:203], v[208:211], v[6:9]
	v_mfma_f32_16x16x32_bf16 v[2:5], v[200:203], v[216:219], v[2:5]
	s_add_i32 s0, s0, 2
	s_addk_i32 s1, 0x100
	s_add_i32 s3, s1, 0xffffff00
	s_add_i32 m0, s100, 0xc000
	s_cmp_lt_u32 s0, 28
	s_barrier
; #define WAIT_V(n) asm volatile("s_waitcnt vmcnt(" #n ")" ::: "memory")
; #define WAIT_L(n) asm volatile("s_waitcnt lgkmcnt(" #n ")" ::: "memory")
; #define BAR __builtin_amdgcn_s_barrier()
; #define SCHED __builtin_amdgcn_sched_barrier(0)
; __device__ __forceinline__ void mainloop_8phase(const u16* __restrict__ A, const u16* __restrict__ Bt, int K,
;                                                 f32x4 (&acc)[2][2][4][2], int wid_s, int ld) {
;     ...
;   for (int t = 0; t < nt - 2; t += 2) {
;     LDB(B0, 0, 0); SCHED; LDA(At, 0, 0); STAGE(SA(1, 1), A, brow + G_HALF, t + 1);
;     WAIT_L(8); BAR; WAIT_L(0); MMA(0, 0, At, B0); BAR; SCHED;
;     LDB(B1, 0, 1); STAGE(SB(0, 0), Bt, bcol, t + 2);
;     BAR; WAIT_L(0); MMA(0, 1, At, B1); BAR;
;     LDA(At, 0, 1); STAGE(SA(0, 0), A, brow, t + 2);
;     BAR; WAIT_L(0); MMA(1, 0, At, B0); BAR; SCHED;
;     STAGE(SB(0, 1), Bt, bcol + G_HALF, t + 2);
;     WAIT_V(6); BAR; MMA(1, 1, At, B1); BAR;
.LBB0_247:
	ds_read_b128 v[156:159], v155
	ds_read_b128 v[160:163], v155 offset:1024
	ds_read_b128 v[164:167], v155 offset:2048
	ds_read_b128 v[168:171], v155 offset:3072
	ds_read_b128 v[172:175], v133
	ds_read_b128 v[176:179], v133 offset:1024
	ds_read_b128 v[180:183], v132
	ds_read_b128 v[184:187], v132 offset:1024
	ds_read_b128 v[188:191], v131
	ds_read_b128 v[192:195], v131 offset:1024
	ds_read_b128 v[196:199], v130
	buffer_load_dwordx4 v137, s[88:91], s3 offen lds
	s_add_i32 m0, s100, 0xe000
	ds_read_b128 v[200:203], v130 offset:1024
	buffer_load_dwordx4 v136, s[88:91], s3 offen lds
	s_waitcnt lgkmcnt(8)
	s_barrier
	s_waitcnt lgkmcnt(1)
	v_mfma_f32_16x16x32_bf16 v[126:129], v[172:175], v[156:159], v[126:129]
	s_add_i32 s3, s1, 0xfff7ff80
	s_add_i32 m0, s100, 0x10000
	v_mfma_f32_16x16x32_bf16 v[122:125], v[172:175], v[164:167], v[122:125]
	v_mfma_f32_16x16x32_bf16 v[118:121], v[180:183], v[156:159], v[118:121]
	v_mfma_f32_16x16x32_bf16 v[114:117], v[180:183], v[164:167], v[114:117]
	v_mfma_f32_16x16x32_bf16 v[110:113], v[188:191], v[156:159], v[110:113]
	v_mfma_f32_16x16x32_bf16 v[106:109], v[188:191], v[164:167], v[106:109]
	v_mfma_f32_16x16x32_bf16 v[102:105], v[196:199], v[156:159], v[102:105]
	v_mfma_f32_16x16x32_bf16 v[98:101], v[196:199], v[164:167], v[98:101]
	v_mfma_f32_16x16x32_bf16 v[126:129], v[176:179], v[160:163], v[126:129]
	v_mfma_f32_16x16x32_bf16 v[122:125], v[176:179], v[168:171], v[122:125]
	v_mfma_f32_16x16x32_bf16 v[118:121], v[184:187], v[160:163], v[118:121]
	v_mfma_f32_16x16x32_bf16 v[114:117], v[184:187], v[168:171], v[114:117]
	v_mfma_f32_16x16x32_bf16 v[110:113], v[192:195], v[160:163], v[110:113]
	v_mfma_f32_16x16x32_bf16 v[106:109], v[192:195], v[168:171], v[106:109]
	s_waitcnt lgkmcnt(0)
	v_mfma_f32_16x16x32_bf16 v[102:105], v[200:203], v[160:163], v[102:105]
	v_mfma_f32_16x16x32_bf16 v[98:101], v[200:203], v[168:171], v[98:101]
	s_barrier
	ds_read_b128 v[204:207], v147
	ds_read_b128 v[208:211], v147 offset:1024
	ds_read_b128 v[212:215], v147 offset:2048
	buffer_load_dwordx4 v137, s[4:7], s3 offen lds
	s_add_i32 m0, s100, 0x12000
	ds_read_b128 v[216:219], v147 offset:3072
	buffer_load_dwordx4 v136, s[4:7], s3 offen lds
	s_barrier
	s_waitcnt lgkmcnt(1)
	v_mfma_f32_16x16x32_bf16 v[94:97], v[172:175], v[204:207], v[94:97]
	v_mfma_f32_16x16x32_bf16 v[90:93], v[172:175], v[212:215], v[90:93]
	v_mfma_f32_16x16x32_bf16 v[86:89], v[180:183], v[204:207], v[86:89]
	v_mfma_f32_16x16x32_bf16 v[82:85], v[180:183], v[212:215], v[82:85]
	v_mfma_f32_16x16x32_bf16 v[78:81], v[188:191], v[204:207], v[78:81]
	v_mfma_f32_16x16x32_bf16 v[74:77], v[188:191], v[212:215], v[74:77]
	v_mfma_f32_16x16x32_bf16 v[70:73], v[196:199], v[204:207], v[70:73]
	v_mfma_f32_16x16x32_bf16 v[66:69], v[196:199], v[212:215], v[66:69]
	v_mfma_f32_16x16x32_bf16 v[94:97], v[176:179], v[208:211], v[94:97]
	s_waitcnt lgkmcnt(0)
	v_mfma_f32_16x16x32_bf16 v[90:93], v[176:179], v[216:219], v[90:93]
	v_mfma_f32_16x16x32_bf16 v[86:89], v[184:187], v[208:211], v[86:89]
	v_mfma_f32_16x16x32_bf16 v[82:85], v[184:187], v[216:219], v[82:85]
	v_mfma_f32_16x16x32_bf16 v[78:81], v[192:195], v[208:211], v[78:81]
	v_mfma_f32_16x16x32_bf16 v[74:77], v[192:195], v[216:219], v[74:77]
	v_mfma_f32_16x16x32_bf16 v[70:73], v[200:203], v[208:211], v[70:73]
	v_mfma_f32_16x16x32_bf16 v[66:69], v[200:203], v[216:219], v[66:69]
	s_mov_b32 m0, s100
	s_barrier
	ds_read_b128 v[172:175], v133 offset:16384
	ds_read_b128 v[176:179], v133 offset:17408
	ds_read_b128 v[180:183], v132 offset:16384
	ds_read_b128 v[184:187], v132 offset:17408
	ds_read_b128 v[188:191], v131 offset:16384
	ds_read_b128 v[192:195], v131 offset:17408
	ds_read_b128 v[196:199], v130 offset:16384
	buffer_load_dwordx4 v137, s[88:91], s3 offen lds
	s_add_i32 m0, s100, 0x2000
	ds_read_b128 v[200:203], v130 offset:17408
	buffer_load_dwordx4 v136, s[88:91], s3 offen lds
	s_barrier
	s_waitcnt lgkmcnt(1)
	v_mfma_f32_16x16x32_bf16 v[62:65], v[172:175], v[156:159], v[62:65]
	s_add_i32 s3, s1, 0xffffff80
	s_add_i32 m0, s100, 0x14000
	v_mfma_f32_16x16x32_bf16 v[58:61], v[172:175], v[164:167], v[58:61]
	v_mfma_f32_16x16x32_bf16 v[54:57], v[180:183], v[156:159], v[54:57]
	v_mfma_f32_16x16x32_bf16 v[50:53], v[180:183], v[164:167], v[50:53]
	v_mfma_f32_16x16x32_bf16 v[46:49], v[188:191], v[156:159], v[46:49]
	v_mfma_f32_16x16x32_bf16 v[42:45], v[188:191], v[164:167], v[42:45]
	v_mfma_f32_16x16x32_bf16 v[38:41], v[196:199], v[156:159], v[38:41]
	v_mfma_f32_16x16x32_bf16 v[34:37], v[196:199], v[164:167], v[34:37]
	v_mfma_f32_16x16x32_bf16 v[62:65], v[176:179], v[160:163], v[62:65]
	v_mfma_f32_16x16x32_bf16 v[58:61], v[176:179], v[168:171], v[58:61]
	v_mfma_f32_16x16x32_bf16 v[54:57], v[184:187], v[160:163], v[54:57]
	v_mfma_f32_16x16x32_bf16 v[50:53], v[184:187], v[168:171], v[50:53]
	v_mfma_f32_16x16x32_bf16 v[46:49], v[192:195], v[160:163], v[46:49]
	v_mfma_f32_16x16x32_bf16 v[42:45], v[192:195], v[168:171], v[42:45]
	s_waitcnt lgkmcnt(0)
	v_mfma_f32_16x16x32_bf16 v[38:41], v[200:203], v[160:163], v[38:41]
	v_mfma_f32_16x16x32_bf16 v[34:37], v[200:203], v[168:171], v[34:37]
	s_barrier
	buffer_load_dwordx4 v137, s[4:7], s3 offen lds
	s_add_i32 m0, s100, 0x16000
	s_nop 0
	buffer_load_dwordx4 v136, s[4:7], s3 offen lds
	s_waitcnt vmcnt(6)
	s_barrier
; #define WAIT_V(n) asm volatile("s_waitcnt vmcnt(" #n ")" ::: "memory")
; #define WAIT_L(n) asm volatile("s_waitcnt lgkmcnt(" #n ")" ::: "memory")
; #define BAR __builtin_amdgcn_s_barrier()
; #define SCHED __builtin_amdgcn_sched_barrier(0)
; __device__ __forceinline__ void mainloop_8phase(const u16* __restrict__ A, const u16* __restrict__ Bt, int K,
;                                                 f32x4 (&acc)[2][2][4][2], int wid_s, int ld) {
;     ...
;     WAIT_V(6); BAR; MMA(1, 1, At, B1); BAR;
;     LDB(B0, 1, 0); SCHED; LDA(At, 1, 0); STAGE(SA(0, 1), A, brow + G_HALF, t + 2);
;     WAIT_L(8); BAR; WAIT_L(0); MMA(0, 0, At, B0); BAR; SCHED;
;     LDB(B1, 1, 1); STAGE(SB(1, 0), Bt, bcol, t + 3);
;     BAR; WAIT_L(0); MMA(0, 1, At, B1); BAR;
;     LDA(At, 1, 1); STAGE(SA(1, 0), A, brow, t + 3);
	v_mfma_f32_16x16x32_bf16 v[30:33], v[172:175], v[204:207], v[30:33]
	s_add_i32 m0, s100, 0x4000
	v_mfma_f32_16x16x32_bf16 v[26:29], v[172:175], v[212:215], v[26:29]
	v_mfma_f32_16x16x32_bf16 v[22:25], v[180:183], v[204:207], v[22:25]
	v_mfma_f32_16x16x32_bf16 v[18:21], v[180:183], v[212:215], v[18:21]
	v_mfma_f32_16x16x32_bf16 v[14:17], v[188:191], v[204:207], v[14:17]
	v_mfma_f32_16x16x32_bf16 v[10:13], v[188:191], v[212:215], v[10:13]
	v_mfma_f32_16x16x32_bf16 v[6:9], v[196:199], v[204:207], v[6:9]
	v_mfma_f32_16x16x32_bf16 v[2:5], v[196:199], v[212:215], v[2:5]
	v_mfma_f32_16x16x32_bf16 v[30:33], v[176:179], v[208:211], v[30:33]
	v_mfma_f32_16x16x32_bf16 v[26:29], v[176:179], v[216:219], v[26:29]
	v_mfma_f32_16x16x32_bf16 v[22:25], v[184:187], v[208:211], v[22:25]
	v_mfma_f32_16x16x32_bf16 v[18:21], v[184:187], v[216:219], v[18:21]
	v_mfma_f32_16x16x32_bf16 v[14:17], v[192:195], v[208:211], v[14:17]
	v_mfma_f32_16x16x32_bf16 v[10:13], v[192:195], v[216:219], v[10:13]
	v_mfma_f32_16x16x32_bf16 v[6:9], v[200:203], v[208:211], v[6:9]
	v_mfma_f32_16x16x32_bf16 v[2:5], v[200:203], v[216:219], v[2:5]
	s_barrier
	ds_read_b128 v[156:159], v135
	ds_read_b128 v[160:163], v135 offset:1024
	ds_read_b128 v[164:167], v135 offset:2048
	ds_read_b128 v[168:171], v135 offset:3072
	ds_read_b128 v[172:175], v133 offset:32768
	ds_read_b128 v[176:179], v133 offset:33792
	ds_read_b128 v[180:183], v132 offset:32768
	ds_read_b128 v[184:187], v132 offset:33792
	ds_read_b128 v[188:191], v131 offset:32768
	ds_read_b128 v[192:195], v131 offset:33792
	ds_read_b128 v[196:199], v130 offset:32768
	buffer_load_dwordx4 v137, s[88:91], s3 offen lds
	s_add_i32 m0, s100, 0x6000
	ds_read_b128 v[200:203], v130 offset:33792
	buffer_load_dwordx4 v136, s[88:91], s3 offen lds
	s_waitcnt lgkmcnt(8)
	s_barrier
	s_waitcnt lgkmcnt(1)
	v_mfma_f32_16x16x32_bf16 v[126:129], v[172:175], v[156:159], v[126:129]
	s_add_i32 s3, s1, 0xfff80000
	s_add_i32 m0, s100, 0x18000
	v_mfma_f32_16x16x32_bf16 v[122:125], v[172:175], v[164:167], v[122:125]
	v_mfma_f32_16x16x32_bf16 v[118:121], v[180:183], v[156:159], v[118:121]
	v_mfma_f32_16x16x32_bf16 v[114:117], v[180:183], v[164:167], v[114:117]
	v_mfma_f32_16x16x32_bf16 v[110:113], v[188:191], v[156:159], v[110:113]
	v_mfma_f32_16x16x32_bf16 v[106:109], v[188:191], v[164:167], v[106:109]
	v_mfma_f32_16x16x32_bf16 v[102:105], v[196:199], v[156:159], v[102:105]
	v_mfma_f32_16x16x32_bf16 v[98:101], v[196:199], v[164:167], v[98:101]
	v_mfma_f32_16x16x32_bf16 v[126:129], v[176:179], v[160:163], v[126:129]
	v_mfma_f32_16x16x32_bf16 v[122:125], v[176:179], v[168:171], v[122:125]
	v_mfma_f32_16x16x32_bf16 v[118:121], v[184:187], v[160:163], v[118:121]
	v_mfma_f32_16x16x32_bf16 v[114:117], v[184:187], v[168:171], v[114:117]
	v_mfma_f32_16x16x32_bf16 v[110:113], v[192:195], v[160:163], v[110:113]
	v_mfma_f32_16x16x32_bf16 v[106:109], v[192:195], v[168:171], v[106:109]
	s_waitcnt lgkmcnt(0)
	v_mfma_f32_16x16x32_bf16 v[102:105], v[200:203], v[160:163], v[102:105]
	v_mfma_f32_16x16x32_bf16 v[98:101], v[200:203], v[168:171], v[98:101]
	s_barrier
	ds_read_b128 v[204:207], v134
	ds_read_b128 v[208:211], v134 offset:1024
	ds_read_b128 v[212:215], v134 offset:2048
	buffer_load_dwordx4 v137, s[4:7], s3 offen lds
	s_add_i32 m0, s100, 0x1a000
	ds_read_b128 v[216:219], v134 offset:3072
	buffer_load_dwordx4 v136, s[4:7], s3 offen lds
	s_barrier
	s_waitcnt lgkmcnt(1)
	v_mfma_f32_16x16x32_bf16 v[94:97], v[172:175], v[204:207], v[94:97]
	v_mfma_f32_16x16x32_bf16 v[90:93], v[172:175], v[212:215], v[90:93]
	v_mfma_f32_16x16x32_bf16 v[86:89], v[180:183], v[204:207], v[86:89]
	v_mfma_f32_16x16x32_bf16 v[82:85], v[180:183], v[212:215], v[82:85]
	v_mfma_f32_16x16x32_bf16 v[78:81], v[188:191], v[204:207], v[78:81]
	v_mfma_f32_16x16x32_bf16 v[74:77], v[188:191], v[212:215], v[74:77]
	v_mfma_f32_16x16x32_bf16 v[70:73], v[196:199], v[204:207], v[70:73]
	v_mfma_f32_16x16x32_bf16 v[66:69], v[196:199], v[212:215], v[66:69]
	v_mfma_f32_16x16x32_bf16 v[94:97], v[176:179], v[208:211], v[94:97]
	s_waitcnt lgkmcnt(0)
	v_mfma_f32_16x16x32_bf16 v[90:93], v[176:179], v[216:219], v[90:93]
	v_mfma_f32_16x16x32_bf16 v[86:89], v[184:187], v[208:211], v[86:89]
	v_mfma_f32_16x16x32_bf16 v[82:85], v[184:187], v[216:219], v[82:85]
	v_mfma_f32_16x16x32_bf16 v[78:81], v[192:195], v[208:211], v[78:81]
	v_mfma_f32_16x16x32_bf16 v[74:77], v[192:195], v[216:219], v[74:77]
	v_mfma_f32_16x16x32_bf16 v[70:73], v[200:203], v[208:211], v[70:73]
	v_mfma_f32_16x16x32_bf16 v[66:69], v[200:203], v[216:219], v[66:69]
	s_add_i32 m0, s100, 0x8000
	s_barrier
	ds_read_b128 v[172:175], v133 offset:49152
	ds_read_b128 v[176:179], v133 offset:50176
	ds_read_b128 v[180:183], v132 offset:49152
	ds_read_b128 v[184:187], v132 offset:50176
	ds_read_b128 v[188:191], v131 offset:49152
	ds_read_b128 v[192:195], v131 offset:50176
	ds_read_b128 v[196:199], v130 offset:49152
	buffer_load_dwordx4 v137, s[88:91], s3 offen lds
	s_add_i32 m0, s100, 0xa000
	ds_read_b128 v[200:203], v130 offset:50176
	buffer_load_dwordx4 v136, s[88:91], s3 offen lds
	s_barrier
; #define WAIT_V(n) asm volatile("s_waitcnt vmcnt(" #n ")" ::: "memory")
; #define WAIT_L(n) asm volatile("s_waitcnt lgkmcnt(" #n ")" ::: "memory")
; #define BAR __builtin_amdgcn_s_barrier()
; #define SCHED __builtin_amdgcn_sched_barrier(0)
; __device__ __forceinline__ void mainloop_8phase(const u16* __restrict__ A, const u16* __restrict__ Bt, int K,
;                                                 f32x4 (&acc)[2][2][4][2], int wid_s, int ld) {
;     ...
;     BAR; WAIT_L(0); MMA(1, 0, At, B0); BAR; SCHED;
;     STAGE(SB(1, 1), Bt, bcol + G_HALF, t + 3);
;     WAIT_V(6); BAR; MMA(1, 1, At, B1); BAR;
;   }
;   { LDB(B0, 0, 0); LDA(At, 0, 0); STAGE(SA(1, 1), A, brow + G_HALF, nt - 1);
;     BAR; WAIT_L(0); MMA(0, 0, At, B0); BAR;
;     LDB(B1, 0, 1); BAR; WAIT_L(0); MMA(0, 1, At, B1); BAR;
	s_waitcnt lgkmcnt(1)
	v_mfma_f32_16x16x32_bf16 v[62:65], v[172:175], v[156:159], v[62:65]
	s_add_i32 m0, s100, 0x1c000
	v_mfma_f32_16x16x32_bf16 v[58:61], v[172:175], v[164:167], v[58:61]
	v_mfma_f32_16x16x32_bf16 v[54:57], v[180:183], v[156:159], v[54:57]
	v_mfma_f32_16x16x32_bf16 v[50:53], v[180:183], v[164:167], v[50:53]
	v_mfma_f32_16x16x32_bf16 v[46:49], v[188:191], v[156:159], v[46:49]
	v_mfma_f32_16x16x32_bf16 v[42:45], v[188:191], v[164:167], v[42:45]
	v_mfma_f32_16x16x32_bf16 v[38:41], v[196:199], v[156:159], v[38:41]
	v_mfma_f32_16x16x32_bf16 v[34:37], v[196:199], v[164:167], v[34:37]
	v_mfma_f32_16x16x32_bf16 v[62:65], v[176:179], v[160:163], v[62:65]
	v_mfma_f32_16x16x32_bf16 v[58:61], v[176:179], v[168:171], v[58:61]
	v_mfma_f32_16x16x32_bf16 v[54:57], v[184:187], v[160:163], v[54:57]
	v_mfma_f32_16x16x32_bf16 v[50:53], v[184:187], v[168:171], v[50:53]
	v_mfma_f32_16x16x32_bf16 v[46:49], v[192:195], v[160:163], v[46:49]
	v_mfma_f32_16x16x32_bf16 v[42:45], v[192:195], v[168:171], v[42:45]
	s_waitcnt lgkmcnt(0)
	v_mfma_f32_16x16x32_bf16 v[38:41], v[200:203], v[160:163], v[38:41]
	v_mfma_f32_16x16x32_bf16 v[34:37], v[200:203], v[168:171], v[34:37]
	s_barrier
	buffer_load_dwordx4 v137, s[4:7], s1 offen lds
	s_add_i32 m0, s100, 0x1e000
	s_nop 0
	buffer_load_dwordx4 v136, s[4:7], s1 offen lds
	s_waitcnt vmcnt(6)
	s_barrier
	v_mfma_f32_16x16x32_bf16 v[30:33], v[172:175], v[204:207], v[30:33]
	v_mfma_f32_16x16x32_bf16 v[26:29], v[172:175], v[212:215], v[26:29]
	v_mfma_f32_16x16x32_bf16 v[22:25], v[180:183], v[204:207], v[22:25]
	v_mfma_f32_16x16x32_bf16 v[18:21], v[180:183], v[212:215], v[18:21]
	v_mfma_f32_16x16x32_bf16 v[14:17], v[188:191], v[204:207], v[14:17]
	v_mfma_f32_16x16x32_bf16 v[10:13], v[188:191], v[212:215], v[10:13]
	v_mfma_f32_16x16x32_bf16 v[6:9], v[196:199], v[204:207], v[6:9]
	v_mfma_f32_16x16x32_bf16 v[2:5], v[196:199], v[212:215], v[2:5]
	v_mfma_f32_16x16x32_bf16 v[30:33], v[176:179], v[208:211], v[30:33]
	v_mfma_f32_16x16x32_bf16 v[26:29], v[176:179], v[216:219], v[26:29]
	v_mfma_f32_16x16x32_bf16 v[22:25], v[184:187], v[208:211], v[22:25]
	v_mfma_f32_16x16x32_bf16 v[18:21], v[184:187], v[216:219], v[18:21]
	v_mfma_f32_16x16x32_bf16 v[14:17], v[192:195], v[208:211], v[14:17]
	v_mfma_f32_16x16x32_bf16 v[10:13], v[192:195], v[216:219], v[10:13]
	v_mfma_f32_16x16x32_bf16 v[6:9], v[200:203], v[208:211], v[6:9]
	v_mfma_f32_16x16x32_bf16 v[2:5], v[200:203], v[216:219], v[2:5]
	s_add_i32 s0, s0, 2
	s_addk_i32 s1, 0x100
	s_add_i32 s3, s1, 0xffffff00
	s_add_i32 m0, s100, 0xc000
	s_cmp_lt_u32 s0, 28
	s_barrier
	s_cbranch_scc1 .LBB0_247
	v_readfirstlane_b32 s0, v145
	s_mov_b32 m0, s0
	s_mov_b32 s1, 0x80f80
	v_readfirstlane_b32 s0, v144
	ds_read_b128 v[138:141], v155
	ds_read_b128 v[148:151], v155 offset:1024
	ds_read_b128 v[156:159], v155 offset:2048
	ds_read_b128 v[152:155], v155 offset:3072
	ds_read_b128 v[160:163], v133
	ds_read_b128 v[164:167], v133 offset:1024
	ds_read_b128 v[168:171], v132
	ds_read_b128 v[172:175], v132 offset:1024
	ds_read_b128 v[176:179], v131
	ds_read_b128 v[180:183], v131 offset:1024
	ds_read_b128 v[184:187], v130
	ds_read_b128 v[188:191], v130 offset:1024
	buffer_load_dwordx4 v137, s[88:91], s1 offen lds
	s_mov_b32 m0, s0
	s_nop 0
	buffer_load_dwordx4 v136, s[88:91], s1 offen lds
	s_barrier
	s_waitcnt lgkmcnt(0)
	v_mfma_f32_16x16x32_bf16 v[126:129], v[160:163], v[138:141], v[126:129]
	v_mfma_f32_16x16x32_bf16 v[118:121], v[168:171], v[138:141], v[118:121]
	v_mfma_f32_16x16x32_bf16 v[110:113], v[176:179], v[138:141], v[110:113]
	v_mfma_f32_16x16x32_bf16 v[102:105], v[184:187], v[138:141], v[102:105]
	v_mfma_f32_16x16x32_bf16 v[126:129], v[164:167], v[148:151], v[126:129]
	v_mfma_f32_16x16x32_bf16 v[122:125], v[160:163], v[156:159], v[122:125]
	v_mfma_f32_16x16x32_bf16 v[118:121], v[172:175], v[148:151], v[118:121]
	v_mfma_f32_16x16x32_bf16 v[114:117], v[168:171], v[156:159], v[114:117]
	v_mfma_f32_16x16x32_bf16 v[110:113], v[180:183], v[148:151], v[110:113]
	v_mfma_f32_16x16x32_bf16 v[106:109], v[176:179], v[156:159], v[106:109]
	v_mfma_f32_16x16x32_bf16 v[102:105], v[188:191], v[148:151], v[102:105]
	v_mfma_f32_16x16x32_bf16 v[98:101], v[184:187], v[156:159], v[98:101]
	v_mfma_f32_16x16x32_bf16 v[142:145], v[164:167], v[152:155], v[122:125]
	v_mfma_f32_16x16x32_bf16 v[192:195], v[172:175], v[152:155], v[114:117]
	v_mfma_f32_16x16x32_bf16 v[196:199], v[180:183], v[152:155], v[106:109]
	v_mfma_f32_16x16x32_bf16 v[200:203], v[188:191], v[152:155], v[98:101]
	s_barrier
	s_nop 1
	ds_read_b128 v[98:101], v147
	ds_read_b128 v[106:109], v147 offset:1024
	ds_read_b128 v[114:117], v147 offset:2048
	ds_read_b128 v[122:125], v147 offset:3072
	s_barrier
	s_waitcnt lgkmcnt(0)
	v_mfma_f32_16x16x32_bf16 v[94:97], v[160:163], v[98:101], v[94:97]
	v_mfma_f32_16x16x32_bf16 v[90:93], v[160:163], v[114:117], v[90:93]
	v_mfma_f32_16x16x32_bf16 v[86:89], v[168:171], v[98:101], v[86:89]
	v_mfma_f32_16x16x32_bf16 v[82:85], v[168:171], v[114:117], v[82:85]
	v_mfma_f32_16x16x32_bf16 v[78:81], v[176:179], v[98:101], v[78:81]
	v_mfma_f32_16x16x32_bf16 v[74:77], v[176:179], v[114:117], v[74:77]
	v_mfma_f32_16x16x32_bf16 v[70:73], v[184:187], v[98:101], v[70:73]
	v_mfma_f32_16x16x32_bf16 v[66:69], v[184:187], v[114:117], v[66:69]
	v_mfma_f32_16x16x32_bf16 v[94:97], v[164:167], v[106:109], v[94:97]
	v_mfma_f32_16x16x32_bf16 v[90:93], v[164:167], v[122:125], v[90:93]
	v_mfma_f32_16x16x32_bf16 v[86:89], v[172:175], v[106:109], v[86:89]
	v_mfma_f32_16x16x32_bf16 v[82:85], v[172:175], v[122:125], v[82:85]
	v_mfma_f32_16x16x32_bf16 v[78:81], v[180:183], v[106:109], v[78:81]
	v_mfma_f32_16x16x32_bf16 v[74:77], v[180:183], v[122:125], v[74:77]
	v_mfma_f32_16x16x32_bf16 v[70:73], v[188:191], v[106:109], v[70:73]
	v_mfma_f32_16x16x32_bf16 v[66:69], v[188:191], v[122:125], v[66:69]
	s_barrier
; #define WAIT_V(n) asm volatile("s_waitcnt vmcnt(" #n ")" ::: "memory")
; #define WAIT_L(n) asm volatile("s_waitcnt lgkmcnt(" #n ")" ::: "memory")
; #define BAR __builtin_amdgcn_s_barrier()
; __device__ __forceinline__ void mainloop_8phase(const u16* __restrict__ A, const u16* __restrict__ Bt, int K,
;                                                 f32x4 (&acc)[2][2][4][2], int wid_s, int ld) {
;     ...
;     LDA(At, 0, 1); WAIT_V(4); BAR; WAIT_L(0); MMA(1, 0, At, B0); MMA(1, 1, At, B1); BAR; }
;   { LDB(B0, 1, 0); LDA(At, 1, 0); WAIT_V(2); BAR; WAIT_L(0); MMA(0, 0, At, B0); BAR;
	ds_read_b128 v[160:163], v133 offset:16384
	ds_read_b128 v[164:167], v133 offset:17408
	ds_read_b128 v[168:171], v132 offset:16384
	ds_read_b128 v[172:175], v132 offset:17408
	ds_read_b128 v[176:179], v131 offset:16384
	ds_read_b128 v[180:183], v131 offset:17408
	ds_read_b128 v[184:187], v130 offset:16384
	ds_read_b128 v[188:191], v130 offset:17408
	s_waitcnt vmcnt(4)
	s_barrier
	s_waitcnt lgkmcnt(0)
	v_mfma_f32_16x16x32_bf16 v[62:65], v[160:163], v[138:141], v[62:65]
	v_mfma_f32_16x16x32_bf16 v[58:61], v[160:163], v[156:159], v[58:61]
	v_mfma_f32_16x16x32_bf16 v[54:57], v[168:171], v[138:141], v[54:57]
	v_mfma_f32_16x16x32_bf16 v[50:53], v[168:171], v[156:159], v[50:53]
	v_mfma_f32_16x16x32_bf16 v[46:49], v[176:179], v[138:141], v[46:49]
	v_mfma_f32_16x16x32_bf16 v[42:45], v[176:179], v[156:159], v[42:45]
	v_mfma_f32_16x16x32_bf16 v[38:41], v[184:187], v[138:141], v[38:41]
	v_mfma_f32_16x16x32_bf16 v[34:37], v[184:187], v[156:159], v[34:37]
	v_mfma_f32_16x16x32_bf16 v[204:207], v[164:167], v[148:151], v[62:65]
	v_mfma_f32_16x16x32_bf16 v[208:211], v[164:167], v[152:155], v[58:61]
	v_mfma_f32_16x16x32_bf16 v[212:215], v[172:175], v[148:151], v[54:57]
	v_mfma_f32_16x16x32_bf16 v[216:219], v[172:175], v[152:155], v[50:53]
	v_mfma_f32_16x16x32_bf16 v[220:223], v[180:183], v[148:151], v[46:49]
	v_mfma_f32_16x16x32_bf16 v[224:227], v[180:183], v[152:155], v[42:45]
	v_mfma_f32_16x16x32_bf16 v[136:139], v[188:191], v[148:151], v[38:41]
	v_mfma_f32_16x16x32_bf16 v[146:149], v[188:191], v[152:155], v[34:37]
	v_mfma_f32_16x16x32_bf16 v[30:33], v[160:163], v[98:101], v[30:33]
	v_mfma_f32_16x16x32_bf16 v[22:25], v[168:171], v[98:101], v[22:25]
	v_mfma_f32_16x16x32_bf16 v[14:17], v[176:179], v[98:101], v[14:17]
	v_mfma_f32_16x16x32_bf16 v[6:9], v[184:187], v[98:101], v[6:9]
	v_mfma_f32_16x16x32_bf16 v[30:33], v[164:167], v[106:109], v[30:33]
	v_mfma_f32_16x16x32_bf16 v[26:29], v[160:163], v[114:117], v[26:29]
	v_mfma_f32_16x16x32_bf16 v[22:25], v[172:175], v[106:109], v[22:25]
	v_mfma_f32_16x16x32_bf16 v[18:21], v[168:171], v[114:117], v[18:21]
	v_mfma_f32_16x16x32_bf16 v[14:17], v[180:183], v[106:109], v[14:17]
	v_mfma_f32_16x16x32_bf16 v[10:13], v[176:179], v[114:117], v[10:13]
	v_mfma_f32_16x16x32_bf16 v[6:9], v[188:191], v[106:109], v[6:9]
	v_mfma_f32_16x16x32_bf16 v[2:5], v[184:187], v[114:117], v[2:5]
	v_mfma_f32_16x16x32_bf16 v[150:153], v[164:167], v[122:125], v[26:29]
	v_mfma_f32_16x16x32_bf16 v[154:157], v[172:175], v[122:125], v[18:21]
	v_mfma_f32_16x16x32_bf16 v[158:161], v[180:183], v[122:125], v[10:13]
	v_mfma_f32_16x16x32_bf16 v[162:165], v[188:191], v[122:125], v[2:5]
	s_barrier
	s_nop 1
	ds_read_b128 v[2:5], v135
	ds_read_b128 v[10:13], v135 offset:1024
	ds_read_b128 v[18:21], v135 offset:2048
	ds_read_b128 v[26:29], v135 offset:3072
	ds_read_b128 v[34:37], v133 offset:32768
	ds_read_b128 v[38:41], v133 offset:33792
	ds_read_b128 v[42:45], v132 offset:32768
	ds_read_b128 v[46:49], v132 offset:33792
	ds_read_b128 v[166:169], v131 offset:32768
	ds_read_b128 v[170:173], v131 offset:33792
	ds_read_b128 v[174:177], v130 offset:32768
	ds_read_b128 v[178:181], v130 offset:33792
	s_waitcnt vmcnt(2)
	s_barrier
	s_waitcnt lgkmcnt(0)
	v_mfma_f32_16x16x32_bf16 v[50:53], v[34:37], v[2:5], v[126:129]
	v_mfma_f32_16x16x32_bf16 v[122:125], v[38:41], v[10:13], v[50:53]
	v_mfma_f32_16x16x32_bf16 v[50:53], v[34:37], v[18:21], v[142:145]
	v_mfma_f32_16x16x32_bf16 v[126:129], v[38:41], v[26:29], v[50:53]
	v_mfma_f32_16x16x32_bf16 v[50:53], v[42:45], v[2:5], v[118:121]
	v_mfma_f32_16x16x32_bf16 v[114:117], v[46:49], v[10:13], v[50:53]
	v_mfma_f32_16x16x32_bf16 v[50:53], v[42:45], v[18:21], v[192:195]
	v_mfma_f32_16x16x32_bf16 v[118:121], v[46:49], v[26:29], v[50:53]
	v_mfma_f32_16x16x32_bf16 v[50:53], v[166:169], v[2:5], v[110:113]
	v_mfma_f32_16x16x32_bf16 v[106:109], v[170:173], v[10:13], v[50:53]
	v_mfma_f32_16x16x32_bf16 v[50:53], v[166:169], v[18:21], v[196:199]
	v_mfma_f32_16x16x32_bf16 v[110:113], v[170:173], v[26:29], v[50:53]
	v_mfma_f32_16x16x32_bf16 v[50:53], v[174:177], v[2:5], v[102:105]
	v_mfma_f32_16x16x32_bf16 v[98:101], v[178:181], v[10:13], v[50:53]
	v_mfma_f32_16x16x32_bf16 v[50:53], v[174:177], v[18:21], v[200:203]
	v_mfma_f32_16x16x32_bf16 v[102:105], v[178:181], v[26:29], v[50:53]
	s_barrier
; #define WAIT_V(n) asm volatile("s_waitcnt vmcnt(" #n ")" ::: "memory")
; #define WAIT_L(n) asm volatile("s_waitcnt lgkmcnt(" #n ")" ::: "memory")
; #define BAR __builtin_amdgcn_s_barrier()
; __device__ __forceinline__ void mainloop_8phase(const u16* __restrict__ A, const u16* __restrict__ Bt, int K,
;                                                 f32x4 (&acc)[2][2][4][2], int wid_s, int ld) {
;     ...
;     LDB(B1, 1, 1); WAIT_V(0); BAR; WAIT_L(0); MMA(0, 1, At, B1); BAR;
;     LDA(At, 1, 1); BAR; WAIT_L(0); MMA(1, 0, At, B0); MMA(1, 1, At, B1); BAR; }
;   if (wr == 0) BAR;
	ds_read_b128 v[140:143], v134
	ds_read_b128 v[182:185], v134 offset:1024
	ds_read_b128 v[186:189], v134 offset:2048
	ds_read_b128 v[190:193], v134 offset:3072
	s_waitcnt vmcnt(0)
	s_barrier
	s_waitcnt lgkmcnt(0)
	v_mfma_f32_16x16x32_bf16 v[50:53], v[34:37], v[140:143], v[94:97]
	v_mfma_f32_16x16x32_bf16 v[34:37], v[34:37], v[186:189], v[90:93]
	v_mfma_f32_16x16x32_bf16 v[62:65], v[38:41], v[190:193], v[34:37]
	v_mfma_f32_16x16x32_bf16 v[34:37], v[42:45], v[140:143], v[86:89]
	v_mfma_f32_16x16x32_bf16 v[58:61], v[38:41], v[182:185], v[50:53]
	v_mfma_f32_16x16x32_bf16 v[50:53], v[46:49], v[182:185], v[34:37]
	v_mfma_f32_16x16x32_bf16 v[34:37], v[42:45], v[186:189], v[82:85]
	v_mfma_f32_16x16x32_bf16 v[54:57], v[46:49], v[190:193], v[34:37]
	v_mfma_f32_16x16x32_bf16 v[34:37], v[166:169], v[140:143], v[78:81]
	v_mfma_f32_16x16x32_bf16 v[42:45], v[170:173], v[182:185], v[34:37]
	v_mfma_f32_16x16x32_bf16 v[34:37], v[166:169], v[186:189], v[74:77]
	v_mfma_f32_16x16x32_bf16 v[46:49], v[170:173], v[190:193], v[34:37]
	v_mfma_f32_16x16x32_bf16 v[34:37], v[174:177], v[140:143], v[70:73]
	v_mfma_f32_16x16x32_bf16 v[38:41], v[174:177], v[186:189], v[66:69]
	v_mfma_f32_16x16x32_bf16 v[34:37], v[178:181], v[182:185], v[34:37]
	v_mfma_f32_16x16x32_bf16 v[38:41], v[178:181], v[190:193], v[38:41]
	s_barrier
	ds_read_b128 v[166:169], v133 offset:49152
	ds_read_b128 v[170:173], v133 offset:50176
	ds_read_b128 v[174:177], v132 offset:49152
	ds_read_b128 v[132:135], v132 offset:50176
	ds_read_b128 v[178:181], v131 offset:49152
	ds_read_b128 v[194:197], v131 offset:50176
	ds_read_b128 v[198:201], v130 offset:49152
	ds_read_b128 v[228:231], v130 offset:50176
	s_barrier
	s_waitcnt lgkmcnt(0)
	v_mfma_f32_16x16x32_bf16 v[66:69], v[166:169], v[2:5], v[204:207]
	v_mfma_f32_16x16x32_bf16 v[90:93], v[170:173], v[10:13], v[66:69]
	v_mfma_f32_16x16x32_bf16 v[66:69], v[166:169], v[18:21], v[208:211]
	v_mfma_f32_16x16x32_bf16 v[94:97], v[170:173], v[26:29], v[66:69]
	v_mfma_f32_16x16x32_bf16 v[66:69], v[174:177], v[2:5], v[212:215]
	v_mfma_f32_16x16x32_bf16 v[82:85], v[132:135], v[10:13], v[66:69]
	v_mfma_f32_16x16x32_bf16 v[66:69], v[174:177], v[18:21], v[216:219]
	v_mfma_f32_16x16x32_bf16 v[86:89], v[132:135], v[26:29], v[66:69]
	v_mfma_f32_16x16x32_bf16 v[66:69], v[178:181], v[2:5], v[220:223]
	v_mfma_f32_16x16x32_bf16 v[74:77], v[194:197], v[10:13], v[66:69]
	v_mfma_f32_16x16x32_bf16 v[66:69], v[178:181], v[18:21], v[224:227]
	v_mfma_f32_16x16x32_bf16 v[2:5], v[198:201], v[2:5], v[136:139]
	v_mfma_f32_16x16x32_bf16 v[78:81], v[194:197], v[26:29], v[66:69]
	v_mfma_f32_16x16x32_bf16 v[66:69], v[228:231], v[10:13], v[2:5]
	v_mfma_f32_16x16x32_bf16 v[2:5], v[198:201], v[18:21], v[146:149]
	v_mfma_f32_16x16x32_bf16 v[70:73], v[228:231], v[26:29], v[2:5]
	v_mfma_f32_16x16x32_bf16 v[2:5], v[166:169], v[140:143], v[30:33]
	v_mfma_f32_16x16x32_bf16 v[26:29], v[170:173], v[182:185], v[2:5]
	v_mfma_f32_16x16x32_bf16 v[2:5], v[166:169], v[186:189], v[150:153]
	v_mfma_f32_16x16x32_bf16 v[30:33], v[170:173], v[190:193], v[2:5]
	v_mfma_f32_16x16x32_bf16 v[2:5], v[174:177], v[140:143], v[22:25]
	v_mfma_f32_16x16x32_bf16 v[18:21], v[132:135], v[182:185], v[2:5]
	v_mfma_f32_16x16x32_bf16 v[2:5], v[174:177], v[186:189], v[154:157]
	v_mfma_f32_16x16x32_bf16 v[22:25], v[132:135], v[190:193], v[2:5]
	v_mfma_f32_16x16x32_bf16 v[2:5], v[178:181], v[140:143], v[14:17]
	v_mfma_f32_16x16x32_bf16 v[10:13], v[194:197], v[182:185], v[2:5]
	v_mfma_f32_16x16x32_bf16 v[2:5], v[178:181], v[186:189], v[158:161]
	v_mfma_f32_16x16x32_bf16 v[14:17], v[194:197], v[190:193], v[2:5]
	v_mfma_f32_16x16x32_bf16 v[2:5], v[198:201], v[140:143], v[6:9]
	v_mfma_f32_16x16x32_bf16 v[6:9], v[198:201], v[186:189], v[162:165]
	v_mfma_f32_16x16x32_bf16 v[2:5], v[228:231], v[182:185], v[2:5]
	v_mfma_f32_16x16x32_bf16 v[6:9], v[228:231], v[190:193], v[6:9]
	s_movk_i32 s0, 0x100
	v_cmp_gt_u32_e32 vcc, s0, v0
	s_barrier
	s_and_saveexec_b64 s[0:1], vcc
	s_cbranch_execz .LBB0_250
	s_barrier

; #define WAIT_V(n) asm volatile("s_waitcnt vmcnt(" #n ")" ::: "memory")
; #define BAR __builtin_amdgcn_s_barrier()
; #define SCHED __builtin_amdgcn_sched_barrier(0)
; __device__ __forceinline__ void mainloop_8phase(const u16* __restrict__ A, const u16* __restrict__ Bt, int K,
;                                                 f32x4 (&acc)[2][2][4][2], int wid_s, int ld) {
;     ...
;   int tid = get_tid(wid_s), wid = tid >> 6, lane = tid & 63, wr = wid >> 2, wc = wid & 3, fr = lane & 15, fq = lane >> 4;
;   unsigned goff0, goff1;
;   {
;     int r0, c0, r1, c1;
;     stage_rc(tid * 16, r0, c0);
;     stage_rc(tid * 16 + 8192, r1, c1);
;     goff0 = (unsigned)(r0 * ld + c0) * 2u;
;     goff1 = (unsigned)(r1 * ld + c1) * 2u;
;   }
;   __amdgpu_buffer_rsrc_t rs_A, rs_Bt;
;   {
;     unsigned long ua = (unsigned long)A, ub = (unsigned long)Bt;
;     unsigned alo = __builtin_amdgcn_readfirstlane((unsigned)ua), ahi = __builtin_amdgcn_readfirstlane((unsigned)(ua >> 32));
;     unsigned blo = __builtin_amdgcn_readfirstlane((unsigned)ub), bhi = __builtin_amdgcn_readfirstlane((unsigned)(ub >> 32));
;     rs_A = __builtin_amdgcn_make_buffer_rsrc((void*)(((unsigned long)ahi << 32) | alo), (short)0, 0x7ffffff0, 0x00020000);
;     rs_Bt = __builtin_amdgcn_make_buffer_rsrc((void*)(((unsigned long)bhi << 32) | blo), (short)0, 0x7ffffff0, 0x00020000);
;   }
;   bf16x8 At[4][2], B0[2][2], B1[2][2];
;   const int brow = 0, bcol = 0;
;   int nt = K / G_BK;
;   if (wr == 1) BAR;
;   WAIT_V(0); BAR;
;   STAGE(SB(1, 0), Bt, bcol, 1); STAGE(SA(1, 0), A, brow, 1); STAGE(SB(1, 1), Bt, bcol + G_HALF, 1);
;   WAIT_V(6); BAR;
;   for (int t = 0; t < nt - 2; t += 2) {
;     LDB(B0, 0, 0); SCHED; LDA(At, 0, 0); STAGE(SA(1, 1), A, brow + G_HALF, t + 1);
;     ...
;     f32x4 acc[2][2][4][2];
; #pragma unroll
;     for (int a = 0; a < 2; ++a)
; #pragma unroll
;       for (int b = 0; b < 2; ++b)
; #pragma unroll
;         for (int c = 0; c < 4; ++c)
; #pragma unroll
;           for (int d = 0; d < 2; ++d) acc[a][b][c][d] = f32x4{0.f, 0.f, 0.f, 0.f};
.LBB0_341:
	s_or_b64 exec, exec, s[2:3]
	v_bfe_i32 v8, v0, 27, 1
	v_lshlrev_b32_e32 v6, 4, v0
	v_lshrrev_b32_e32 v8, 22, v8
	v_add_u32_e32 v8, v6, v8
	v_and_b32_e32 v8, 0xfffffc00, v8
	v_sub_u32_e32 v8, v6, v8
	v_lshrrev_b32_e32 v9, 4, v8
	v_ashrrev_i32_e32 v7, 31, v0
	v_bitop3_b32 v8, v9, v8, 32 bitop3:0x6c
	v_lshrrev_b32_e32 v7, 26, v7
	v_ashrrev_i32_e32 v10, 31, v8
	v_add_u32_e32 v7, v0, v7
	v_lshrrev_b32_e32 v10, 26, v10
	v_ashrrev_i32_e32 v7, 6, v7
	v_add_u32_e32 v10, v8, v10
	v_lshlrev_b32_e32 v9, 3, v7
	v_lshrrev_b32_e32 v11, 6, v10
	v_and_b32_e32 v10, 0xc0, v10
	v_and_b32_e32 v9, 0xffff0, v9
	v_sub_u32_e32 v8, v8, v10
	v_add_u32_e32 v10, 0x2000, v6
	v_add_u32_e32 v9, v11, v9
	v_ashrrev_i32_e32 v11, 31, v10
	v_lshrrev_b32_e32 v11, 22, v11
	v_add_u32_e32 v11, v10, v11
	v_ashrrev_i32_e32 v11, 10, v11
	v_mul_i32_i24_e32 v12, 0x400, v11
	v_sub_u32_e32 v10, v10, v12
	v_lshrrev_b32_e32 v12, 4, v10
	v_bitop3_b32 v10, v12, v10, 32 bitop3:0x6c
	v_readlane_b32 s2, v254, 62
	v_ashrrev_i32_e32 v13, 31, v10
	v_readlane_b32 s3, v254, 63
	v_lshrrev_b32_e32 v13, 26, v13
	s_and_b32 s89, s3, 0xffff
	s_mov_b32 s88, s2
	s_mov_b32 s12, s2
	v_readlane_b32 s2, v255, 0
	v_add_u32_e32 v13, v10, v13
	v_readlane_b32 s3, v255, 1
	v_lshlrev_b32_e32 v7, 5, v7
	v_lshlrev_b32_e32 v12, 3, v11
	v_lshrrev_b32_e32 v14, 6, v13
	v_and_b32_e32 v13, 0xc0, v13
	s_and_b32 s5, s3, 0xffff
	v_readlane_b32 s3, v254, 43
	v_and_b32_e32 v7, 32, v7
	v_ashrrev_i16_sdwa v8, v244, sext(v8) dst_sel:DWORD dst_unused:UNUSED_PAD src0_sel:DWORD src1_sel:BYTE_0
	v_and_b32_e32 v12, 0xffff0, v12
	v_lshlrev_b32_e32 v11, 5, v11
	v_sub_u32_e32 v10, v10, v13
	s_waitcnt vmcnt(7)
	v_add_u32_e32 v138, s3, v6
	v_bfe_i32 v8, v8, 0, 16
	v_add_u32_e32 v12, v14, v12
	v_and_b32_e32 v11, 32, v11
	v_ashrrev_i16_sdwa v10, v244, sext(v10) dst_sel:DWORD dst_unused:UNUSED_PAD src0_sel:DWORD src1_sel:BYTE_0
	v_lshl_or_b32 v7, v9, 11, v7
	v_readfirstlane_b32 s1, v138
	v_add_u32_e32 v139, 0x2000, v138
	v_add_u32_e32 v140, 16, v6
	v_bfe_i32 v10, v10, 0, 16
	v_add_lshl_u32 v136, v7, v8, 1
	v_lshl_or_b32 v7, v12, 11, v11
	s_mov_b32 s4, s2
	s_mov_b32 s16, s2
	s_mov_b32 s17, s5
	s_mov_b32 s18, s90
	s_mov_b32 s19, s91
	s_mov_b32 m0, s1
	s_movk_i32 s2, 0x80
	v_readfirstlane_b32 s1, v139
	v_add_u32_e32 v141, 0x8000, v140
	v_add_lshl_u32 v135, v7, v10, 1
	s_waitcnt vmcnt(0)
	s_barrier
	buffer_load_dwordx4 v136, s[16:19], s2 offen lds
	s_mov_b32 m0, s1
	v_readfirstlane_b32 s1, v141
	v_add_u32_e32 v142, 0xa000, v140
	v_readlane_b32 s6, v254, 44
	s_mov_b32 s13, s89
	s_mov_b32 s14, s90
	s_mov_b32 s15, s91
	buffer_load_dwordx4 v135, s[16:19], s2 offen lds
	s_mov_b32 m0, s1
	v_readfirstlane_b32 s1, v142
	v_add_u32_e32 v143, s6, v6
	buffer_load_dwordx4 v136, s[12:15], s2 offen lds
	s_mov_b32 m0, s1
	v_readfirstlane_b32 s1, v143
	v_add_u32_e32 v146, 0x2000, v143
	buffer_load_dwordx4 v135, s[12:15], s2 offen lds
	s_mov_b32 m0, s1
	s_mov_b32 s2, 0x80080
	v_readfirstlane_b32 s1, v146
	buffer_load_dwordx4 v136, s[16:19], s2 offen lds
	s_mov_b32 m0, s1
	v_and_b32_e32 v4, 15, v2
	buffer_load_dwordx4 v135, s[16:19], s2 offen lds
	v_lshlrev_b32_e32 v7, 2, v2
	v_and_b32_e32 v5, 48, v2
	v_lshlrev_b32_e32 v4, 6, v4
	v_and_b32_e32 v7, 32, v7
	v_bitop3_b32 v4, v4, v7, v5 bitop3:0x36
	v_readlane_b32 s1, v254, 41
	v_lshlrev_b32_e32 v2, 6, v2
	s_waitcnt vmcnt(6)
	v_readlane_b32 s2, v254, 42
	v_add_u32_e32 v8, s1, v4
	v_add_u32_e32 v148, s1, v6
	s_movk_i32 s1, 0x3c0
	v_lshlrev_b32_e32 v11, 6, v0
	v_lshlrev_b32_e32 v3, 13, v3
	v_and_or_b32 v2, v2, s1, v5
	v_add_u32_e32 v9, s2, v4
	v_add_u32_e32 v151, s2, v6
	v_add_u32_e32 v6, s3, v4
	v_add_u32_e32 v10, s6, v4
	v_and_b32_e32 v11, 0x3000, v11
	v_add_u32_e32 v4, 16, v4
	v_xad_u32 v5, v2, v7, 16
	v_or_b32_e32 v7, 0x800, v3
	v_or_b32_e32 v12, 0x1000, v3
	v_or_b32_e32 v13, 0x1800, v3
	v_mov_b32_e32 v2, 0
	v_add_u32_e32 v145, 0xc000, v140
	v_add_u32_e32 v144, 0xe000, v140
	v_add_u32_e32 v149, 0x2000, v148
	v_add_u32_e32 v150, 0x2000, v140
	v_add_u32_e32 v152, 0x2000, v151
	v_add_u32_e32 v153, 0x4000, v140
	v_add_u32_e32 v154, 0x6000, v140
	s_mov_b32 s1, -2
	s_mov_b32 s2, 0x80180
	v_add_u32_e32 v155, v8, v11
	s_waitcnt lgkmcnt(0)
	v_add_u32_e32 v133, v4, v3
	v_add_u32_e32 v132, v5, v7
	v_add_u32_e32 v131, v5, v12
	v_add_u32_e32 v130, v5, v13
	v_add_u32_e32 v147, v9, v11
	v_add_u32_e32 v137, v6, v11
	v_add_u32_e32 v134, v10, v11
	s_waitcnt vmcnt(9)
	s_waitcnt vmcnt(8)
	s_waitcnt vmcnt(7)
	s_waitcnt vmcnt(6)
	s_barrier
	s_mov_b32 s6, s90
	s_mov_b32 s7, s91
	s_add_i32 s3, s2, 0xffffff00
	s_add_i32 m0, s100, 0xc000
	ds_read_b128 v[156:159], v155
	ds_read_b128 v[160:163], v155 offset:1024
	ds_read_b128 v[164:167], v155 offset:2048
	ds_read_b128 v[168:171], v155 offset:3072
	ds_read_b128 v[172:175], v133
	ds_read_b128 v[176:179], v133 offset:1024
	ds_read_b128 v[180:183], v132
	ds_read_b128 v[184:187], v132 offset:1024
	ds_read_b128 v[188:191], v131
	ds_read_b128 v[192:195], v131 offset:1024
	ds_read_b128 v[196:199], v130
	buffer_load_dwordx4 v136, s[88:91], s3 offen lds
	s_add_i32 m0, s100, 0xe000
	ds_read_b128 v[200:203], v130 offset:1024
	buffer_load_dwordx4 v135, s[88:91], s3 offen lds
	s_waitcnt lgkmcnt(8)
	s_barrier
; #define WAIT_V(n) asm volatile("s_waitcnt vmcnt(" #n ")" ::: "memory")
; #define WAIT_L(n) asm volatile("s_waitcnt lgkmcnt(" #n ")" ::: "memory")
; #define BAR __builtin_amdgcn_s_barrier()
; #define SCHED __builtin_amdgcn_sched_barrier(0)
; __device__ __forceinline__ void mainloop_8phase(const u16* __restrict__ A, const u16* __restrict__ Bt, int K,
;                                                 f32x4 (&acc)[2][2][4][2], int wid_s, int ld) {
;     ...
;     WAIT_L(8); BAR; WAIT_L(0); MMA(0, 0, At, B0); BAR; SCHED;
;     LDB(B1, 0, 1); STAGE(SB(0, 0), Bt, bcol, t + 2);
;     BAR; WAIT_L(0); MMA(0, 1, At, B1); BAR;
;     LDA(At, 0, 1); STAGE(SA(0, 0), A, brow, t + 2);
;     BAR; WAIT_L(0); MMA(1, 0, At, B0); BAR; SCHED;
;     STAGE(SB(0, 1), Bt, bcol + G_HALF, t + 2);
;     WAIT_V(6); BAR; MMA(1, 1, At, B1); BAR;
	s_waitcnt lgkmcnt(1)
	v_mfma_f32_16x16x32_bf16 v[126:129], v[172:175], v[156:159], 0
	s_add_i32 s3, s2, 0xfff7ff80
	s_add_i32 m0, s100, 0x10000
	v_mfma_f32_16x16x32_bf16 v[122:125], v[172:175], v[164:167], 0
	v_mfma_f32_16x16x32_bf16 v[118:121], v[180:183], v[156:159], 0
	v_mfma_f32_16x16x32_bf16 v[114:117], v[180:183], v[164:167], 0
	v_mfma_f32_16x16x32_bf16 v[110:113], v[188:191], v[156:159], 0
	v_mfma_f32_16x16x32_bf16 v[106:109], v[188:191], v[164:167], 0
	v_mfma_f32_16x16x32_bf16 v[102:105], v[196:199], v[156:159], 0
	v_mfma_f32_16x16x32_bf16 v[98:101], v[196:199], v[164:167], 0
	v_mfma_f32_16x16x32_bf16 v[126:129], v[176:179], v[160:163], v[126:129]
	v_mfma_f32_16x16x32_bf16 v[122:125], v[176:179], v[168:171], v[122:125]
	v_mfma_f32_16x16x32_bf16 v[118:121], v[184:187], v[160:163], v[118:121]
	v_mfma_f32_16x16x32_bf16 v[114:117], v[184:187], v[168:171], v[114:117]
	v_mfma_f32_16x16x32_bf16 v[110:113], v[192:195], v[160:163], v[110:113]
	v_mfma_f32_16x16x32_bf16 v[106:109], v[192:195], v[168:171], v[106:109]
	s_waitcnt lgkmcnt(0)
	v_mfma_f32_16x16x32_bf16 v[102:105], v[200:203], v[160:163], v[102:105]
	v_mfma_f32_16x16x32_bf16 v[98:101], v[200:203], v[168:171], v[98:101]
	s_barrier
	ds_read_b128 v[204:207], v147
	ds_read_b128 v[208:211], v147 offset:1024
	ds_read_b128 v[212:215], v147 offset:2048
	buffer_load_dwordx4 v136, s[4:7], s3 offen lds
	s_add_i32 m0, s100, 0x12000
	ds_read_b128 v[216:219], v147 offset:3072
	buffer_load_dwordx4 v135, s[4:7], s3 offen lds
	s_barrier
	s_waitcnt lgkmcnt(1)
	v_mfma_f32_16x16x32_bf16 v[94:97], v[172:175], v[204:207], 0
	v_mfma_f32_16x16x32_bf16 v[90:93], v[172:175], v[212:215], 0
	v_mfma_f32_16x16x32_bf16 v[86:89], v[180:183], v[204:207], 0
	v_mfma_f32_16x16x32_bf16 v[82:85], v[180:183], v[212:215], 0
	v_mfma_f32_16x16x32_bf16 v[78:81], v[188:191], v[204:207], 0
	v_mfma_f32_16x16x32_bf16 v[74:77], v[188:191], v[212:215], 0
	v_mfma_f32_16x16x32_bf16 v[70:73], v[196:199], v[204:207], 0
	v_mfma_f32_16x16x32_bf16 v[66:69], v[196:199], v[212:215], 0
	v_mfma_f32_16x16x32_bf16 v[94:97], v[176:179], v[208:211], v[94:97]
	s_waitcnt lgkmcnt(0)
	v_mfma_f32_16x16x32_bf16 v[90:93], v[176:179], v[216:219], v[90:93]
	v_mfma_f32_16x16x32_bf16 v[86:89], v[184:187], v[208:211], v[86:89]
	v_mfma_f32_16x16x32_bf16 v[82:85], v[184:187], v[216:219], v[82:85]
	v_mfma_f32_16x16x32_bf16 v[78:81], v[192:195], v[208:211], v[78:81]
	v_mfma_f32_16x16x32_bf16 v[74:77], v[192:195], v[216:219], v[74:77]
	v_mfma_f32_16x16x32_bf16 v[70:73], v[200:203], v[208:211], v[70:73]
	v_mfma_f32_16x16x32_bf16 v[66:69], v[200:203], v[216:219], v[66:69]
	s_mov_b32 m0, s100
	s_barrier
	ds_read_b128 v[172:175], v133 offset:16384
	ds_read_b128 v[176:179], v133 offset:17408
	ds_read_b128 v[180:183], v132 offset:16384
	ds_read_b128 v[184:187], v132 offset:17408
	ds_read_b128 v[188:191], v131 offset:16384
	ds_read_b128 v[192:195], v131 offset:17408
	ds_read_b128 v[196:199], v130 offset:16384
	buffer_load_dwordx4 v136, s[88:91], s3 offen lds
	s_add_i32 m0, s100, 0x2000
	ds_read_b128 v[200:203], v130 offset:17408
	buffer_load_dwordx4 v135, s[88:91], s3 offen lds
	s_barrier
	s_waitcnt lgkmcnt(1)
	v_mfma_f32_16x16x32_bf16 v[62:65], v[172:175], v[156:159], 0
	s_add_i32 s3, s2, 0xffffff80
	s_add_i32 m0, s100, 0x14000
	v_mfma_f32_16x16x32_bf16 v[58:61], v[172:175], v[164:167], 0
	v_mfma_f32_16x16x32_bf16 v[54:57], v[180:183], v[156:159], 0
	v_mfma_f32_16x16x32_bf16 v[50:53], v[180:183], v[164:167], 0
	v_mfma_f32_16x16x32_bf16 v[46:49], v[188:191], v[156:159], 0
	v_mfma_f32_16x16x32_bf16 v[42:45], v[188:191], v[164:167], 0
	v_mfma_f32_16x16x32_bf16 v[38:41], v[196:199], v[156:159], 0
	v_mfma_f32_16x16x32_bf16 v[34:37], v[196:199], v[164:167], 0
	v_mfma_f32_16x16x32_bf16 v[62:65], v[176:179], v[160:163], v[62:65]
	v_mfma_f32_16x16x32_bf16 v[58:61], v[176:179], v[168:171], v[58:61]
	v_mfma_f32_16x16x32_bf16 v[54:57], v[184:187], v[160:163], v[54:57]
	v_mfma_f32_16x16x32_bf16 v[50:53], v[184:187], v[168:171], v[50:53]
	v_mfma_f32_16x16x32_bf16 v[46:49], v[192:195], v[160:163], v[46:49]
	v_mfma_f32_16x16x32_bf16 v[42:45], v[192:195], v[168:171], v[42:45]
	s_waitcnt lgkmcnt(0)
	v_mfma_f32_16x16x32_bf16 v[38:41], v[200:203], v[160:163], v[38:41]
	v_mfma_f32_16x16x32_bf16 v[34:37], v[200:203], v[168:171], v[34:37]
	s_barrier
	buffer_load_dwordx4 v136, s[4:7], s3 offen lds
	s_add_i32 m0, s100, 0x16000
	s_nop 0
	buffer_load_dwordx4 v135, s[4:7], s3 offen lds
	s_waitcnt vmcnt(6)
	s_barrier
	v_mfma_f32_16x16x32_bf16 v[30:33], v[172:175], v[204:207], 0
	s_add_i32 m0, s100, 0x4000
	v_mfma_f32_16x16x32_bf16 v[26:29], v[172:175], v[212:215], 0
	v_mfma_f32_16x16x32_bf16 v[22:25], v[180:183], v[204:207], 0
	v_mfma_f32_16x16x32_bf16 v[18:21], v[180:183], v[212:215], 0
	v_mfma_f32_16x16x32_bf16 v[14:17], v[188:191], v[204:207], 0
	v_mfma_f32_16x16x32_bf16 v[10:13], v[188:191], v[212:215], 0
	v_mfma_f32_16x16x32_bf16 v[6:9], v[196:199], v[204:207], 0
	v_mfma_f32_16x16x32_bf16 v[2:5], v[196:199], v[212:215], 0
	v_mfma_f32_16x16x32_bf16 v[30:33], v[176:179], v[208:211], v[30:33]
	v_mfma_f32_16x16x32_bf16 v[26:29], v[176:179], v[216:219], v[26:29]
	v_mfma_f32_16x16x32_bf16 v[22:25], v[184:187], v[208:211], v[22:25]
	v_mfma_f32_16x16x32_bf16 v[18:21], v[184:187], v[216:219], v[18:21]
	v_mfma_f32_16x16x32_bf16 v[14:17], v[192:195], v[208:211], v[14:17]
	v_mfma_f32_16x16x32_bf16 v[10:13], v[192:195], v[216:219], v[10:13]
	v_mfma_f32_16x16x32_bf16 v[6:9], v[200:203], v[208:211], v[6:9]
	v_mfma_f32_16x16x32_bf16 v[2:5], v[200:203], v[216:219], v[2:5]
	s_barrier
; #define WAIT_V(n) asm volatile("s_waitcnt vmcnt(" #n ")" ::: "memory")
; #define WAIT_L(n) asm volatile("s_waitcnt lgkmcnt(" #n ")" ::: "memory")
; #define BAR __builtin_amdgcn_s_barrier()
; #define SCHED __builtin_amdgcn_sched_barrier(0)
; __device__ __forceinline__ void mainloop_8phase(const u16* __restrict__ A, const u16* __restrict__ Bt, int K,
;                                                 f32x4 (&acc)[2][2][4][2], int wid_s, int ld) {
;     ...
;     LDB(B0, 1, 0); SCHED; LDA(At, 1, 0); STAGE(SA(0, 1), A, brow + G_HALF, t + 2);
;     WAIT_L(8); BAR; WAIT_L(0); MMA(0, 0, At, B0); BAR; SCHED;
;     LDB(B1, 1, 1); STAGE(SB(1, 0), Bt, bcol, t + 3);
;     BAR; WAIT_L(0); MMA(0, 1, At, B1); BAR;
;     LDA(At, 1, 1); STAGE(SA(1, 0), A, brow, t + 3);
;     BAR; WAIT_L(0); MMA(1, 0, At, B0); BAR; SCHED;
;     STAGE(SB(1, 1), Bt, bcol + G_HALF, t + 3);
;     WAIT_V(6); BAR; MMA(1, 1, At, B1); BAR;
;   }
	ds_read_b128 v[156:159], v137
	ds_read_b128 v[160:163], v137 offset:1024
	ds_read_b128 v[164:167], v137 offset:2048
	ds_read_b128 v[168:171], v137 offset:3072
	ds_read_b128 v[172:175], v133 offset:32768
	ds_read_b128 v[176:179], v133 offset:33792
	ds_read_b128 v[180:183], v132 offset:32768
	ds_read_b128 v[184:187], v132 offset:33792
	ds_read_b128 v[188:191], v131 offset:32768
	ds_read_b128 v[192:195], v131 offset:33792
	ds_read_b128 v[196:199], v130 offset:32768
	buffer_load_dwordx4 v136, s[88:91], s3 offen lds
	s_add_i32 m0, s100, 0x6000
	ds_read_b128 v[200:203], v130 offset:33792
	buffer_load_dwordx4 v135, s[88:91], s3 offen lds
	s_waitcnt lgkmcnt(8)
	s_barrier
	s_waitcnt lgkmcnt(1)
	v_mfma_f32_16x16x32_bf16 v[126:129], v[172:175], v[156:159], v[126:129]
	s_add_i32 s3, s2, 0xfff80000
	s_add_i32 m0, s100, 0x18000
	v_mfma_f32_16x16x32_bf16 v[122:125], v[172:175], v[164:167], v[122:125]
	v_mfma_f32_16x16x32_bf16 v[118:121], v[180:183], v[156:159], v[118:121]
	v_mfma_f32_16x16x32_bf16 v[114:117], v[180:183], v[164:167], v[114:117]
	v_mfma_f32_16x16x32_bf16 v[110:113], v[188:191], v[156:159], v[110:113]
	v_mfma_f32_16x16x32_bf16 v[106:109], v[188:191], v[164:167], v[106:109]
	v_mfma_f32_16x16x32_bf16 v[102:105], v[196:199], v[156:159], v[102:105]
	v_mfma_f32_16x16x32_bf16 v[98:101], v[196:199], v[164:167], v[98:101]
	v_mfma_f32_16x16x32_bf16 v[126:129], v[176:179], v[160:163], v[126:129]
	v_mfma_f32_16x16x32_bf16 v[122:125], v[176:179], v[168:171], v[122:125]
	v_mfma_f32_16x16x32_bf16 v[118:121], v[184:187], v[160:163], v[118:121]
	v_mfma_f32_16x16x32_bf16 v[114:117], v[184:187], v[168:171], v[114:117]
	v_mfma_f32_16x16x32_bf16 v[110:113], v[192:195], v[160:163], v[110:113]
	v_mfma_f32_16x16x32_bf16 v[106:109], v[192:195], v[168:171], v[106:109]
	s_waitcnt lgkmcnt(0)
	v_mfma_f32_16x16x32_bf16 v[102:105], v[200:203], v[160:163], v[102:105]
	v_mfma_f32_16x16x32_bf16 v[98:101], v[200:203], v[168:171], v[98:101]
	s_barrier
	ds_read_b128 v[204:207], v134
	ds_read_b128 v[208:211], v134 offset:1024
	ds_read_b128 v[212:215], v134 offset:2048
	buffer_load_dwordx4 v136, s[4:7], s3 offen lds
	s_add_i32 m0, s100, 0x1a000
	ds_read_b128 v[216:219], v134 offset:3072
	buffer_load_dwordx4 v135, s[4:7], s3 offen lds
	s_barrier
	s_waitcnt lgkmcnt(1)
	v_mfma_f32_16x16x32_bf16 v[94:97], v[172:175], v[204:207], v[94:97]
	v_mfma_f32_16x16x32_bf16 v[90:93], v[172:175], v[212:215], v[90:93]
	v_mfma_f32_16x16x32_bf16 v[86:89], v[180:183], v[204:207], v[86:89]
	v_mfma_f32_16x16x32_bf16 v[82:85], v[180:183], v[212:215], v[82:85]
	v_mfma_f32_16x16x32_bf16 v[78:81], v[188:191], v[204:207], v[78:81]
	v_mfma_f32_16x16x32_bf16 v[74:77], v[188:191], v[212:215], v[74:77]
	v_mfma_f32_16x16x32_bf16 v[70:73], v[196:199], v[204:207], v[70:73]
	v_mfma_f32_16x16x32_bf16 v[66:69], v[196:199], v[212:215], v[66:69]
	v_mfma_f32_16x16x32_bf16 v[94:97], v[176:179], v[208:211], v[94:97]
	s_waitcnt lgkmcnt(0)
	v_mfma_f32_16x16x32_bf16 v[90:93], v[176:179], v[216:219], v[90:93]
	v_mfma_f32_16x16x32_bf16 v[86:89], v[184:187], v[208:211], v[86:89]
	v_mfma_f32_16x16x32_bf16 v[82:85], v[184:187], v[216:219], v[82:85]
	v_mfma_f32_16x16x32_bf16 v[78:81], v[192:195], v[208:211], v[78:81]
	v_mfma_f32_16x16x32_bf16 v[74:77], v[192:195], v[216:219], v[74:77]
	v_mfma_f32_16x16x32_bf16 v[70:73], v[200:203], v[208:211], v[70:73]
	v_mfma_f32_16x16x32_bf16 v[66:69], v[200:203], v[216:219], v[66:69]
	s_add_i32 m0, s100, 0x8000
	s_barrier
	ds_read_b128 v[172:175], v133 offset:49152
	ds_read_b128 v[176:179], v133 offset:50176
	ds_read_b128 v[180:183], v132 offset:49152
	ds_read_b128 v[184:187], v132 offset:50176
	ds_read_b128 v[188:191], v131 offset:49152
	ds_read_b128 v[192:195], v131 offset:50176
	ds_read_b128 v[196:199], v130 offset:49152
	buffer_load_dwordx4 v136, s[88:91], s3 offen lds
	s_add_i32 m0, s100, 0xa000
	ds_read_b128 v[200:203], v130 offset:50176
	buffer_load_dwordx4 v135, s[88:91], s3 offen lds
	s_barrier
	s_waitcnt lgkmcnt(1)
	v_mfma_f32_16x16x32_bf16 v[62:65], v[172:175], v[156:159], v[62:65]
	s_add_i32 m0, s100, 0x1c000
	v_mfma_f32_16x16x32_bf16 v[58:61], v[172:175], v[164:167], v[58:61]
	v_mfma_f32_16x16x32_bf16 v[54:57], v[180:183], v[156:159], v[54:57]
	v_mfma_f32_16x16x32_bf16 v[50:53], v[180:183], v[164:167], v[50:53]
	v_mfma_f32_16x16x32_bf16 v[46:49], v[188:191], v[156:159], v[46:49]
	v_mfma_f32_16x16x32_bf16 v[42:45], v[188:191], v[164:167], v[42:45]
	v_mfma_f32_16x16x32_bf16 v[38:41], v[196:199], v[156:159], v[38:41]
	v_mfma_f32_16x16x32_bf16 v[34:37], v[196:199], v[164:167], v[34:37]
	v_mfma_f32_16x16x32_bf16 v[62:65], v[176:179], v[160:163], v[62:65]
	v_mfma_f32_16x16x32_bf16 v[58:61], v[176:179], v[168:171], v[58:61]
	v_mfma_f32_16x16x32_bf16 v[54:57], v[184:187], v[160:163], v[54:57]
	v_mfma_f32_16x16x32_bf16 v[50:53], v[184:187], v[168:171], v[50:53]
	v_mfma_f32_16x16x32_bf16 v[46:49], v[192:195], v[160:163], v[46:49]
	v_mfma_f32_16x16x32_bf16 v[42:45], v[192:195], v[168:171], v[42:45]
	s_waitcnt lgkmcnt(0)
	v_mfma_f32_16x16x32_bf16 v[38:41], v[200:203], v[160:163], v[38:41]
	v_mfma_f32_16x16x32_bf16 v[34:37], v[200:203], v[168:171], v[34:37]
	s_barrier
	buffer_load_dwordx4 v136, s[4:7], s2 offen lds
	s_add_i32 m0, s100, 0x1e000
	s_nop 0
	buffer_load_dwordx4 v135, s[4:7], s2 offen lds
	s_waitcnt vmcnt(6)
	s_barrier
	v_mfma_f32_16x16x32_bf16 v[30:33], v[172:175], v[204:207], v[30:33]
	v_mfma_f32_16x16x32_bf16 v[26:29], v[172:175], v[212:215], v[26:29]
	v_mfma_f32_16x16x32_bf16 v[22:25], v[180:183], v[204:207], v[22:25]
	v_mfma_f32_16x16x32_bf16 v[18:21], v[180:183], v[212:215], v[18:21]
	v_mfma_f32_16x16x32_bf16 v[14:17], v[188:191], v[204:207], v[14:17]
	v_mfma_f32_16x16x32_bf16 v[10:13], v[188:191], v[212:215], v[10:13]
	v_mfma_f32_16x16x32_bf16 v[6:9], v[196:199], v[204:207], v[6:9]
	v_mfma_f32_16x16x32_bf16 v[2:5], v[196:199], v[212:215], v[2:5]
	v_mfma_f32_16x16x32_bf16 v[30:33], v[176:179], v[208:211], v[30:33]
	v_mfma_f32_16x16x32_bf16 v[26:29], v[176:179], v[216:219], v[26:29]
	v_mfma_f32_16x16x32_bf16 v[22:25], v[184:187], v[208:211], v[22:25]
	v_mfma_f32_16x16x32_bf16 v[18:21], v[184:187], v[216:219], v[18:21]
	v_mfma_f32_16x16x32_bf16 v[14:17], v[192:195], v[208:211], v[14:17]
	v_mfma_f32_16x16x32_bf16 v[10:13], v[192:195], v[216:219], v[10:13]
	v_mfma_f32_16x16x32_bf16 v[6:9], v[200:203], v[208:211], v[6:9]
	v_mfma_f32_16x16x32_bf16 v[2:5], v[200:203], v[216:219], v[2:5]
	s_add_i32 s1, s1, 2
	s_addk_i32 s2, 0x100
	s_add_i32 s3, s2, 0xffffff00
	s_add_i32 m0, s100, 0xc000
	s_cmp_lt_u32 s1, 28
	s_barrier
; #define WAIT_V(n) asm volatile("s_waitcnt vmcnt(" #n ")" ::: "memory")
; #define WAIT_L(n) asm volatile("s_waitcnt lgkmcnt(" #n ")" ::: "memory")
; #define BAR __builtin_amdgcn_s_barrier()
; #define SCHED __builtin_amdgcn_sched_barrier(0)
; __device__ __forceinline__ void mainloop_8phase(const u16* __restrict__ A, const u16* __restrict__ Bt, int K,
;                                                 f32x4 (&acc)[2][2][4][2], int wid_s, int ld) {
;     ...
;     LDB(B0, 0, 0); SCHED; LDA(At, 0, 0); STAGE(SA(1, 1), A, brow + G_HALF, t + 1);
;     WAIT_L(8); BAR; WAIT_L(0); MMA(0, 0, At, B0); BAR; SCHED;
;     LDB(B1, 0, 1); STAGE(SB(0, 0), Bt, bcol, t + 2);
;     BAR; WAIT_L(0); MMA(0, 1, At, B1); BAR;
;     LDA(At, 0, 1); STAGE(SA(0, 0), A, brow, t + 2);
;     BAR; WAIT_L(0); MMA(1, 0, At, B0); BAR; SCHED;
;     STAGE(SB(0, 1), Bt, bcol + G_HALF, t + 2);
;     WAIT_V(6); BAR; MMA(1, 1, At, B1); BAR;
.LBB0_342:
	ds_read_b128 v[156:159], v155
	ds_read_b128 v[160:163], v155 offset:1024
	ds_read_b128 v[164:167], v155 offset:2048
	ds_read_b128 v[168:171], v155 offset:3072
	ds_read_b128 v[172:175], v133
	ds_read_b128 v[176:179], v133 offset:1024
	ds_read_b128 v[180:183], v132
	ds_read_b128 v[184:187], v132 offset:1024
	ds_read_b128 v[188:191], v131
	ds_read_b128 v[192:195], v131 offset:1024
	ds_read_b128 v[196:199], v130
	buffer_load_dwordx4 v136, s[88:91], s3 offen lds
	s_add_i32 m0, s100, 0xe000
	ds_read_b128 v[200:203], v130 offset:1024
	buffer_load_dwordx4 v135, s[88:91], s3 offen lds
	s_waitcnt lgkmcnt(8)
	s_barrier
	s_waitcnt lgkmcnt(1)
	v_mfma_f32_16x16x32_bf16 v[126:129], v[172:175], v[156:159], v[126:129]
	s_add_i32 s3, s2, 0xfff7ff80
	s_add_i32 m0, s100, 0x10000
	v_mfma_f32_16x16x32_bf16 v[122:125], v[172:175], v[164:167], v[122:125]
	v_mfma_f32_16x16x32_bf16 v[118:121], v[180:183], v[156:159], v[118:121]
	v_mfma_f32_16x16x32_bf16 v[114:117], v[180:183], v[164:167], v[114:117]
	v_mfma_f32_16x16x32_bf16 v[110:113], v[188:191], v[156:159], v[110:113]
	v_mfma_f32_16x16x32_bf16 v[106:109], v[188:191], v[164:167], v[106:109]
	v_mfma_f32_16x16x32_bf16 v[102:105], v[196:199], v[156:159], v[102:105]
	v_mfma_f32_16x16x32_bf16 v[98:101], v[196:199], v[164:167], v[98:101]
	v_mfma_f32_16x16x32_bf16 v[126:129], v[176:179], v[160:163], v[126:129]
	v_mfma_f32_16x16x32_bf16 v[122:125], v[176:179], v[168:171], v[122:125]
	v_mfma_f32_16x16x32_bf16 v[118:121], v[184:187], v[160:163], v[118:121]
	v_mfma_f32_16x16x32_bf16 v[114:117], v[184:187], v[168:171], v[114:117]
	v_mfma_f32_16x16x32_bf16 v[110:113], v[192:195], v[160:163], v[110:113]
	v_mfma_f32_16x16x32_bf16 v[106:109], v[192:195], v[168:171], v[106:109]
	s_waitcnt lgkmcnt(0)
	v_mfma_f32_16x16x32_bf16 v[102:105], v[200:203], v[160:163], v[102:105]
	v_mfma_f32_16x16x32_bf16 v[98:101], v[200:203], v[168:171], v[98:101]
	s_barrier
	ds_read_b128 v[204:207], v147
	ds_read_b128 v[208:211], v147 offset:1024
	ds_read_b128 v[212:215], v147 offset:2048
	buffer_load_dwordx4 v136, s[4:7], s3 offen lds
	s_add_i32 m0, s100, 0x12000
	ds_read_b128 v[216:219], v147 offset:3072
	buffer_load_dwordx4 v135, s[4:7], s3 offen lds
	s_barrier
	s_waitcnt lgkmcnt(1)
	v_mfma_f32_16x16x32_bf16 v[94:97], v[172:175], v[204:207], v[94:97]
	v_mfma_f32_16x16x32_bf16 v[90:93], v[172:175], v[212:215], v[90:93]
	v_mfma_f32_16x16x32_bf16 v[86:89], v[180:183], v[204:207], v[86:89]
	v_mfma_f32_16x16x32_bf16 v[82:85], v[180:183], v[212:215], v[82:85]
	v_mfma_f32_16x16x32_bf16 v[78:81], v[188:191], v[204:207], v[78:81]
	v_mfma_f32_16x16x32_bf16 v[74:77], v[188:191], v[212:215], v[74:77]
	v_mfma_f32_16x16x32_bf16 v[70:73], v[196:199], v[204:207], v[70:73]
	v_mfma_f32_16x16x32_bf16 v[66:69], v[196:199], v[212:215], v[66:69]
	v_mfma_f32_16x16x32_bf16 v[94:97], v[176:179], v[208:211], v[94:97]
	s_waitcnt lgkmcnt(0)
	v_mfma_f32_16x16x32_bf16 v[90:93], v[176:179], v[216:219], v[90:93]
	v_mfma_f32_16x16x32_bf16 v[86:89], v[184:187], v[208:211], v[86:89]
	v_mfma_f32_16x16x32_bf16 v[82:85], v[184:187], v[216:219], v[82:85]
	v_mfma_f32_16x16x32_bf16 v[78:81], v[192:195], v[208:211], v[78:81]
	v_mfma_f32_16x16x32_bf16 v[74:77], v[192:195], v[216:219], v[74:77]
	v_mfma_f32_16x16x32_bf16 v[70:73], v[200:203], v[208:211], v[70:73]
	v_mfma_f32_16x16x32_bf16 v[66:69], v[200:203], v[216:219], v[66:69]
	s_mov_b32 m0, s100
	s_barrier
	ds_read_b128 v[172:175], v133 offset:16384
	ds_read_b128 v[176:179], v133 offset:17408
	ds_read_b128 v[180:183], v132 offset:16384
	ds_read_b128 v[184:187], v132 offset:17408
	ds_read_b128 v[188:191], v131 offset:16384
	ds_read_b128 v[192:195], v131 offset:17408
	ds_read_b128 v[196:199], v130 offset:16384
	buffer_load_dwordx4 v136, s[88:91], s3 offen lds
	s_add_i32 m0, s100, 0x2000
	ds_read_b128 v[200:203], v130 offset:17408
	buffer_load_dwordx4 v135, s[88:91], s3 offen lds
	s_barrier
	s_waitcnt lgkmcnt(1)
	v_mfma_f32_16x16x32_bf16 v[62:65], v[172:175], v[156:159], v[62:65]
	s_add_i32 s3, s2, 0xffffff80
	s_add_i32 m0, s100, 0x14000
	v_mfma_f32_16x16x32_bf16 v[58:61], v[172:175], v[164:167], v[58:61]
	v_mfma_f32_16x16x32_bf16 v[54:57], v[180:183], v[156:159], v[54:57]
	v_mfma_f32_16x16x32_bf16 v[50:53], v[180:183], v[164:167], v[50:53]
	v_mfma_f32_16x16x32_bf16 v[46:49], v[188:191], v[156:159], v[46:49]
	v_mfma_f32_16x16x32_bf16 v[42:45], v[188:191], v[164:167], v[42:45]
	v_mfma_f32_16x16x32_bf16 v[38:41], v[196:199], v[156:159], v[38:41]
	v_mfma_f32_16x16x32_bf16 v[34:37], v[196:199], v[164:167], v[34:37]
	v_mfma_f32_16x16x32_bf16 v[62:65], v[176:179], v[160:163], v[62:65]
	v_mfma_f32_16x16x32_bf16 v[58:61], v[176:179], v[168:171], v[58:61]
	v_mfma_f32_16x16x32_bf16 v[54:57], v[184:187], v[160:163], v[54:57]
	v_mfma_f32_16x16x32_bf16 v[50:53], v[184:187], v[168:171], v[50:53]
	v_mfma_f32_16x16x32_bf16 v[46:49], v[192:195], v[160:163], v[46:49]
	v_mfma_f32_16x16x32_bf16 v[42:45], v[192:195], v[168:171], v[42:45]
	s_waitcnt lgkmcnt(0)
	v_mfma_f32_16x16x32_bf16 v[38:41], v[200:203], v[160:163], v[38:41]
	v_mfma_f32_16x16x32_bf16 v[34:37], v[200:203], v[168:171], v[34:37]
	s_barrier
	buffer_load_dwordx4 v136, s[4:7], s3 offen lds
	s_add_i32 m0, s100, 0x16000
	s_nop 0
	buffer_load_dwordx4 v135, s[4:7], s3 offen lds
	s_waitcnt vmcnt(6)
	s_barrier
; #define WAIT_V(n) asm volatile("s_waitcnt vmcnt(" #n ")" ::: "memory")
; #define WAIT_L(n) asm volatile("s_waitcnt lgkmcnt(" #n ")" ::: "memory")
; #define BAR __builtin_amdgcn_s_barrier()
; #define SCHED __builtin_amdgcn_sched_barrier(0)
; __device__ __forceinline__ void mainloop_8phase(const u16* __restrict__ A, const u16* __restrict__ Bt, int K,
;                                                 f32x4 (&acc)[2][2][4][2], int wid_s, int ld) {
;     ...
;     WAIT_V(6); BAR; MMA(1, 1, At, B1); BAR;
;     LDB(B0, 1, 0); SCHED; LDA(At, 1, 0); STAGE(SA(0, 1), A, brow + G_HALF, t + 2);
;     WAIT_L(8); BAR; WAIT_L(0); MMA(0, 0, At, B0); BAR; SCHED;
;     LDB(B1, 1, 1); STAGE(SB(1, 0), Bt, bcol, t + 3);
;     BAR; WAIT_L(0); MMA(0, 1, At, B1); BAR;
;     LDA(At, 1, 1); STAGE(SA(1, 0), A, brow, t + 3);
	v_mfma_f32_16x16x32_bf16 v[30:33], v[172:175], v[204:207], v[30:33]
	s_add_i32 m0, s100, 0x4000
	v_mfma_f32_16x16x32_bf16 v[26:29], v[172:175], v[212:215], v[26:29]
	v_mfma_f32_16x16x32_bf16 v[22:25], v[180:183], v[204:207], v[22:25]
	v_mfma_f32_16x16x32_bf16 v[18:21], v[180:183], v[212:215], v[18:21]
	v_mfma_f32_16x16x32_bf16 v[14:17], v[188:191], v[204:207], v[14:17]
	v_mfma_f32_16x16x32_bf16 v[10:13], v[188:191], v[212:215], v[10:13]
	v_mfma_f32_16x16x32_bf16 v[6:9], v[196:199], v[204:207], v[6:9]
	v_mfma_f32_16x16x32_bf16 v[2:5], v[196:199], v[212:215], v[2:5]
	v_mfma_f32_16x16x32_bf16 v[30:33], v[176:179], v[208:211], v[30:33]
	v_mfma_f32_16x16x32_bf16 v[26:29], v[176:179], v[216:219], v[26:29]
	v_mfma_f32_16x16x32_bf16 v[22:25], v[184:187], v[208:211], v[22:25]
	v_mfma_f32_16x16x32_bf16 v[18:21], v[184:187], v[216:219], v[18:21]
	v_mfma_f32_16x16x32_bf16 v[14:17], v[192:195], v[208:211], v[14:17]
	v_mfma_f32_16x16x32_bf16 v[10:13], v[192:195], v[216:219], v[10:13]
	v_mfma_f32_16x16x32_bf16 v[6:9], v[200:203], v[208:211], v[6:9]
	v_mfma_f32_16x16x32_bf16 v[2:5], v[200:203], v[216:219], v[2:5]
	s_barrier
	ds_read_b128 v[156:159], v137
	ds_read_b128 v[160:163], v137 offset:1024
	ds_read_b128 v[164:167], v137 offset:2048
	ds_read_b128 v[168:171], v137 offset:3072
	ds_read_b128 v[172:175], v133 offset:32768
	ds_read_b128 v[176:179], v133 offset:33792
	ds_read_b128 v[180:183], v132 offset:32768
	ds_read_b128 v[184:187], v132 offset:33792
	ds_read_b128 v[188:191], v131 offset:32768
	ds_read_b128 v[192:195], v131 offset:33792
	ds_read_b128 v[196:199], v130 offset:32768
	buffer_load_dwordx4 v136, s[88:91], s3 offen lds
	s_add_i32 m0, s100, 0x6000
	ds_read_b128 v[200:203], v130 offset:33792
	buffer_load_dwordx4 v135, s[88:91], s3 offen lds
	s_waitcnt lgkmcnt(8)
	s_barrier
	s_waitcnt lgkmcnt(1)
	v_mfma_f32_16x16x32_bf16 v[126:129], v[172:175], v[156:159], v[126:129]
	s_add_i32 s3, s2, 0xfff80000
	s_add_i32 m0, s100, 0x18000
	v_mfma_f32_16x16x32_bf16 v[122:125], v[172:175], v[164:167], v[122:125]
	v_mfma_f32_16x16x32_bf16 v[118:121], v[180:183], v[156:159], v[118:121]
	v_mfma_f32_16x16x32_bf16 v[114:117], v[180:183], v[164:167], v[114:117]
	v_mfma_f32_16x16x32_bf16 v[110:113], v[188:191], v[156:159], v[110:113]
	v_mfma_f32_16x16x32_bf16 v[106:109], v[188:191], v[164:167], v[106:109]
	v_mfma_f32_16x16x32_bf16 v[102:105], v[196:199], v[156:159], v[102:105]
	v_mfma_f32_16x16x32_bf16 v[98:101], v[196:199], v[164:167], v[98:101]
	v_mfma_f32_16x16x32_bf16 v[126:129], v[176:179], v[160:163], v[126:129]
	v_mfma_f32_16x16x32_bf16 v[122:125], v[176:179], v[168:171], v[122:125]
	v_mfma_f32_16x16x32_bf16 v[118:121], v[184:187], v[160:163], v[118:121]
	v_mfma_f32_16x16x32_bf16 v[114:117], v[184:187], v[168:171], v[114:117]
	v_mfma_f32_16x16x32_bf16 v[110:113], v[192:195], v[160:163], v[110:113]
	v_mfma_f32_16x16x32_bf16 v[106:109], v[192:195], v[168:171], v[106:109]
	s_waitcnt lgkmcnt(0)
	v_mfma_f32_16x16x32_bf16 v[102:105], v[200:203], v[160:163], v[102:105]
	v_mfma_f32_16x16x32_bf16 v[98:101], v[200:203], v[168:171], v[98:101]
	s_barrier
	ds_read_b128 v[204:207], v134
	ds_read_b128 v[208:211], v134 offset:1024
	ds_read_b128 v[212:215], v134 offset:2048
	buffer_load_dwordx4 v136, s[4:7], s3 offen lds
	s_add_i32 m0, s100, 0x1a000
	ds_read_b128 v[216:219], v134 offset:3072
	buffer_load_dwordx4 v135, s[4:7], s3 offen lds
	s_barrier
	s_waitcnt lgkmcnt(1)
	v_mfma_f32_16x16x32_bf16 v[94:97], v[172:175], v[204:207], v[94:97]
	v_mfma_f32_16x16x32_bf16 v[90:93], v[172:175], v[212:215], v[90:93]
	v_mfma_f32_16x16x32_bf16 v[86:89], v[180:183], v[204:207], v[86:89]
	v_mfma_f32_16x16x32_bf16 v[82:85], v[180:183], v[212:215], v[82:85]
	v_mfma_f32_16x16x32_bf16 v[78:81], v[188:191], v[204:207], v[78:81]
	v_mfma_f32_16x16x32_bf16 v[74:77], v[188:191], v[212:215], v[74:77]
	v_mfma_f32_16x16x32_bf16 v[70:73], v[196:199], v[204:207], v[70:73]
	v_mfma_f32_16x16x32_bf16 v[66:69], v[196:199], v[212:215], v[66:69]
	v_mfma_f32_16x16x32_bf16 v[94:97], v[176:179], v[208:211], v[94:97]
	s_waitcnt lgkmcnt(0)
	v_mfma_f32_16x16x32_bf16 v[90:93], v[176:179], v[216:219], v[90:93]
	v_mfma_f32_16x16x32_bf16 v[86:89], v[184:187], v[208:211], v[86:89]
	v_mfma_f32_16x16x32_bf16 v[82:85], v[184:187], v[216:219], v[82:85]
	v_mfma_f32_16x16x32_bf16 v[78:81], v[192:195], v[208:211], v[78:81]
	v_mfma_f32_16x16x32_bf16 v[74:77], v[192:195], v[216:219], v[74:77]
	v_mfma_f32_16x16x32_bf16 v[70:73], v[200:203], v[208:211], v[70:73]
	v_mfma_f32_16x16x32_bf16 v[66:69], v[200:203], v[216:219], v[66:69]
	s_add_i32 m0, s100, 0x8000
	s_barrier
	ds_read_b128 v[172:175], v133 offset:49152
	ds_read_b128 v[176:179], v133 offset:50176
	ds_read_b128 v[180:183], v132 offset:49152
	ds_read_b128 v[184:187], v132 offset:50176
	ds_read_b128 v[188:191], v131 offset:49152
	ds_read_b128 v[192:195], v131 offset:50176
	ds_read_b128 v[196:199], v130 offset:49152
	buffer_load_dwordx4 v136, s[88:91], s3 offen lds
	s_add_i32 m0, s100, 0xa000
	ds_read_b128 v[200:203], v130 offset:50176
	buffer_load_dwordx4 v135, s[88:91], s3 offen lds
	s_barrier
; #define WAIT_V(n) asm volatile("s_waitcnt vmcnt(" #n ")" ::: "memory")
; #define WAIT_L(n) asm volatile("s_waitcnt lgkmcnt(" #n ")" ::: "memory")
; #define BAR __builtin_amdgcn_s_barrier()
; #define SCHED __builtin_amdgcn_sched_barrier(0)
; __device__ __forceinline__ void mainloop_8phase(const u16* __restrict__ A, const u16* __restrict__ Bt, int K,
;                                                 f32x4 (&acc)[2][2][4][2], int wid_s, int ld) {
;     ...
;     BAR; WAIT_L(0); MMA(1, 0, At, B0); BAR; SCHED;
;     STAGE(SB(1, 1), Bt, bcol + G_HALF, t + 3);
;     WAIT_V(6); BAR; MMA(1, 1, At, B1); BAR;
;   }
;   { LDB(B0, 0, 0); LDA(At, 0, 0); STAGE(SA(1, 1), A, brow + G_HALF, nt - 1);
;     BAR; WAIT_L(0); MMA(0, 0, At, B0); BAR;
;     LDB(B1, 0, 1); BAR; WAIT_L(0); MMA(0, 1, At, B1); BAR;
	s_waitcnt lgkmcnt(1)
	v_mfma_f32_16x16x32_bf16 v[62:65], v[172:175], v[156:159], v[62:65]
	s_add_i32 m0, s100, 0x1c000
	v_mfma_f32_16x16x32_bf16 v[58:61], v[172:175], v[164:167], v[58:61]
	v_mfma_f32_16x16x32_bf16 v[54:57], v[180:183], v[156:159], v[54:57]
	v_mfma_f32_16x16x32_bf16 v[50:53], v[180:183], v[164:167], v[50:53]
	v_mfma_f32_16x16x32_bf16 v[46:49], v[188:191], v[156:159], v[46:49]
	v_mfma_f32_16x16x32_bf16 v[42:45], v[188:191], v[164:167], v[42:45]
	v_mfma_f32_16x16x32_bf16 v[38:41], v[196:199], v[156:159], v[38:41]
	v_mfma_f32_16x16x32_bf16 v[34:37], v[196:199], v[164:167], v[34:37]
	v_mfma_f32_16x16x32_bf16 v[62:65], v[176:179], v[160:163], v[62:65]
	v_mfma_f32_16x16x32_bf16 v[58:61], v[176:179], v[168:171], v[58:61]
	v_mfma_f32_16x16x32_bf16 v[54:57], v[184:187], v[160:163], v[54:57]
	v_mfma_f32_16x16x32_bf16 v[50:53], v[184:187], v[168:171], v[50:53]
	v_mfma_f32_16x16x32_bf16 v[46:49], v[192:195], v[160:163], v[46:49]
	v_mfma_f32_16x16x32_bf16 v[42:45], v[192:195], v[168:171], v[42:45]
	s_waitcnt lgkmcnt(0)
	v_mfma_f32_16x16x32_bf16 v[38:41], v[200:203], v[160:163], v[38:41]
	v_mfma_f32_16x16x32_bf16 v[34:37], v[200:203], v[168:171], v[34:37]
	s_barrier
	buffer_load_dwordx4 v136, s[4:7], s2 offen lds
	s_add_i32 m0, s100, 0x1e000
	s_nop 0
	buffer_load_dwordx4 v135, s[4:7], s2 offen lds
	s_waitcnt vmcnt(6)
	s_barrier
	v_mfma_f32_16x16x32_bf16 v[30:33], v[172:175], v[204:207], v[30:33]
	v_mfma_f32_16x16x32_bf16 v[26:29], v[172:175], v[212:215], v[26:29]
	v_mfma_f32_16x16x32_bf16 v[22:25], v[180:183], v[204:207], v[22:25]
	v_mfma_f32_16x16x32_bf16 v[18:21], v[180:183], v[212:215], v[18:21]
	v_mfma_f32_16x16x32_bf16 v[14:17], v[188:191], v[204:207], v[14:17]
	v_mfma_f32_16x16x32_bf16 v[10:13], v[188:191], v[212:215], v[10:13]
	v_mfma_f32_16x16x32_bf16 v[6:9], v[196:199], v[204:207], v[6:9]
	v_mfma_f32_16x16x32_bf16 v[2:5], v[196:199], v[212:215], v[2:5]
	v_mfma_f32_16x16x32_bf16 v[30:33], v[176:179], v[208:211], v[30:33]
	v_mfma_f32_16x16x32_bf16 v[26:29], v[176:179], v[216:219], v[26:29]
	v_mfma_f32_16x16x32_bf16 v[22:25], v[184:187], v[208:211], v[22:25]
	v_mfma_f32_16x16x32_bf16 v[18:21], v[184:187], v[216:219], v[18:21]
	v_mfma_f32_16x16x32_bf16 v[14:17], v[192:195], v[208:211], v[14:17]
	v_mfma_f32_16x16x32_bf16 v[10:13], v[192:195], v[216:219], v[10:13]
	v_mfma_f32_16x16x32_bf16 v[6:9], v[200:203], v[208:211], v[6:9]
	v_mfma_f32_16x16x32_bf16 v[2:5], v[200:203], v[216:219], v[2:5]
	s_add_i32 s1, s1, 2
	s_addk_i32 s2, 0x100
	s_add_i32 s3, s2, 0xffffff00
	s_add_i32 m0, s100, 0xc000
	s_cmp_lt_u32 s1, 28
	s_barrier
	s_cbranch_scc1 .LBB0_342
	v_readfirstlane_b32 s1, v145
	s_mov_b32 m0, s1
	s_mov_b32 s2, 0x80f80
	v_readfirstlane_b32 s1, v144
	ds_read_b128 v[138:141], v155
	ds_read_b128 v[148:151], v155 offset:1024
	ds_read_b128 v[156:159], v155 offset:2048
	ds_read_b128 v[152:155], v155 offset:3072
	ds_read_b128 v[160:163], v133
	ds_read_b128 v[164:167], v133 offset:1024
	ds_read_b128 v[168:171], v132
	ds_read_b128 v[172:175], v132 offset:1024
	ds_read_b128 v[176:179], v131
	ds_read_b128 v[180:183], v131 offset:1024
	ds_read_b128 v[184:187], v130
	ds_read_b128 v[188:191], v130 offset:1024
	buffer_load_dwordx4 v136, s[88:91], s2 offen lds
	s_mov_b32 m0, s1
	s_nop 0
	buffer_load_dwordx4 v135, s[88:91], s2 offen lds
	s_barrier
	s_waitcnt lgkmcnt(0)
	v_mfma_f32_16x16x32_bf16 v[126:129], v[160:163], v[138:141], v[126:129]
	v_mfma_f32_16x16x32_bf16 v[118:121], v[168:171], v[138:141], v[118:121]
	v_mfma_f32_16x16x32_bf16 v[110:113], v[176:179], v[138:141], v[110:113]
	v_mfma_f32_16x16x32_bf16 v[102:105], v[184:187], v[138:141], v[102:105]
	v_mfma_f32_16x16x32_bf16 v[126:129], v[164:167], v[148:151], v[126:129]
	v_mfma_f32_16x16x32_bf16 v[122:125], v[160:163], v[156:159], v[122:125]
	v_mfma_f32_16x16x32_bf16 v[118:121], v[172:175], v[148:151], v[118:121]
	v_mfma_f32_16x16x32_bf16 v[114:117], v[168:171], v[156:159], v[114:117]
	v_mfma_f32_16x16x32_bf16 v[110:113], v[180:183], v[148:151], v[110:113]
	v_mfma_f32_16x16x32_bf16 v[106:109], v[176:179], v[156:159], v[106:109]
	v_mfma_f32_16x16x32_bf16 v[102:105], v[188:191], v[148:151], v[102:105]
	v_mfma_f32_16x16x32_bf16 v[98:101], v[184:187], v[156:159], v[98:101]
	v_mfma_f32_16x16x32_bf16 v[142:145], v[164:167], v[152:155], v[122:125]
	v_mfma_f32_16x16x32_bf16 v[192:195], v[172:175], v[152:155], v[114:117]
	v_mfma_f32_16x16x32_bf16 v[196:199], v[180:183], v[152:155], v[106:109]
	v_mfma_f32_16x16x32_bf16 v[200:203], v[188:191], v[152:155], v[98:101]
	s_barrier
	s_nop 1
	ds_read_b128 v[98:101], v147
	ds_read_b128 v[106:109], v147 offset:1024
	ds_read_b128 v[114:117], v147 offset:2048
	ds_read_b128 v[122:125], v147 offset:3072
	s_barrier
	s_waitcnt lgkmcnt(0)
	v_mfma_f32_16x16x32_bf16 v[94:97], v[160:163], v[98:101], v[94:97]
	v_mfma_f32_16x16x32_bf16 v[90:93], v[160:163], v[114:117], v[90:93]
	v_mfma_f32_16x16x32_bf16 v[86:89], v[168:171], v[98:101], v[86:89]
	v_mfma_f32_16x16x32_bf16 v[82:85], v[168:171], v[114:117], v[82:85]
	v_mfma_f32_16x16x32_bf16 v[78:81], v[176:179], v[98:101], v[78:81]
	v_mfma_f32_16x16x32_bf16 v[74:77], v[176:179], v[114:117], v[74:77]
	v_mfma_f32_16x16x32_bf16 v[70:73], v[184:187], v[98:101], v[70:73]
	v_mfma_f32_16x16x32_bf16 v[66:69], v[184:187], v[114:117], v[66:69]
	v_mfma_f32_16x16x32_bf16 v[94:97], v[164:167], v[106:109], v[94:97]
	v_mfma_f32_16x16x32_bf16 v[90:93], v[164:167], v[122:125], v[90:93]
	v_mfma_f32_16x16x32_bf16 v[86:89], v[172:175], v[106:109], v[86:89]
	v_mfma_f32_16x16x32_bf16 v[82:85], v[172:175], v[122:125], v[82:85]
	v_mfma_f32_16x16x32_bf16 v[78:81], v[180:183], v[106:109], v[78:81]
	v_mfma_f32_16x16x32_bf16 v[74:77], v[180:183], v[122:125], v[74:77]
	v_mfma_f32_16x16x32_bf16 v[70:73], v[188:191], v[106:109], v[70:73]
	v_mfma_f32_16x16x32_bf16 v[66:69], v[188:191], v[122:125], v[66:69]
	s_barrier
; #define WAIT_V(n) asm volatile("s_waitcnt vmcnt(" #n ")" ::: "memory")
; #define WAIT_L(n) asm volatile("s_waitcnt lgkmcnt(" #n ")" ::: "memory")
; #define BAR __builtin_amdgcn_s_barrier()
; __device__ __forceinline__ void mainloop_8phase(const u16* __restrict__ A, const u16* __restrict__ Bt, int K,
;                                                 f32x4 (&acc)[2][2][4][2], int wid_s, int ld) {
;     ...
;     LDA(At, 0, 1); WAIT_V(4); BAR; WAIT_L(0); MMA(1, 0, At, B0); MMA(1, 1, At, B1); BAR; }
;   { LDB(B0, 1, 0); LDA(At, 1, 0); WAIT_V(2); BAR; WAIT_L(0); MMA(0, 0, At, B0); BAR;
	ds_read_b128 v[160:163], v133 offset:16384
	ds_read_b128 v[164:167], v133 offset:17408
	ds_read_b128 v[168:171], v132 offset:16384
	ds_read_b128 v[172:175], v132 offset:17408
	ds_read_b128 v[176:179], v131 offset:16384
	ds_read_b128 v[180:183], v131 offset:17408
	ds_read_b128 v[184:187], v130 offset:16384
	ds_read_b128 v[188:191], v130 offset:17408
	s_waitcnt vmcnt(4)
	s_barrier
	s_waitcnt lgkmcnt(0)
	v_mfma_f32_16x16x32_bf16 v[62:65], v[160:163], v[138:141], v[62:65]
	v_mfma_f32_16x16x32_bf16 v[58:61], v[160:163], v[156:159], v[58:61]
	v_mfma_f32_16x16x32_bf16 v[54:57], v[168:171], v[138:141], v[54:57]
	v_mfma_f32_16x16x32_bf16 v[50:53], v[168:171], v[156:159], v[50:53]
	v_mfma_f32_16x16x32_bf16 v[46:49], v[176:179], v[138:141], v[46:49]
	v_mfma_f32_16x16x32_bf16 v[42:45], v[176:179], v[156:159], v[42:45]
	v_mfma_f32_16x16x32_bf16 v[38:41], v[184:187], v[138:141], v[38:41]
	v_mfma_f32_16x16x32_bf16 v[34:37], v[184:187], v[156:159], v[34:37]
	v_mfma_f32_16x16x32_bf16 v[204:207], v[164:167], v[148:151], v[62:65]
	v_mfma_f32_16x16x32_bf16 v[208:211], v[164:167], v[152:155], v[58:61]
	v_mfma_f32_16x16x32_bf16 v[212:215], v[172:175], v[148:151], v[54:57]
	v_mfma_f32_16x16x32_bf16 v[216:219], v[172:175], v[152:155], v[50:53]
	v_mfma_f32_16x16x32_bf16 v[220:223], v[180:183], v[148:151], v[46:49]
	v_mfma_f32_16x16x32_bf16 v[224:227], v[180:183], v[152:155], v[42:45]
	v_mfma_f32_16x16x32_bf16 v[138:141], v[188:191], v[148:151], v[38:41]
	v_mfma_f32_16x16x32_bf16 v[146:149], v[188:191], v[152:155], v[34:37]
	v_mfma_f32_16x16x32_bf16 v[30:33], v[160:163], v[98:101], v[30:33]
	v_mfma_f32_16x16x32_bf16 v[22:25], v[168:171], v[98:101], v[22:25]
	v_mfma_f32_16x16x32_bf16 v[14:17], v[176:179], v[98:101], v[14:17]
	v_mfma_f32_16x16x32_bf16 v[6:9], v[184:187], v[98:101], v[6:9]
	v_mfma_f32_16x16x32_bf16 v[30:33], v[164:167], v[106:109], v[30:33]
	v_mfma_f32_16x16x32_bf16 v[26:29], v[160:163], v[114:117], v[26:29]
	v_mfma_f32_16x16x32_bf16 v[22:25], v[172:175], v[106:109], v[22:25]
	v_mfma_f32_16x16x32_bf16 v[18:21], v[168:171], v[114:117], v[18:21]
	v_mfma_f32_16x16x32_bf16 v[14:17], v[180:183], v[106:109], v[14:17]
	v_mfma_f32_16x16x32_bf16 v[10:13], v[176:179], v[114:117], v[10:13]
	v_mfma_f32_16x16x32_bf16 v[6:9], v[188:191], v[106:109], v[6:9]
	v_mfma_f32_16x16x32_bf16 v[2:5], v[184:187], v[114:117], v[2:5]
	v_mfma_f32_16x16x32_bf16 v[150:153], v[164:167], v[122:125], v[26:29]
	v_mfma_f32_16x16x32_bf16 v[154:157], v[172:175], v[122:125], v[18:21]
	v_mfma_f32_16x16x32_bf16 v[158:161], v[180:183], v[122:125], v[10:13]
	v_mfma_f32_16x16x32_bf16 v[162:165], v[188:191], v[122:125], v[2:5]
	s_barrier
	s_nop 1
	ds_read_b128 v[2:5], v137
	ds_read_b128 v[166:169], v137 offset:1024
	ds_read_b128 v[170:173], v137 offset:2048
	ds_read_b128 v[174:177], v137 offset:3072
	ds_read_b128 v[10:13], v133 offset:32768
	ds_read_b128 v[18:21], v133 offset:33792
	ds_read_b128 v[26:29], v132 offset:32768
	ds_read_b128 v[38:41], v132 offset:33792
	ds_read_b128 v[46:49], v131 offset:32768
	ds_read_b128 v[178:181], v131 offset:33792
	ds_read_b128 v[182:185], v130 offset:32768
	ds_read_b128 v[186:189], v130 offset:33792
	s_waitcnt vmcnt(2)
	s_barrier
	s_waitcnt lgkmcnt(0)
	v_mfma_f32_16x16x32_bf16 v[34:37], v[10:13], v[2:5], v[126:129]
	v_mfma_f32_16x16x32_bf16 v[122:125], v[18:21], v[166:169], v[34:37]
	v_mfma_f32_16x16x32_bf16 v[34:37], v[10:13], v[170:173], v[142:145]
	v_mfma_f32_16x16x32_bf16 v[58:61], v[18:21], v[174:177], v[34:37]
	v_mfma_f32_16x16x32_bf16 v[34:37], v[26:29], v[2:5], v[118:121]
	v_mfma_f32_16x16x32_bf16 v[114:117], v[38:41], v[166:169], v[34:37]
	v_mfma_f32_16x16x32_bf16 v[34:37], v[26:29], v[170:173], v[192:195]
	v_mfma_f32_16x16x32_bf16 v[50:53], v[38:41], v[174:177], v[34:37]
	v_mfma_f32_16x16x32_bf16 v[34:37], v[46:49], v[2:5], v[110:113]
	v_mfma_f32_16x16x32_bf16 v[106:109], v[178:181], v[166:169], v[34:37]
	v_mfma_f32_16x16x32_bf16 v[34:37], v[46:49], v[170:173], v[196:199]
	v_mfma_f32_16x16x32_bf16 v[42:45], v[178:181], v[174:177], v[34:37]
	v_mfma_f32_16x16x32_bf16 v[34:37], v[182:185], v[2:5], v[102:105]
	v_mfma_f32_16x16x32_bf16 v[98:101], v[186:189], v[166:169], v[34:37]
	v_mfma_f32_16x16x32_bf16 v[34:37], v[182:185], v[170:173], v[200:203]
	v_mfma_f32_16x16x32_bf16 v[34:37], v[186:189], v[174:177], v[34:37]
	s_barrier
; #define WAIT_V(n) asm volatile("s_waitcnt vmcnt(" #n ")" ::: "memory")
; #define WAIT_L(n) asm volatile("s_waitcnt lgkmcnt(" #n ")" ::: "memory")
; #define BAR __builtin_amdgcn_s_barrier()
; __device__ __forceinline__ void mainloop_8phase(const u16* __restrict__ A, const u16* __restrict__ Bt, int K,
;                                                 f32x4 (&acc)[2][2][4][2], int wid_s, int ld) {
;     ...
;     LDB(B1, 1, 1); WAIT_V(0); BAR; WAIT_L(0); MMA(0, 1, At, B1); BAR;
;     LDA(At, 1, 1); BAR; WAIT_L(0); MMA(1, 0, At, B0); MMA(1, 1, At, B1); BAR; }
;   if (wr == 0) BAR;
	ds_read_b128 v[142:145], v134
	ds_read_b128 v[190:193], v134 offset:1024
	ds_read_b128 v[194:197], v134 offset:2048
	ds_read_b128 v[134:137], v134 offset:3072
	s_waitcnt vmcnt(0)
	s_barrier
	s_waitcnt lgkmcnt(0)
	v_mfma_f32_16x16x32_bf16 v[54:57], v[10:13], v[142:145], v[94:97]
	v_mfma_f32_16x16x32_bf16 v[10:13], v[10:13], v[194:197], v[90:93]
	v_mfma_f32_16x16x32_bf16 v[62:65], v[18:21], v[134:137], v[10:13]
	v_mfma_f32_16x16x32_bf16 v[10:13], v[26:29], v[142:145], v[86:89]
	v_mfma_f32_16x16x32_bf16 v[118:121], v[38:41], v[190:193], v[10:13]
	v_mfma_f32_16x16x32_bf16 v[10:13], v[26:29], v[194:197], v[82:85]
	v_mfma_f32_16x16x32_bf16 v[126:129], v[18:21], v[190:193], v[54:57]
	v_mfma_f32_16x16x32_bf16 v[54:57], v[38:41], v[134:137], v[10:13]
	v_mfma_f32_16x16x32_bf16 v[10:13], v[46:49], v[142:145], v[78:81]
	v_mfma_f32_16x16x32_bf16 v[110:113], v[178:181], v[190:193], v[10:13]
	v_mfma_f32_16x16x32_bf16 v[10:13], v[46:49], v[194:197], v[74:77]
	v_mfma_f32_16x16x32_bf16 v[46:49], v[178:181], v[134:137], v[10:13]
	v_mfma_f32_16x16x32_bf16 v[10:13], v[182:185], v[142:145], v[70:73]
	v_mfma_f32_16x16x32_bf16 v[102:105], v[186:189], v[190:193], v[10:13]
	v_mfma_f32_16x16x32_bf16 v[10:13], v[182:185], v[194:197], v[66:69]
	v_mfma_f32_16x16x32_bf16 v[38:41], v[186:189], v[134:137], v[10:13]
	s_barrier
	ds_read_b128 v[66:69], v133 offset:49152
	ds_read_b128 v[78:81], v133 offset:50176
	ds_read_b128 v[178:181], v132 offset:49152
	ds_read_b128 v[182:185], v132 offset:50176
	ds_read_b128 v[186:189], v131 offset:49152
	ds_read_b128 v[198:201], v131 offset:50176
	ds_read_b128 v[228:231], v130 offset:49152
	ds_read_b128 v[130:133], v130 offset:50176
	s_barrier
	s_waitcnt lgkmcnt(0)
	v_mfma_f32_16x16x32_bf16 v[10:13], v[66:69], v[2:5], v[204:207]
	v_mfma_f32_16x16x32_bf16 v[90:93], v[78:81], v[166:169], v[10:13]
	v_mfma_f32_16x16x32_bf16 v[10:13], v[66:69], v[170:173], v[208:211]
	v_mfma_f32_16x16x32_bf16 v[26:29], v[78:81], v[174:177], v[10:13]
	v_mfma_f32_16x16x32_bf16 v[10:13], v[178:181], v[2:5], v[212:215]
	v_mfma_f32_16x16x32_bf16 v[82:85], v[182:185], v[166:169], v[10:13]
	v_mfma_f32_16x16x32_bf16 v[10:13], v[178:181], v[170:173], v[216:219]
	v_mfma_f32_16x16x32_bf16 v[18:21], v[182:185], v[174:177], v[10:13]
	v_mfma_f32_16x16x32_bf16 v[10:13], v[186:189], v[2:5], v[220:223]
	v_mfma_f32_16x16x32_bf16 v[2:5], v[228:231], v[2:5], v[138:141]
	v_mfma_f32_16x16x32_bf16 v[74:77], v[198:201], v[166:169], v[10:13]
	v_mfma_f32_16x16x32_bf16 v[10:13], v[186:189], v[170:173], v[224:227]
	v_mfma_f32_16x16x32_bf16 v[70:73], v[130:133], v[166:169], v[2:5]
	v_mfma_f32_16x16x32_bf16 v[2:5], v[228:231], v[170:173], v[146:149]
	v_mfma_f32_16x16x32_bf16 v[10:13], v[198:201], v[174:177], v[10:13]
	v_mfma_f32_16x16x32_bf16 v[2:5], v[130:133], v[174:177], v[2:5]
	v_mfma_f32_16x16x32_bf16 v[30:33], v[66:69], v[142:145], v[30:33]
	v_mfma_f32_16x16x32_bf16 v[94:97], v[78:81], v[190:193], v[30:33]
	v_mfma_f32_16x16x32_bf16 v[30:33], v[66:69], v[194:197], v[150:153]
	v_mfma_f32_16x16x32_bf16 v[22:25], v[178:181], v[142:145], v[22:25]
	v_mfma_f32_16x16x32_bf16 v[14:17], v[186:189], v[142:145], v[14:17]
	v_mfma_f32_16x16x32_bf16 v[6:9], v[228:231], v[142:145], v[6:9]
	v_mfma_f32_16x16x32_bf16 v[30:33], v[78:81], v[134:137], v[30:33]
	v_mfma_f32_16x16x32_bf16 v[86:89], v[182:185], v[190:193], v[22:25]
	v_mfma_f32_16x16x32_bf16 v[22:25], v[178:181], v[194:197], v[154:157]
	v_mfma_f32_16x16x32_bf16 v[78:81], v[198:201], v[190:193], v[14:17]
	v_mfma_f32_16x16x32_bf16 v[14:17], v[186:189], v[194:197], v[158:161]
	v_mfma_f32_16x16x32_bf16 v[66:69], v[130:133], v[190:193], v[6:9]
	v_mfma_f32_16x16x32_bf16 v[6:9], v[228:231], v[194:197], v[162:165]
	v_mfma_f32_16x16x32_bf16 v[22:25], v[182:185], v[134:137], v[22:25]
	v_mfma_f32_16x16x32_bf16 v[14:17], v[198:201], v[134:137], v[14:17]
	v_mfma_f32_16x16x32_bf16 v[6:9], v[130:133], v[134:137], v[6:9]
	s_movk_i32 s1, 0x100
	v_cmp_gt_u32_e32 vcc, s1, v0
	s_barrier
	s_and_saveexec_b64 s[2:3], vcc
	s_cbranch_execz .LBB0_345
	s_barrier

; #define WAIT_V(n) asm volatile("s_waitcnt vmcnt(" #n ")" ::: "memory")
; #define WAIT_L(n) asm volatile("s_waitcnt lgkmcnt(" #n ")" ::: "memory")
; #define BAR __builtin_amdgcn_s_barrier()
; #define SCHED __builtin_amdgcn_sched_barrier(0)
; __device__ __forceinline__ void mainloop_8phase(const u16* __restrict__ A, const u16* __restrict__ Bt, int K,
;                                                 f32x4 (&acc)[2][2][4][2], int wid_s, int ld) {
;     ...
;   int tid = get_tid(wid_s), wid = tid >> 6, lane = tid & 63, wr = wid >> 2, wc = wid & 3, fr = lane & 15, fq = lane >> 4;
;   unsigned goff0, goff1;
;   {
;     int r0, c0, r1, c1;
;     stage_rc(tid * 16, r0, c0);
;     stage_rc(tid * 16 + 8192, r1, c1);
;     goff0 = (unsigned)(r0 * ld + c0) * 2u;
;     goff1 = (unsigned)(r1 * ld + c1) * 2u;
;   }
;   __amdgpu_buffer_rsrc_t rs_A, rs_Bt;
;   {
;     unsigned long ua = (unsigned long)A, ub = (unsigned long)Bt;
;     unsigned alo = __builtin_amdgcn_readfirstlane((unsigned)ua), ahi = __builtin_amdgcn_readfirstlane((unsigned)(ua >> 32));
;     unsigned blo = __builtin_amdgcn_readfirstlane((unsigned)ub), bhi = __builtin_amdgcn_readfirstlane((unsigned)(ub >> 32));
;     rs_A = __builtin_amdgcn_make_buffer_rsrc((void*)(((unsigned long)ahi << 32) | alo), (short)0, 0x7ffffff0, 0x00020000);
;     rs_Bt = __builtin_amdgcn_make_buffer_rsrc((void*)(((unsigned long)bhi << 32) | blo), (short)0, 0x7ffffff0, 0x00020000);
;   }
;   bf16x8 At[4][2], B0[2][2], B1[2][2];
;   const int brow = 0, bcol = 0;
;   int nt = K / G_BK;
;   if (wr == 1) BAR;
;   WAIT_V(0); BAR;
;   STAGE(SB(1, 0), Bt, bcol, 1); STAGE(SA(1, 0), A, brow, 1); STAGE(SB(1, 1), Bt, bcol + G_HALF, 1);
;   WAIT_V(6); BAR;
;   for (int t = 0; t < nt - 2; t += 2) {
;     LDB(B0, 0, 0); SCHED; LDA(At, 0, 0); STAGE(SA(1, 1), A, brow + G_HALF, t + 1);
;     WAIT_L(8); BAR; WAIT_L(0); MMA(0, 0, At, B0); BAR; SCHED;
;     ...
;     f32x4 acc[2][2][4][2];
; #pragma unroll
;     for (int a = 0; a < 2; ++a)
; #pragma unroll
;       for (int b = 0; b < 2; ++b)
; #pragma unroll
;         for (int c = 0; c < 4; ++c)
; #pragma unroll
;           for (int d = 0; d < 2; ++d) acc[a][b][c][d] = f32x4{0.f, 0.f, 0.f, 0.f};
.LBB0_564:
	s_or_b64 exec, exec, s[2:3]
	v_bfe_i32 v8, v0, 27, 1
	v_lshlrev_b32_e32 v6, 4, v0
	v_lshrrev_b32_e32 v8, 22, v8
	v_add_u32_e32 v8, v6, v8
	v_and_b32_e32 v8, 0xfffffc00, v8
	v_sub_u32_e32 v8, v6, v8
	v_lshrrev_b32_e32 v9, 4, v8
	v_ashrrev_i32_e32 v7, 31, v0
	v_bitop3_b32 v8, v9, v8, 32 bitop3:0x6c
	v_lshrrev_b32_e32 v7, 26, v7
	v_ashrrev_i32_e32 v10, 31, v8
	v_add_u32_e32 v7, v0, v7
	v_lshrrev_b32_e32 v10, 26, v10
	v_ashrrev_i32_e32 v7, 6, v7
	v_add_u32_e32 v10, v8, v10
	v_lshlrev_b32_e32 v9, 3, v7
	v_ashrrev_i32_e32 v11, 6, v10
	v_and_b32_e32 v10, 0xc0, v10
	v_and_b32_e32 v9, 0x7ffffff0, v9
	v_sub_u32_e32 v8, v8, v10
	v_add_u32_e32 v10, 0x2000, v6
	v_add_u32_e32 v9, v11, v9
	v_ashrrev_i32_e32 v11, 31, v10
	v_lshrrev_b32_e32 v11, 22, v11
	v_add_u32_e32 v11, v10, v11
	v_ashrrev_i32_e32 v11, 10, v11
	v_mul_i32_i24_e32 v12, 0x400, v11
	v_sub_u32_e32 v10, v10, v12
	v_lshrrev_b32_e32 v12, 4, v10
	v_bitop3_b32 v10, v12, v10, 32 bitop3:0x6c
	v_ashrrev_i32_e32 v13, 31, v10
	v_lshrrev_b32_e32 v13, 26, v13
	v_lshlrev_b32_e32 v12, 3, v11
	v_add_u32_e32 v13, v10, v13
	v_lshlrev_b32_e32 v7, 5, v7
	v_ashrrev_i16_sdwa v8, v244, sext(v8) dst_sel:DWORD dst_unused:UNUSED_PAD src0_sel:DWORD src1_sel:BYTE_0
	v_and_b32_e32 v12, 0x7ffffff0, v12
	v_ashrrev_i32_e32 v14, 6, v13
	v_and_b32_e32 v13, 0xc0, v13
	v_mul_lo_u32 v9, v9, s25
	v_readlane_b32 s6, v254, 43
	v_bfe_i32 v8, v8, 0, 16
	v_add_u32_e32 v12, v14, v12
	v_sub_u32_e32 v10, v10, v13
	v_and_or_b32 v7, v7, 32, v9
	s_waitcnt vmcnt(7)
	v_add_u32_e32 v139, s6, v6
	v_lshlrev_b32_e32 v11, 5, v11
	v_ashrrev_i16_sdwa v10, v244, sext(v10) dst_sel:DWORD dst_unused:UNUSED_PAD src0_sel:DWORD src1_sel:BYTE_0
	v_add_lshl_u32 v137, v7, v8, 1
	v_mul_lo_u32 v7, v12, s25
	s_and_b32 s5, s85, 0xffff
	v_readfirstlane_b32 s2, v139
	v_add_u32_e32 v140, 0x2000, v139
	v_add_u32_e32 v141, 16, v6
	v_bfe_i32 v10, v10, 0, 16
	v_and_or_b32 v7, v11, 32, v7
	s_mov_b32 s40, s84
	s_mov_b32 s41, s5
	s_mov_b32 s42, s90
	s_mov_b32 s43, s91
	s_mov_b32 m0, s2
	s_movk_i32 s3, 0x80
	v_readfirstlane_b32 s2, v140
	v_add_u32_e32 v142, 0x8000, v141
	v_add_lshl_u32 v138, v7, v10, 1
	s_and_b32 s77, s71, 0xffff
	s_waitcnt vmcnt(0)
	s_barrier
	buffer_load_dwordx4 v137, s[40:43], s3 offen lds
	s_mov_b32 m0, s2
	v_readfirstlane_b32 s2, v142
	v_add_u32_e32 v143, 0xa000, v141
	v_readlane_b32 s7, v254, 44
	s_mov_b32 s88, s70
	s_mov_b32 s89, s77
	buffer_load_dwordx4 v138, s[40:43], s3 offen lds
	s_mov_b32 m0, s2
	v_readfirstlane_b32 s2, v143
	v_add_u32_e32 v144, s7, v6
	buffer_load_dwordx4 v137, s[88:91], s3 offen lds
	s_mov_b32 m0, s2
	v_readfirstlane_b32 s2, v144
	v_add_u32_e32 v147, 0x2000, v144
	buffer_load_dwordx4 v138, s[88:91], s3 offen lds
	s_mov_b32 m0, s2
	v_readfirstlane_b32 s2, v147
	buffer_load_dwordx4 v137, s[40:43], s28 offen lds
	s_mov_b32 m0, s2
	v_and_b32_e32 v4, 15, v2
	buffer_load_dwordx4 v138, s[40:43], s28 offen lds
	v_lshlrev_b32_e32 v7, 2, v2
	v_and_b32_e32 v5, 48, v2
	v_lshlrev_b32_e32 v4, 6, v4
	v_and_b32_e32 v7, 32, v7
	v_bitop3_b32 v4, v4, v7, v5 bitop3:0x36
	v_readlane_b32 s2, v254, 41
	v_lshlrev_b32_e32 v2, 6, v2
	s_waitcnt vmcnt(6)
	v_readlane_b32 s3, v254, 42
	v_add_u32_e32 v8, s2, v4
	v_add_u32_e32 v149, s2, v6
	s_movk_i32 s2, 0x3c0
	v_lshlrev_b32_e32 v11, 6, v0
	v_lshlrev_b32_e32 v3, 13, v3
	v_and_or_b32 v2, v2, s2, v5
	v_add_u32_e32 v9, s3, v4
	v_add_u32_e32 v152, s3, v6
	v_add_u32_e32 v6, s6, v4
	v_add_u32_e32 v10, s7, v4
	v_and_b32_e32 v11, 0x3000, v11
	v_add_u32_e32 v4, 16, v4
	v_xad_u32 v5, v2, v7, 16
	v_or_b32_e32 v7, 0x800, v3
	v_or_b32_e32 v12, 0x1000, v3
	v_or_b32_e32 v13, 0x1800, v3
	v_mov_b32_e32 v2, 0
	s_mov_b32 s76, s70
	s_mov_b32 s4, s84
	v_add_u32_e32 v146, 0xc000, v141
	v_add_u32_e32 v145, 0xe000, v141
	v_add_u32_e32 v150, 0x2000, v149
	v_add_u32_e32 v151, 0x2000, v141
	v_add_u32_e32 v153, 0x2000, v152
	v_add_u32_e32 v154, 0x4000, v141
	v_add_u32_e32 v155, 0x6000, v141
	s_mov_b32 s3, 0
	v_add_u32_e32 v156, v8, v11
	v_add_u32_e32 v134, v4, v3
	s_waitcnt lgkmcnt(0)
	v_add_u32_e32 v133, v5, v7
	v_add_u32_e32 v132, v5, v12
	v_add_u32_e32 v131, v5, v13
	v_add_u32_e32 v148, v9, v11
	v_add_u32_e32 v136, v6, v11
	v_add_u32_e32 v135, v10, v11
	s_mov_b32 s2, 0
	s_waitcnt vmcnt(9)
	s_waitcnt vmcnt(8)
	s_waitcnt vmcnt(7)
	s_waitcnt vmcnt(6)
	s_barrier
	ds_read_b128 v[158:161], v156
	ds_read_b128 v[162:165], v156 offset:1024
	ds_read_b128 v[166:169], v156 offset:2048
	ds_read_b128 v[170:173], v156 offset:3072
	s_add_i32 s15, s27, s3
	s_add_i32 s6, s15, 0x80
	s_add_i32 m0, s100, 0xc000
	ds_read_b128 v[174:177], v134
	ds_read_b128 v[178:181], v134 offset:1024
	ds_read_b128 v[182:185], v133
	ds_read_b128 v[186:189], v133 offset:1024
	ds_read_b128 v[190:193], v132
	ds_read_b128 v[194:197], v132 offset:1024
	ds_read_b128 v[198:201], v131
	buffer_load_dwordx4 v137, s[76:79], s6 offen lds
	s_add_i32 m0, s100, 0xe000
	ds_read_b128 v[202:205], v131 offset:1024
	buffer_load_dwordx4 v138, s[76:79], s6 offen lds
	s_waitcnt lgkmcnt(8)
	s_barrier
	s_waitcnt lgkmcnt(1)
	v_mfma_f32_16x16x32_bf16 v[126:129], v[174:177], v[158:161], 0
	v_mfma_f32_16x16x32_bf16 v[122:125], v[174:177], v[166:169], 0
	v_mfma_f32_16x16x32_bf16 v[118:121], v[182:185], v[158:161], 0
	v_mfma_f32_16x16x32_bf16 v[114:117], v[182:185], v[166:169], 0
	v_mfma_f32_16x16x32_bf16 v[110:113], v[190:193], v[158:161], 0
	v_mfma_f32_16x16x32_bf16 v[106:109], v[190:193], v[166:169], 0
	v_mfma_f32_16x16x32_bf16 v[102:105], v[198:201], v[158:161], 0
	v_mfma_f32_16x16x32_bf16 v[98:101], v[198:201], v[166:169], 0
	v_mfma_f32_16x16x32_bf16 v[126:129], v[178:181], v[162:165], v[126:129]
	v_mfma_f32_16x16x32_bf16 v[122:125], v[178:181], v[170:173], v[122:125]
	v_mfma_f32_16x16x32_bf16 v[118:121], v[186:189], v[162:165], v[118:121]
	v_mfma_f32_16x16x32_bf16 v[114:117], v[186:189], v[170:173], v[114:117]
	v_mfma_f32_16x16x32_bf16 v[110:113], v[194:197], v[162:165], v[110:113]
	v_mfma_f32_16x16x32_bf16 v[106:109], v[194:197], v[170:173], v[106:109]
	s_waitcnt lgkmcnt(0)
	v_mfma_f32_16x16x32_bf16 v[102:105], v[202:205], v[162:165], v[102:105]
	v_mfma_f32_16x16x32_bf16 v[98:101], v[202:205], v[170:173], v[98:101]
	s_barrier
; #define WAIT_V(n) asm volatile("s_waitcnt vmcnt(" #n ")" ::: "memory")
; #define WAIT_L(n) asm volatile("s_waitcnt lgkmcnt(" #n ")" ::: "memory")
; #define BAR __builtin_amdgcn_s_barrier()
; #define SCHED __builtin_amdgcn_sched_barrier(0)
; __device__ __forceinline__ void mainloop_8phase(const u16* __restrict__ A, const u16* __restrict__ Bt, int K,
;                                                 f32x4 (&acc)[2][2][4][2], int wid_s, int ld) {
;     ...
;     LDB(B1, 0, 1); STAGE(SB(0, 0), Bt, bcol, t + 2);
;     BAR; WAIT_L(0); MMA(0, 1, At, B1); BAR;
;     LDA(At, 0, 1); STAGE(SA(0, 0), A, brow, t + 2);
;     BAR; WAIT_L(0); MMA(1, 0, At, B0); BAR; SCHED;
;     STAGE(SB(0, 1), Bt, bcol + G_HALF, t + 2);
;     WAIT_V(6); BAR; MMA(1, 1, At, B1); BAR;
;     LDB(B0, 1, 0); SCHED; LDA(At, 1, 0); STAGE(SA(0, 1), A, brow + G_HALF, t + 2);
;     WAIT_L(8); BAR; WAIT_L(0); MMA(0, 0, At, B0); BAR; SCHED;
	s_add_i32 s14, s3, 0x100
	s_mov_b32 s6, s78
	s_mov_b32 s7, s79
	s_add_i32 m0, s100, 0x10000
	ds_read_b128 v[206:209], v148
	ds_read_b128 v[210:213], v148 offset:1024
	ds_read_b128 v[214:217], v148 offset:2048
	ds_read_b128 v[218:221], v148 offset:3072
	buffer_load_dwordx4 v137, s[4:7], s14 offen lds
	s_add_i32 m0, s100, 0x12000
	s_add_i32 s2, s2, 2
	buffer_load_dwordx4 v138, s[4:7], s14 offen lds
	s_barrier
	s_waitcnt lgkmcnt(0)
	v_mfma_f32_16x16x32_bf16 v[94:97], v[174:177], v[206:209], 0
	v_mfma_f32_16x16x32_bf16 v[90:93], v[174:177], v[214:217], 0
	v_mfma_f32_16x16x32_bf16 v[86:89], v[182:185], v[206:209], 0
	v_mfma_f32_16x16x32_bf16 v[82:85], v[182:185], v[214:217], 0
	v_mfma_f32_16x16x32_bf16 v[78:81], v[190:193], v[206:209], 0
	v_mfma_f32_16x16x32_bf16 v[74:77], v[190:193], v[214:217], 0
	v_mfma_f32_16x16x32_bf16 v[70:73], v[198:201], v[206:209], 0
	v_mfma_f32_16x16x32_bf16 v[66:69], v[198:201], v[214:217], 0
	v_mfma_f32_16x16x32_bf16 v[94:97], v[178:181], v[210:213], v[94:97]
	v_mfma_f32_16x16x32_bf16 v[90:93], v[178:181], v[218:221], v[90:93]
	v_mfma_f32_16x16x32_bf16 v[86:89], v[186:189], v[210:213], v[86:89]
	v_mfma_f32_16x16x32_bf16 v[82:85], v[186:189], v[218:221], v[82:85]
	v_mfma_f32_16x16x32_bf16 v[78:81], v[194:197], v[210:213], v[78:81]
	v_mfma_f32_16x16x32_bf16 v[74:77], v[194:197], v[218:221], v[74:77]
	v_mfma_f32_16x16x32_bf16 v[70:73], v[202:205], v[210:213], v[70:73]
	v_mfma_f32_16x16x32_bf16 v[66:69], v[202:205], v[218:221], v[66:69]
	s_mov_b32 m0, s100
	s_barrier
	ds_read_b128 v[174:177], v134 offset:16384
	ds_read_b128 v[178:181], v134 offset:17408
	ds_read_b128 v[182:185], v133 offset:16384
	ds_read_b128 v[186:189], v133 offset:17408
	ds_read_b128 v[190:193], v132 offset:16384
	ds_read_b128 v[194:197], v132 offset:17408
	ds_read_b128 v[198:201], v131 offset:16384
	buffer_load_dwordx4 v137, s[76:79], s14 offen lds
	s_add_i32 m0, s100, 0x2000
	ds_read_b128 v[202:205], v131 offset:17408
	buffer_load_dwordx4 v138, s[76:79], s14 offen lds
	s_barrier
	s_waitcnt lgkmcnt(1)
	v_mfma_f32_16x16x32_bf16 v[62:65], v[174:177], v[158:161], 0
	v_mfma_f32_16x16x32_bf16 v[58:61], v[174:177], v[166:169], 0
	v_mfma_f32_16x16x32_bf16 v[54:57], v[182:185], v[158:161], 0
	v_mfma_f32_16x16x32_bf16 v[50:53], v[182:185], v[166:169], 0
	v_mfma_f32_16x16x32_bf16 v[46:49], v[190:193], v[158:161], 0
	v_mfma_f32_16x16x32_bf16 v[42:45], v[190:193], v[166:169], 0
	v_mfma_f32_16x16x32_bf16 v[38:41], v[198:201], v[158:161], 0
	v_mfma_f32_16x16x32_bf16 v[34:37], v[198:201], v[166:169], 0
	v_mfma_f32_16x16x32_bf16 v[62:65], v[178:181], v[162:165], v[62:65]
	v_mfma_f32_16x16x32_bf16 v[58:61], v[178:181], v[170:173], v[58:61]
	v_mfma_f32_16x16x32_bf16 v[54:57], v[186:189], v[162:165], v[54:57]
	v_mfma_f32_16x16x32_bf16 v[50:53], v[186:189], v[170:173], v[50:53]
	v_mfma_f32_16x16x32_bf16 v[46:49], v[194:197], v[162:165], v[46:49]
	v_mfma_f32_16x16x32_bf16 v[42:45], v[194:197], v[170:173], v[42:45]
	s_waitcnt lgkmcnt(0)
	v_mfma_f32_16x16x32_bf16 v[38:41], v[202:205], v[162:165], v[38:41]
	v_mfma_f32_16x16x32_bf16 v[34:37], v[202:205], v[170:173], v[34:37]
	s_barrier
	s_add_i32 s34, s15, 0x100
	s_add_i32 m0, s100, 0x14000
	buffer_load_dwordx4 v137, s[4:7], s34 offen lds
	s_add_i32 m0, s100, 0x16000
	s_nop 0
	buffer_load_dwordx4 v138, s[4:7], s34 offen lds
	s_waitcnt vmcnt(6)
	s_barrier
	v_mfma_f32_16x16x32_bf16 v[30:33], v[174:177], v[206:209], 0
	v_mfma_f32_16x16x32_bf16 v[26:29], v[174:177], v[214:217], 0
	v_mfma_f32_16x16x32_bf16 v[22:25], v[182:185], v[206:209], 0
	v_mfma_f32_16x16x32_bf16 v[18:21], v[182:185], v[214:217], 0
	v_mfma_f32_16x16x32_bf16 v[14:17], v[190:193], v[206:209], 0
	v_mfma_f32_16x16x32_bf16 v[10:13], v[190:193], v[214:217], 0
	v_mfma_f32_16x16x32_bf16 v[6:9], v[198:201], v[206:209], 0
	v_mfma_f32_16x16x32_bf16 v[2:5], v[198:201], v[214:217], 0
	v_mfma_f32_16x16x32_bf16 v[30:33], v[178:181], v[210:213], v[30:33]
	v_mfma_f32_16x16x32_bf16 v[26:29], v[178:181], v[218:221], v[26:29]
	v_mfma_f32_16x16x32_bf16 v[22:25], v[186:189], v[210:213], v[22:25]
	v_mfma_f32_16x16x32_bf16 v[18:21], v[186:189], v[218:221], v[18:21]
	v_mfma_f32_16x16x32_bf16 v[14:17], v[194:197], v[210:213], v[14:17]
	v_mfma_f32_16x16x32_bf16 v[10:13], v[194:197], v[218:221], v[10:13]
	v_mfma_f32_16x16x32_bf16 v[6:9], v[202:205], v[210:213], v[6:9]
	v_mfma_f32_16x16x32_bf16 v[2:5], v[202:205], v[218:221], v[2:5]
	s_barrier
	ds_read_b128 v[158:161], v136
	ds_read_b128 v[162:165], v136 offset:1024
	ds_read_b128 v[166:169], v136 offset:2048
	ds_read_b128 v[170:173], v136 offset:3072
	s_add_i32 m0, s100, 0x4000
	ds_read_b128 v[174:177], v134 offset:32768
	ds_read_b128 v[178:181], v134 offset:33792
	ds_read_b128 v[182:185], v133 offset:32768
	ds_read_b128 v[186:189], v133 offset:33792
	ds_read_b128 v[190:193], v132 offset:32768
	ds_read_b128 v[194:197], v132 offset:33792
	ds_read_b128 v[198:201], v131 offset:32768
	buffer_load_dwordx4 v137, s[76:79], s34 offen lds
	s_add_i32 m0, s100, 0x6000
	ds_read_b128 v[202:205], v131 offset:33792
	buffer_load_dwordx4 v138, s[76:79], s34 offen lds
	s_waitcnt lgkmcnt(8)
	s_barrier
; #define WAIT_V(n) asm volatile("s_waitcnt vmcnt(" #n ")" ::: "memory")
; #define WAIT_L(n) asm volatile("s_waitcnt lgkmcnt(" #n ")" ::: "memory")
; #define BAR __builtin_amdgcn_s_barrier()
; #define SCHED __builtin_amdgcn_sched_barrier(0)
; __device__ __forceinline__ void mainloop_8phase(const u16* __restrict__ A, const u16* __restrict__ Bt, int K,
;                                                 f32x4 (&acc)[2][2][4][2], int wid_s, int ld) {
;     ...
;     WAIT_L(8); BAR; WAIT_L(0); MMA(0, 0, At, B0); BAR; SCHED;
;     LDB(B1, 1, 1); STAGE(SB(1, 0), Bt, bcol, t + 3);
;     BAR; WAIT_L(0); MMA(0, 1, At, B1); BAR;
;     LDA(At, 1, 1); STAGE(SA(1, 0), A, brow, t + 3);
;     BAR; WAIT_L(0); MMA(1, 0, At, B0); BAR; SCHED;
;     STAGE(SB(1, 1), Bt, bcol + G_HALF, t + 3);
;     WAIT_V(6); BAR; MMA(1, 1, At, B1); BAR;
;   }
	s_waitcnt lgkmcnt(1)
	v_mfma_f32_16x16x32_bf16 v[126:129], v[174:177], v[158:161], v[126:129]
	v_mfma_f32_16x16x32_bf16 v[122:125], v[174:177], v[166:169], v[122:125]
	v_mfma_f32_16x16x32_bf16 v[118:121], v[182:185], v[158:161], v[118:121]
	v_mfma_f32_16x16x32_bf16 v[114:117], v[182:185], v[166:169], v[114:117]
	v_mfma_f32_16x16x32_bf16 v[110:113], v[190:193], v[158:161], v[110:113]
	v_mfma_f32_16x16x32_bf16 v[106:109], v[190:193], v[166:169], v[106:109]
	v_mfma_f32_16x16x32_bf16 v[102:105], v[198:201], v[158:161], v[102:105]
	v_mfma_f32_16x16x32_bf16 v[98:101], v[198:201], v[166:169], v[98:101]
	v_mfma_f32_16x16x32_bf16 v[126:129], v[178:181], v[162:165], v[126:129]
	v_mfma_f32_16x16x32_bf16 v[122:125], v[178:181], v[170:173], v[122:125]
	v_mfma_f32_16x16x32_bf16 v[118:121], v[186:189], v[162:165], v[118:121]
	v_mfma_f32_16x16x32_bf16 v[114:117], v[186:189], v[170:173], v[114:117]
	v_mfma_f32_16x16x32_bf16 v[110:113], v[194:197], v[162:165], v[110:113]
	v_mfma_f32_16x16x32_bf16 v[106:109], v[194:197], v[170:173], v[106:109]
	s_waitcnt lgkmcnt(0)
	v_mfma_f32_16x16x32_bf16 v[102:105], v[202:205], v[162:165], v[102:105]
	v_mfma_f32_16x16x32_bf16 v[98:101], v[202:205], v[170:173], v[98:101]
	s_barrier
	s_addk_i32 s3, 0x180
	s_add_i32 m0, s100, 0x18000
	ds_read_b128 v[206:209], v135
	ds_read_b128 v[210:213], v135 offset:1024
	ds_read_b128 v[214:217], v135 offset:2048
	buffer_load_dwordx4 v137, s[4:7], s3 offen lds
	s_add_i32 m0, s100, 0x1a000
	ds_read_b128 v[218:221], v135 offset:3072
	buffer_load_dwordx4 v138, s[4:7], s3 offen lds
	s_barrier
	s_waitcnt lgkmcnt(1)
	v_mfma_f32_16x16x32_bf16 v[94:97], v[174:177], v[206:209], v[94:97]
	v_mfma_f32_16x16x32_bf16 v[90:93], v[174:177], v[214:217], v[90:93]
	v_mfma_f32_16x16x32_bf16 v[86:89], v[182:185], v[206:209], v[86:89]
	v_mfma_f32_16x16x32_bf16 v[82:85], v[182:185], v[214:217], v[82:85]
	v_mfma_f32_16x16x32_bf16 v[78:81], v[190:193], v[206:209], v[78:81]
	v_mfma_f32_16x16x32_bf16 v[74:77], v[190:193], v[214:217], v[74:77]
	v_mfma_f32_16x16x32_bf16 v[70:73], v[198:201], v[206:209], v[70:73]
	v_mfma_f32_16x16x32_bf16 v[66:69], v[198:201], v[214:217], v[66:69]
	v_mfma_f32_16x16x32_bf16 v[94:97], v[178:181], v[210:213], v[94:97]
	s_waitcnt lgkmcnt(0)
	v_mfma_f32_16x16x32_bf16 v[90:93], v[178:181], v[218:221], v[90:93]
	v_mfma_f32_16x16x32_bf16 v[86:89], v[186:189], v[210:213], v[86:89]
	v_mfma_f32_16x16x32_bf16 v[82:85], v[186:189], v[218:221], v[82:85]
	v_mfma_f32_16x16x32_bf16 v[78:81], v[194:197], v[210:213], v[78:81]
	v_mfma_f32_16x16x32_bf16 v[74:77], v[194:197], v[218:221], v[74:77]
	v_mfma_f32_16x16x32_bf16 v[70:73], v[202:205], v[210:213], v[70:73]
	v_mfma_f32_16x16x32_bf16 v[66:69], v[202:205], v[218:221], v[66:69]
	s_add_i32 m0, s100, 0x8000
	s_barrier
	ds_read_b128 v[174:177], v134 offset:49152
	ds_read_b128 v[178:181], v134 offset:50176
	ds_read_b128 v[182:185], v133 offset:49152
	ds_read_b128 v[186:189], v133 offset:50176
	ds_read_b128 v[190:193], v132 offset:49152
	ds_read_b128 v[194:197], v132 offset:50176
	ds_read_b128 v[198:201], v131 offset:49152
	buffer_load_dwordx4 v137, s[76:79], s3 offen lds
	s_add_i32 m0, s100, 0xa000
	ds_read_b128 v[202:205], v131 offset:50176
	buffer_load_dwordx4 v138, s[76:79], s3 offen lds
	s_barrier
	s_waitcnt lgkmcnt(1)
	v_mfma_f32_16x16x32_bf16 v[62:65], v[174:177], v[158:161], v[62:65]
	v_mfma_f32_16x16x32_bf16 v[58:61], v[174:177], v[166:169], v[58:61]
	v_mfma_f32_16x16x32_bf16 v[54:57], v[182:185], v[158:161], v[54:57]
	v_mfma_f32_16x16x32_bf16 v[50:53], v[182:185], v[166:169], v[50:53]
	v_mfma_f32_16x16x32_bf16 v[46:49], v[190:193], v[158:161], v[46:49]
	v_mfma_f32_16x16x32_bf16 v[42:45], v[190:193], v[166:169], v[42:45]
	v_mfma_f32_16x16x32_bf16 v[38:41], v[198:201], v[158:161], v[38:41]
	v_mfma_f32_16x16x32_bf16 v[34:37], v[198:201], v[166:169], v[34:37]
	v_mfma_f32_16x16x32_bf16 v[62:65], v[178:181], v[162:165], v[62:65]
	v_mfma_f32_16x16x32_bf16 v[58:61], v[178:181], v[170:173], v[58:61]
	v_mfma_f32_16x16x32_bf16 v[54:57], v[186:189], v[162:165], v[54:57]
	v_mfma_f32_16x16x32_bf16 v[50:53], v[186:189], v[170:173], v[50:53]
	v_mfma_f32_16x16x32_bf16 v[46:49], v[194:197], v[162:165], v[46:49]
	v_mfma_f32_16x16x32_bf16 v[42:45], v[194:197], v[170:173], v[42:45]
	s_waitcnt lgkmcnt(0)
	v_mfma_f32_16x16x32_bf16 v[38:41], v[202:205], v[162:165], v[38:41]
	v_mfma_f32_16x16x32_bf16 v[34:37], v[202:205], v[170:173], v[34:37]
	s_barrier
	s_addk_i32 s15, 0x180
	s_add_i32 m0, s100, 0x1c000
	buffer_load_dwordx4 v137, s[4:7], s15 offen lds
	s_add_i32 m0, s100, 0x1e000
	s_nop 0
	buffer_load_dwordx4 v138, s[4:7], s15 offen lds
	s_waitcnt vmcnt(6)
	s_barrier
	v_mfma_f32_16x16x32_bf16 v[30:33], v[174:177], v[206:209], v[30:33]
	v_mfma_f32_16x16x32_bf16 v[26:29], v[174:177], v[214:217], v[26:29]
	v_mfma_f32_16x16x32_bf16 v[22:25], v[182:185], v[206:209], v[22:25]
	v_mfma_f32_16x16x32_bf16 v[18:21], v[182:185], v[214:217], v[18:21]
	v_mfma_f32_16x16x32_bf16 v[14:17], v[190:193], v[206:209], v[14:17]
	v_mfma_f32_16x16x32_bf16 v[10:13], v[190:193], v[214:217], v[10:13]
	v_mfma_f32_16x16x32_bf16 v[6:9], v[198:201], v[206:209], v[6:9]
	v_mfma_f32_16x16x32_bf16 v[2:5], v[198:201], v[214:217], v[2:5]
	v_mfma_f32_16x16x32_bf16 v[30:33], v[178:181], v[210:213], v[30:33]
	v_mfma_f32_16x16x32_bf16 v[26:29], v[178:181], v[218:221], v[26:29]
	v_mfma_f32_16x16x32_bf16 v[22:25], v[186:189], v[210:213], v[22:25]
	v_mfma_f32_16x16x32_bf16 v[18:21], v[186:189], v[218:221], v[18:21]
	v_mfma_f32_16x16x32_bf16 v[14:17], v[194:197], v[210:213], v[14:17]
	v_mfma_f32_16x16x32_bf16 v[10:13], v[194:197], v[218:221], v[10:13]
	v_mfma_f32_16x16x32_bf16 v[6:9], v[202:205], v[210:213], v[6:9]
	v_mfma_f32_16x16x32_bf16 v[2:5], v[202:205], v[218:221], v[2:5]
	s_cmp_lt_u32 s2, s29
	s_mov_b32 s3, s14
	s_barrier
